# nt hint on once-read streaming loads (weight convert + rmsnorm rows) in phases 0/3/9/12
# speedup vs baseline: 1.0190x; 1.0067x over previous
; #define LAS __attribute__((address_space(3)))
; template <int MODE>
; __device__ __forceinline__ void transpose_item(const float* W, const float* W2, int K, int Nsrc, int Ndst, bf16_t* WT, LAS float* scr, int item, int lane) {
;     const int nblk = Ndst / 64, kb = item / nblk, nb = item % nblk, k0 = 64 * kb, n0 = 64 * nb;
;     const int c4 = lane & 15, r4 = lane >> 4;
;     const float* src; bool ok = true; int lcol;
;     if (MODE == 0) { src = W + n0 + 4 * c4; ok = (n0 + 4 * c4) < Nsrc; lcol = 4 * c4; }
;     else if (MODE == 2) {
;         const int n = n0 + 4 * c4; int sc = -1; if (n < 3264) sc = 2120 + n; else if (n >= 3328 && n < 3328 + 2120) sc = n - 3328;
;         ok = sc >= 0; src = W + (ok ? sc : 0); lcol = 4 * c4; }
;     else if (MODE == 3) { const int n = n0 + 4 * c4; ok = n < 2120; src = W + (ok ? n : 0); lcol = 4 * c4; }
;     else { const int t = c4 >> 3, g = c4 & 7; src = (t ? W2 : W) + n0 / 2 + 4 * g; lcol = 8 * g + 4 * t; }
;     f32x4 v[16];
; #pragma unroll
;     for (int i = 0; i < 16; ++i) v[i] = ok ? *(const f32x4*)(src + (size_t)(k0 + 4 * i + r4) * Nsrc) : (f32x4){0.f, 0.f, 0.f, 0.f};
; #pragma unroll
;     for (int i = 0; i < 16; ++i) { LAS float* d = scr + (4 * i + r4) * 65 + lcol; d[0] = v[i].x; d[1] = v[i].y; d[2] = v[i].z; d[3] = v[i].w; }
.LBB0_25:
	s_mul_hi_i32 s16, s15, 0x2e8ba2e9
	s_lshr_b32 s17, s16, 31
	s_ashr_i32 s16, s16, 5
	s_add_i32 s17, s16, s17
	s_mul_i32 s18, s17, 0xffffea00
	s_lshl_b32 s16, s17, 6
	s_mul_i32 s19, s17, 0xffffd400
	s_add_i32 s18, s5, s18
	v_or_b32_e32 v55, s16, v20
	v_add_u32_e32 v4, s19, v22
	s_ashr_i32 s19, s18, 31
	s_ashr_i32 s17, s16, 31
	v_or_b32_e32 v60, 4, v55
	v_or_b32_e32 v61, 8, v55
	v_or_b32_e32 v62, 12, v55
	v_or_b32_e32 v63, 16, v55
	v_or_b32_e32 v64, 20, v55
	v_or_b32_e32 v65, 24, v55
	v_or_b32_e32 v66, 28, v55
	v_or_b32_e32 v67, 32, v55
	v_or_b32_e32 v68, 36, v55
	v_or_b32_e32 v69, 40, v55
	v_or_b32_e32 v70, 44, v55
	v_or_b32_e32 v71, 48, v55
	v_or_b32_e32 v72, 52, v55
	v_add_u32_e32 v56, -8, v4
	v_lshl_add_u64 v[58:59], s[18:19], 2, v[0:1]
	v_or_b32_e32 v73, 56, v55
	v_or_b32_e32 v74, 60, v55
	v_lshl_add_u64 v[18:19], s[16:17], 1, v[2:3]
	v_ashrrev_i32_e32 v57, 31, v56
	v_mad_i64_i32 v[92:93], s[16:17], v55, s11, v[58:59]
	v_mad_i64_i32 v[94:95], s[16:17], v60, s11, v[58:59]
	v_mad_i64_i32 v[96:97], s[16:17], v61, s11, v[58:59]
	v_mad_i64_i32 v[98:99], s[16:17], v62, s11, v[58:59]
	v_mad_i64_i32 v[100:101], s[16:17], v63, s11, v[58:59]
	v_mad_i64_i32 v[102:103], s[16:17], v64, s11, v[58:59]
	v_mad_i64_i32 v[104:105], s[16:17], v65, s11, v[58:59]
	v_mad_i64_i32 v[106:107], s[16:17], v66, s11, v[58:59]
	v_mad_i64_i32 v[108:109], s[16:17], v67, s11, v[58:59]
	v_mad_i64_i32 v[110:111], s[16:17], v68, s11, v[58:59]
	v_mad_i64_i32 v[112:113], s[16:17], v69, s11, v[58:59]
	v_mad_i64_i32 v[114:115], s[16:17], v70, s11, v[58:59]
	v_mad_i64_i32 v[116:117], s[16:17], v71, s11, v[58:59]
	v_mad_i64_i32 v[118:119], s[16:17], v72, s11, v[58:59]
	v_mad_i64_i32 v[120:121], s[16:17], v73, s11, v[58:59]
	v_mad_i64_i32 v[122:123], s[16:17], v74, s11, v[58:59]
	v_lshlrev_b64 v[124:125], 12, v[56:57]
	global_load_dwordx4 v[56:59], v[92:93], off nt
	global_load_dwordx4 v[60:63], v[94:95], off nt
	global_load_dwordx4 v[64:67], v[96:97], off nt
	global_load_dwordx4 v[68:71], v[98:99], off nt
	global_load_dwordx4 v[72:75], v[100:101], off nt
	global_load_dwordx4 v[76:79], v[102:103], off nt
	global_load_dwordx4 v[80:83], v[104:105], off nt
	global_load_dwordx4 v[84:87], v[106:107], off nt
	global_load_dwordx4 v[88:91], v[108:109], off nt
	global_load_dwordx4 v[92:95], v[110:111], off nt
	global_load_dwordx4 v[96:99], v[112:113], off nt
	global_load_dwordx4 v[100:103], v[114:115], off nt
	s_nop 0
	global_load_dwordx4 v[104:107], v[116:117], off nt
	global_load_dwordx4 v[108:111], v[118:119], off nt
	global_load_dwordx4 v[112:115], v[120:121], off nt
	s_nop 0
	global_load_dwordx4 v[116:119], v[122:123], off nt
	v_subrev_u32_e32 v6, 56, v4
	v_subrev_u32_e32 v8, 48, v4
	v_subrev_u32_e32 v10, 40, v4
	v_subrev_u32_e32 v12, 32, v4
	v_subrev_u32_e32 v14, 24, v4
	v_add_u32_e32 v16, -16, v4
	v_ashrrev_i32_e32 v5, 31, v4
	v_ashrrev_i32_e32 v7, 31, v6
	v_ashrrev_i32_e32 v9, 31, v8
	v_ashrrev_i32_e32 v11, 31, v10
	v_ashrrev_i32_e32 v13, 31, v12
	v_ashrrev_i32_e32 v15, 31, v14
	v_ashrrev_i32_e32 v17, 31, v16
	v_lshlrev_b64 v[4:5], 12, v[4:5]
	v_lshlrev_b64 v[6:7], 12, v[6:7]
	v_lshlrev_b64 v[8:9], 12, v[8:9]
	v_lshlrev_b64 v[10:11], 12, v[10:11]
	v_lshlrev_b64 v[12:13], 12, v[12:13]
	v_lshlrev_b64 v[14:15], 12, v[14:15]
	v_lshlrev_b64 v[16:17], 12, v[16:17]
	v_lshl_add_u64 v[4:5], v[18:19], 0, v[4:5]
	v_lshl_add_u64 v[6:7], v[18:19], 0, v[6:7]
	v_lshl_add_u64 v[8:9], v[18:19], 0, v[8:9]
	s_waitcnt vmcnt(15)
	ds_write2_b32 v23, v56, v57 offset1:1
	ds_write2_b32 v23, v58, v59 offset0:2 offset1:3
	s_waitcnt vmcnt(14)
	ds_write2_b32 v24, v60, v61 offset1:1
	ds_write2_b32 v25, v62, v63 offset1:1
	s_waitcnt vmcnt(13)
	ds_write2_b32 v26, v64, v65 offset1:1
	ds_write2_b32 v27, v66, v67 offset1:1
	s_waitcnt vmcnt(12)
	ds_write2_b32 v28, v68, v69 offset1:1
	ds_write2_b32 v29, v70, v71 offset1:1
	s_waitcnt vmcnt(11)
	ds_write2_b32 v30, v72, v73 offset1:1
	ds_write2_b32 v31, v74, v75 offset1:1
	s_waitcnt vmcnt(10)
	ds_write2_b32 v32, v76, v77 offset1:1
	ds_write2_b32 v33, v78, v79 offset1:1
	s_waitcnt vmcnt(9)
	ds_write2_b32 v34, v80, v81 offset1:1
	ds_write2_b32 v35, v82, v83 offset1:1
	s_waitcnt vmcnt(8)
	ds_write2_b32 v36, v84, v85 offset1:1
	ds_write2_b32 v37, v86, v87 offset1:1
	s_waitcnt vmcnt(7)
	ds_write2_b32 v38, v88, v89 offset1:1
	ds_write2_b32 v39, v90, v91 offset1:1
	s_waitcnt vmcnt(6)
	ds_write2_b32 v40, v92, v93 offset1:1
	ds_write2_b32 v41, v94, v95 offset1:1
	s_waitcnt vmcnt(5)
	ds_write2_b32 v42, v96, v97 offset1:1
	ds_write2_b32 v43, v98, v99 offset1:1
	s_waitcnt vmcnt(4)
	ds_write2_b32 v44, v100, v101 offset1:1
	ds_write2_b32 v45, v102, v103 offset1:1
	s_waitcnt vmcnt(3)
	ds_write2_b32 v46, v104, v105 offset1:1
	ds_write2_b32 v47, v106, v107 offset1:1
	s_waitcnt vmcnt(2)
	ds_write2_b32 v48, v108, v109 offset1:1
	ds_write2_b32 v49, v110, v111 offset1:1
	s_waitcnt vmcnt(1)
	ds_write2_b32 v50, v112, v113 offset1:1
	ds_write2_b32 v51, v114, v115 offset1:1
	s_waitcnt vmcnt(0)
	ds_write2_b32 v52, v116, v117 offset1:1
	ds_write2_b32 v53, v118, v119 offset1:1
	s_waitcnt lgkmcnt(0)
; #define LAS __attribute__((address_space(3)))
; __device__ __forceinline__ unsigned pk2(float lo, float hi) { return f2bf(lo) | (f2bf(hi) << 16); }
; template <int MODE>
; __device__ __forceinline__ void transpose_item(const float* W, const float* W2, int K, int Nsrc, int Ndst, bf16_t* WT, LAS float* scr, int item, int lane) {
;     ...
;     const int c = lane & 7;
; #pragma unroll
;     for (int j = 0; j < 8; ++j) { const int n = (lane >> 3) + 8 * j; const LAS float* sp = scr + (8 * c) * 65 + n;
;         u32x4 o; o.x = pk2(sp[0 * 65], sp[1 * 65]); o.y = pk2(sp[2 * 65], sp[3 * 65]); o.z = pk2(sp[4 * 65], sp[5 * 65]); o.w = pk2(sp[6 * 65], sp[7 * 65]);
	ds_read2_b32 v[56:57], v21 offset0:65 offset1:73
	ds_read2_b32 v[58:59], v21 offset1:8
	ds_read2_b32 v[60:61], v21 offset0:130 offset1:138
	ds_read2_b32 v[62:63], v21 offset0:195 offset1:203
	ds_read2_b32 v[64:65], v54 offset0:4 offset1:12
	ds_read2_b32 v[66:67], v54 offset0:69 offset1:77
	ds_read2_b32 v[68:69], v54 offset0:134 offset1:142
	ds_read2_b32 v[70:71], v54 offset0:199 offset1:207
	ds_read2_b32 v[72:73], v21 offset0:81 offset1:89
	ds_read2_b32 v[74:75], v21 offset0:16 offset1:24
	ds_read2_b32 v[76:77], v21 offset0:146 offset1:154
	ds_read2_b32 v[78:79], v21 offset0:211 offset1:219
	ds_read2_b32 v[80:81], v54 offset0:20 offset1:28
	ds_read2_b32 v[82:83], v54 offset0:85 offset1:93
	ds_read2_b32 v[84:85], v54 offset0:150 offset1:158
	ds_read2_b32 v[86:87], v54 offset0:215 offset1:223
	ds_read2_b32 v[88:89], v21 offset0:32 offset1:40
	ds_read2_b32 v[90:91], v21 offset0:97 offset1:105
	ds_read2_b32 v[92:93], v21 offset0:162 offset1:170
	ds_read2_b32 v[94:95], v21 offset0:227 offset1:235
	ds_read2_b32 v[96:97], v54 offset0:36 offset1:44
	ds_read2_b32 v[98:99], v54 offset0:101 offset1:109
	ds_read2_b32 v[100:101], v54 offset0:166 offset1:174
	ds_read2_b32 v[102:103], v54 offset0:231 offset1:239
	ds_read2_b32 v[104:105], v21 offset0:48 offset1:56
	ds_read2_b32 v[106:107], v21 offset0:113 offset1:121
	ds_read2_b32 v[108:109], v21 offset0:178 offset1:186
	ds_read2_b32 v[110:111], v21 offset0:243 offset1:251
	ds_read2_b32 v[112:113], v54 offset0:52 offset1:60
	ds_read2_b32 v[114:115], v54 offset0:117 offset1:125
	ds_read2_b32 v[116:117], v54 offset0:182 offset1:190
	ds_read2_b32 v[118:119], v54 offset0:247 offset1:255
	v_lshl_add_u64 v[10:11], v[18:19], 0, v[10:11]
	v_lshl_add_u64 v[12:13], v[18:19], 0, v[12:13]
	v_lshl_add_u64 v[14:15], v[18:19], 0, v[14:15]
	v_lshl_add_u64 v[16:17], v[18:19], 0, v[16:17]
	v_lshl_add_u64 v[18:19], v[18:19], 0, v[124:125]
	s_waitcnt lgkmcnt(14)
	v_bfe_u32 v55, v58, 16, 1
	v_bfe_u32 v121, v60, 16, 1
	v_bfe_u32 v122, v62, 16, 1
	v_bfe_u32 v123, v64, 16, 1
	v_bfe_u32 v124, v66, 16, 1
	v_bfe_u32 v125, v68, 16, 1
	v_bfe_u32 v120, v56, 16, 1
	v_bfe_u32 v126, v70, 16, 1
	v_bfe_u32 v127, v59, 16, 1
	v_bfe_u32 v128, v57, 16, 1
	v_bfe_u32 v129, v61, 16, 1
	v_bfe_u32 v130, v63, 16, 1
	v_bfe_u32 v131, v65, 16, 1
	v_bfe_u32 v132, v67, 16, 1
	v_bfe_u32 v133, v69, 16, 1
	v_bfe_u32 v134, v71, 16, 1
	v_bfe_u32 v135, v74, 16, 1
	v_bfe_u32 v137, v76, 16, 1
	v_bfe_u32 v138, v78, 16, 1
	v_bfe_u32 v139, v80, 16, 1
	v_bfe_u32 v140, v82, 16, 1
	v_bfe_u32 v141, v84, 16, 1
	v_bfe_u32 v142, v86, 16, 1
	v_bfe_u32 v143, v75, 16, 1
	v_bfe_u32 v145, v77, 16, 1
	v_bfe_u32 v147, v81, 16, 1
	v_bfe_u32 v149, v85, 16, 1
	v_bfe_u32 v150, v87, 16, 1
	v_bfe_u32 v151, v88, 16, 1
	v_bfe_u32 v152, v90, 16, 1
	s_waitcnt lgkmcnt(13)
	v_bfe_u32 v153, v92, 16, 1
	s_waitcnt lgkmcnt(12)
	v_bfe_u32 v154, v94, 16, 1
	s_waitcnt lgkmcnt(11)
	v_bfe_u32 v155, v96, 16, 1
	s_waitcnt lgkmcnt(10)
	v_bfe_u32 v156, v98, 16, 1
	s_waitcnt lgkmcnt(9)
	v_bfe_u32 v157, v100, 16, 1
	s_waitcnt lgkmcnt(8)
	v_bfe_u32 v158, v102, 16, 1
	v_bfe_u32 v159, v89, 16, 1
	v_bfe_u32 v161, v93, 16, 1
	v_bfe_u32 v163, v97, 16, 1
	v_bfe_u32 v165, v101, 16, 1
	v_bfe_u32 v166, v103, 16, 1
	s_waitcnt lgkmcnt(7)
	v_bfe_u32 v167, v104, 16, 1
	s_waitcnt lgkmcnt(6)
	v_bfe_u32 v168, v106, 16, 1
	v_bfe_u32 v169, v105, 16, 1
	v_bfe_u32 v170, v107, 16, 1
	s_waitcnt lgkmcnt(5)
	v_bfe_u32 v171, v108, 16, 1
	v_bfe_u32 v172, v109, 16, 1
	s_waitcnt lgkmcnt(4)
	v_bfe_u32 v173, v110, 16, 1
	v_bfe_u32 v174, v111, 16, 1
	s_waitcnt lgkmcnt(3)
	v_bfe_u32 v175, v112, 16, 1
	v_bfe_u32 v176, v113, 16, 1
	s_waitcnt lgkmcnt(2)
	v_bfe_u32 v177, v114, 16, 1
	v_bfe_u32 v178, v115, 16, 1
	s_waitcnt lgkmcnt(1)
	v_bfe_u32 v179, v116, 16, 1
	v_bfe_u32 v180, v117, 16, 1
	v_add3_u32 v55, v58, v55, s13
	v_add3_u32 v58, v60, v121, s13
	v_add3_u32 v60, v62, v122, s13
	v_add3_u32 v62, v64, v123, s13
	v_add3_u32 v64, v66, v124, s13
	v_add3_u32 v66, v68, v125, s13
	v_bfe_u32 v136, v72, 16, 1
	v_bfe_u32 v144, v73, 16, 1
	v_bfe_u32 v146, v79, 16, 1
	v_bfe_u32 v148, v83, 16, 1
	v_bfe_u32 v160, v91, 16, 1
	v_bfe_u32 v162, v95, 16, 1
	v_bfe_u32 v164, v99, 16, 1
	s_waitcnt lgkmcnt(0)
; #define LAS __attribute__((address_space(3)))
; __device__ __forceinline__ unsigned pk2(float lo, float hi) { return f2bf(lo) | (f2bf(hi) << 16); }
; #define LDS_WAIT() asm volatile("s_waitcnt lgkmcnt(0)" ::: "memory")
; template <int MODE>
; __device__ __forceinline__ void transpose_item(const float* W, const float* W2, int K, int Nsrc, int Ndst, bf16_t* WT, LAS float* scr, int item, int lane) {
;     ...
;     for (int j = 0; j < 8; ++j) { const int n = (lane >> 3) + 8 * j; const LAS float* sp = scr + (8 * c) * 65 + n;
;         u32x4 o; o.x = pk2(sp[0 * 65], sp[1 * 65]); o.y = pk2(sp[2 * 65], sp[3 * 65]); o.z = pk2(sp[4 * 65], sp[5 * 65]); o.w = pk2(sp[6 * 65], sp[7 * 65]);
;         *(u32x4*)(WT + (size_t)(n0 + n) * K + k0 + 8 * c) = o; }
;     LDS_WAIT(); asm volatile("" ::: "memory");
; }
; template <int MODE>
; __device__ __forceinline__ void convert_weight(Frame& F, const float* W, const float* W2, int K, int Nsrc, int Ndst, bf16_t* WT) {
;     LAS float* scr = (LAS float*)(F.lds + F.wave * 17408);
;     const int gw = F.bid * NWAVES + F.wave, NGW = F.G * NWAVES, nitems = (K / 64) * (Ndst / 64);
;     for (int it = gw; it < nitems; it += NGW) transpose_item<MODE>(W, W2, K, Nsrc, Ndst, WT, scr, it, F.lane);
	v_bfe_u32 v181, v118, 16, 1
	v_bfe_u32 v182, v119, 16, 1
	v_add3_u32 v56, v56, v120, s13
	v_add3_u32 v68, v70, v126, s13
	v_add3_u32 v59, v59, v127, s13
	v_add3_u32 v70, v57, v128, s13
	v_add3_u32 v57, v61, v129, s13
	v_add3_u32 v61, v63, v130, s13
	v_add3_u32 v63, v65, v131, s13
	v_add3_u32 v65, v67, v132, s13
	v_add3_u32 v67, v69, v133, s13
	v_add3_u32 v69, v71, v134, s13
	v_add3_u32 v71, v74, v135, s13
	v_add3_u32 v74, v76, v137, s13
	v_add3_u32 v76, v78, v138, s13
	v_add3_u32 v78, v80, v139, s13
	v_add3_u32 v80, v82, v140, s13
	v_add3_u32 v82, v84, v141, s13
	v_add3_u32 v84, v86, v142, s13
	v_add3_u32 v75, v75, v143, s13
	v_add3_u32 v77, v77, v145, s13
	v_add3_u32 v81, v81, v147, s13
	v_add3_u32 v85, v85, v149, s13
	v_add3_u32 v86, v87, v150, s13
	v_add3_u32 v87, v88, v151, s13
	v_add3_u32 v88, v90, v152, s13
	v_add3_u32 v90, v92, v153, s13
	v_add3_u32 v92, v94, v154, s13
	v_add3_u32 v94, v96, v155, s13
	v_add3_u32 v96, v98, v156, s13
	v_add3_u32 v98, v100, v157, s13
	v_add3_u32 v100, v102, v158, s13
	v_add3_u32 v89, v89, v159, s13
	v_add3_u32 v93, v93, v161, s13
	v_add3_u32 v97, v97, v163, s13
	v_add3_u32 v101, v101, v165, s13
	v_add3_u32 v102, v103, v166, s13
	v_add3_u32 v103, v104, v167, s13
	v_add3_u32 v104, v105, v169, s13
	v_add3_u32 v105, v106, v168, s13
	v_add3_u32 v106, v107, v170, s13
	v_add3_u32 v107, v108, v171, s13
	v_add3_u32 v108, v109, v172, s13
	v_add3_u32 v109, v110, v173, s13
	v_add3_u32 v110, v111, v174, s13
	v_add3_u32 v111, v112, v175, s13
	v_add3_u32 v112, v113, v176, s13
	v_add3_u32 v113, v114, v177, s13
	v_add3_u32 v114, v115, v178, s13
	v_add3_u32 v115, v116, v179, s13
	v_add3_u32 v116, v117, v180, s13
	v_lshrrev_b32_e32 v55, 16, v55
	v_lshrrev_b32_e32 v58, 16, v58
	v_lshrrev_b32_e32 v62, 16, v62
	v_lshrrev_b32_e32 v66, 16, v66
	v_add3_u32 v72, v72, v136, s13
	v_add3_u32 v73, v73, v144, s13
	v_add3_u32 v79, v79, v146, s13
	v_add3_u32 v83, v83, v148, s13
	v_add3_u32 v91, v91, v160, s13
	v_add3_u32 v95, v95, v162, s13
	v_add3_u32 v99, v99, v164, s13
	v_add3_u32 v117, v118, v181, s13
	v_add3_u32 v118, v119, v182, s13
	v_lshrrev_b32_e32 v119, 16, v59
	v_lshrrev_b32_e32 v120, 16, v57
	v_lshrrev_b32_e32 v63, 16, v63
	v_lshrrev_b32_e32 v67, 16, v67
	v_lshrrev_b32_e32 v71, 16, v71
	v_lshrrev_b32_e32 v74, 16, v74
	v_lshrrev_b32_e32 v78, 16, v78
	v_lshrrev_b32_e32 v82, 16, v82
	v_lshrrev_b32_e32 v75, 16, v75
	v_lshrrev_b32_e32 v77, 16, v77
	v_lshrrev_b32_e32 v81, 16, v81
	v_lshrrev_b32_e32 v85, 16, v85
	v_lshrrev_b32_e32 v87, 16, v87
	v_lshrrev_b32_e32 v90, 16, v90
	v_lshrrev_b32_e32 v94, 16, v94
	v_lshrrev_b32_e32 v98, 16, v98
	v_lshrrev_b32_e32 v89, 16, v89
	v_lshrrev_b32_e32 v93, 16, v93
	v_lshrrev_b32_e32 v97, 16, v97
	v_lshrrev_b32_e32 v101, 16, v101
	v_lshrrev_b32_e32 v103, 16, v103
	v_lshrrev_b32_e32 v107, 16, v107
	v_lshrrev_b32_e32 v111, 16, v111
	v_lshrrev_b32_e32 v115, 16, v115
	v_lshrrev_b32_e32 v104, 16, v104
	v_lshrrev_b32_e32 v108, 16, v108
	v_lshrrev_b32_e32 v112, 16, v112
	v_lshrrev_b32_e32 v116, 16, v116
	v_and_or_b32 v56, v56, s14, v55
	v_and_or_b32 v57, v60, s14, v58
	v_and_or_b32 v58, v64, s14, v62
	v_and_or_b32 v59, v68, s14, v66
	v_and_or_b32 v60, v70, s14, v119
	v_and_or_b32 v61, v61, s14, v120
	v_and_or_b32 v62, v65, s14, v63
	v_and_or_b32 v63, v69, s14, v67
	v_and_or_b32 v64, v72, s14, v71
	v_and_or_b32 v65, v76, s14, v74
	v_and_or_b32 v66, v80, s14, v78
	v_and_or_b32 v67, v84, s14, v82
	v_and_or_b32 v68, v73, s14, v75
	v_and_or_b32 v69, v79, s14, v77
	v_and_or_b32 v70, v83, s14, v81
	v_and_or_b32 v71, v86, s14, v85
	v_and_or_b32 v72, v88, s14, v87
	v_and_or_b32 v73, v92, s14, v90
	v_and_or_b32 v74, v96, s14, v94
	v_and_or_b32 v75, v100, s14, v98
	v_and_or_b32 v76, v91, s14, v89
	v_and_or_b32 v77, v95, s14, v93
	v_and_or_b32 v78, v99, s14, v97
	v_and_or_b32 v79, v102, s14, v101
	v_and_or_b32 v80, v105, s14, v103
	v_and_or_b32 v81, v109, s14, v107
	v_and_or_b32 v82, v113, s14, v111
	v_and_or_b32 v83, v117, s14, v115
	v_and_or_b32 v84, v106, s14, v104
	v_and_or_b32 v85, v110, s14, v108
	v_and_or_b32 v86, v114, s14, v112
	v_and_or_b32 v87, v118, s14, v116
	global_store_dwordx4 v[6:7], v[56:59], off
	global_store_dwordx4 v[8:9], v[60:63], off
	global_store_dwordx4 v[10:11], v[64:67], off
	global_store_dwordx4 v[12:13], v[68:71], off
	global_store_dwordx4 v[14:15], v[72:75], off
	global_store_dwordx4 v[16:17], v[76:79], off
	global_store_dwordx4 v[18:19], v[80:83], off
	global_store_dwordx4 v[4:5], v[84:87], off
	s_waitcnt lgkmcnt(0)
	s_add_i32 s15, s15, s12
	s_add_i32 s5, s5, s6
	s_cmpk_lt_i32 s15, 0x1600
	v_add_u32_e32 v22, s7, v22
	s_cbranch_scc1 .LBB0_25

; #define LAS __attribute__((address_space(3)))
; template <int MODE>
; __device__ __forceinline__ void transpose_item(const float* W, const float* W2, int K, int Nsrc, int Ndst, bf16_t* WT, LAS float* scr, int item, int lane) {
;     const int nblk = Ndst / 64, kb = item / nblk, nb = item % nblk, k0 = 64 * kb, n0 = 64 * nb;
;     const int c4 = lane & 15, r4 = lane >> 4;
;     const float* src; bool ok = true; int lcol;
;     if (MODE == 0) { src = W + n0 + 4 * c4; ok = (n0 + 4 * c4) < Nsrc; lcol = 4 * c4; }
;     else if (MODE == 2) {
;         const int n = n0 + 4 * c4; int sc = -1; if (n < 3264) sc = 2120 + n; else if (n >= 3328 && n < 3328 + 2120) sc = n - 3328;
;         ok = sc >= 0; src = W + (ok ? sc : 0); lcol = 4 * c4; }
;     else if (MODE == 3) { const int n = n0 + 4 * c4; ok = n < 2120; src = W + (ok ? n : 0); lcol = 4 * c4; }
;     else { const int t = c4 >> 3, g = c4 & 7; src = (t ? W2 : W) + n0 / 2 + 4 * g; lcol = 8 * g + 4 * t; }
;     f32x4 v[16];
; #pragma unroll
;     for (int i = 0; i < 16; ++i) v[i] = ok ? *(const f32x4*)(src + (size_t)(k0 + 4 * i + r4) * Nsrc) : (f32x4){0.f, 0.f, 0.f, 0.f};
; #pragma unroll
;     for (int i = 0; i < 16; ++i) { LAS float* d = scr + (4 * i + r4) * 65 + lcol; d[0] = v[i].x; d[1] = v[i].y; d[2] = v[i].z; d[3] = v[i].w; }
.LBB0_28:
	s_ashr_i32 s14, s13, 31
	s_lshr_b32 s14, s14, 27
	s_add_i32 s14, s13, s14
	s_ashr_i32 s15, s14, 5
	s_lshl_b32 s14, s15, 6
	s_mul_i32 s17, s15, 0xff500000
	s_lshl_b32 s16, s15, 11
	v_or_b32_e32 v4, s14, v20
	v_add_u32_e32 v6, s17, v22
	s_sub_i32 s16, s5, s16
	s_ashr_i32 s15, s14, 31
	v_or_b32_e32 v8, 4, v4
	v_or_b32_e32 v10, 8, v4
	v_or_b32_e32 v12, 12, v4
	v_or_b32_e32 v14, 16, v4
	v_or_b32_e32 v16, 20, v4
	v_or_b32_e32 v18, 24, v4
	v_or_b32_e32 v56, 28, v4
	v_or_b32_e32 v58, 32, v4
	v_or_b32_e32 v60, 36, v4
	v_or_b32_e32 v62, 40, v4
	v_or_b32_e32 v64, 44, v4
	v_or_b32_e32 v66, 48, v4
	v_add_u32_e32 v70, 0xb000, v6
	v_add_u32_e32 v72, 0x16000, v6
	v_add_u32_e32 v74, 0x21000, v6
	v_add_u32_e32 v76, 0x2c000, v6
	v_add_u32_e32 v78, 0x37000, v6
	v_add_u32_e32 v80, 0x42000, v6
	v_add_u32_e32 v82, 0x4d000, v6
	s_ashr_i32 s17, s16, 31
	v_ashrrev_i32_e32 v5, 31, v4
	v_lshl_add_u64 v[68:69], s[14:15], 1, v[2:3]
	v_ashrrev_i32_e32 v7, 31, v6
	v_or_b32_e32 v84, 52, v4
	v_or_b32_e32 v86, 56, v4
	v_or_b32_e32 v88, 60, v4
	v_ashrrev_i32_e32 v9, 31, v8
	v_ashrrev_i32_e32 v11, 31, v10
	v_ashrrev_i32_e32 v13, 31, v12
	v_ashrrev_i32_e32 v15, 31, v14
	v_ashrrev_i32_e32 v17, 31, v16
	v_ashrrev_i32_e32 v19, 31, v18
	v_ashrrev_i32_e32 v57, 31, v56
	v_ashrrev_i32_e32 v71, 31, v70
	v_ashrrev_i32_e32 v73, 31, v72
	v_ashrrev_i32_e32 v75, 31, v74
	v_ashrrev_i32_e32 v77, 31, v76
	v_ashrrev_i32_e32 v79, 31, v78
	v_ashrrev_i32_e32 v81, 31, v80
	v_ashrrev_i32_e32 v83, 31, v82
	v_ashrrev_i32_e32 v59, 31, v58
	v_ashrrev_i32_e32 v61, 31, v60
	v_ashrrev_i32_e32 v63, 31, v62
	v_ashrrev_i32_e32 v65, 31, v64
	v_ashrrev_i32_e32 v67, 31, v66
	v_lshl_add_u64 v[90:91], s[16:17], 2, v[0:1]
	v_lshlrev_b64 v[92:93], 13, v[4:5]
	v_lshl_add_u64 v[4:5], v[6:7], 1, v[68:69]
	v_ashrrev_i32_e32 v85, 31, v84
	v_ashrrev_i32_e32 v87, 31, v86
	v_ashrrev_i32_e32 v89, 31, v88
	v_lshlrev_b64 v[94:95], 13, v[8:9]
	v_lshlrev_b64 v[96:97], 13, v[10:11]
	v_lshlrev_b64 v[98:99], 13, v[12:13]
	v_lshlrev_b64 v[100:101], 13, v[14:15]
	v_lshlrev_b64 v[102:103], 13, v[16:17]
	v_lshlrev_b64 v[104:105], 13, v[18:19]
	v_lshlrev_b64 v[106:107], 13, v[56:57]
	v_lshl_add_u64 v[6:7], v[70:71], 1, v[68:69]
	v_lshl_add_u64 v[8:9], v[72:73], 1, v[68:69]
	v_lshl_add_u64 v[10:11], v[74:75], 1, v[68:69]
	v_lshl_add_u64 v[12:13], v[76:77], 1, v[68:69]
	v_lshl_add_u64 v[14:15], v[78:79], 1, v[68:69]
	v_lshl_add_u64 v[16:17], v[80:81], 1, v[68:69]
	v_lshl_add_u64 v[18:19], v[82:83], 1, v[68:69]
	v_lshlrev_b64 v[68:69], 13, v[58:59]
	v_lshlrev_b64 v[60:61], 13, v[60:61]
	v_lshlrev_b64 v[62:63], 13, v[62:63]
	v_lshlrev_b64 v[64:65], 13, v[64:65]
	v_lshlrev_b64 v[66:67], 13, v[66:67]
	v_lshl_add_u64 v[92:93], v[90:91], 0, v[92:93]
	v_lshlrev_b64 v[70:71], 13, v[84:85]
	v_lshlrev_b64 v[72:73], 13, v[86:87]
	v_lshlrev_b64 v[74:75], 13, v[88:89]
	v_lshl_add_u64 v[108:109], v[90:91], 0, v[94:95]
	v_lshl_add_u64 v[96:97], v[90:91], 0, v[96:97]
	v_lshl_add_u64 v[98:99], v[90:91], 0, v[98:99]
	v_lshl_add_u64 v[100:101], v[90:91], 0, v[100:101]
	v_lshl_add_u64 v[102:103], v[90:91], 0, v[102:103]
	v_lshl_add_u64 v[104:105], v[90:91], 0, v[104:105]
	v_lshl_add_u64 v[106:107], v[90:91], 0, v[106:107]
	v_lshl_add_u64 v[110:111], v[90:91], 0, v[68:69]
	v_lshl_add_u64 v[112:113], v[90:91], 0, v[60:61]
	v_lshl_add_u64 v[114:115], v[90:91], 0, v[62:63]
	v_lshl_add_u64 v[116:117], v[90:91], 0, v[64:65]
	v_lshl_add_u64 v[118:119], v[90:91], 0, v[66:67]
	global_load_dwordx4 v[56:59], v[92:93], off nt
	v_lshl_add_u64 v[120:121], v[90:91], 0, v[70:71]
	v_lshl_add_u64 v[122:123], v[90:91], 0, v[72:73]
	v_lshl_add_u64 v[124:125], v[90:91], 0, v[74:75]
	global_load_dwordx4 v[60:63], v[108:109], off nt
	global_load_dwordx4 v[64:67], v[96:97], off nt
	global_load_dwordx4 v[68:71], v[98:99], off nt
	global_load_dwordx4 v[72:75], v[100:101], off nt
	global_load_dwordx4 v[76:79], v[102:103], off nt
	global_load_dwordx4 v[80:83], v[104:105], off nt
	global_load_dwordx4 v[84:87], v[106:107], off nt
	global_load_dwordx4 v[88:91], v[110:111], off nt
	global_load_dwordx4 v[92:95], v[112:113], off nt
	global_load_dwordx4 v[96:99], v[114:115], off nt
	global_load_dwordx4 v[100:103], v[116:117], off nt
	s_nop 0
	global_load_dwordx4 v[104:107], v[118:119], off nt
	global_load_dwordx4 v[108:111], v[120:121], off nt
	global_load_dwordx4 v[112:115], v[122:123], off nt
	s_nop 0
	global_load_dwordx4 v[116:119], v[124:125], off nt
	s_waitcnt vmcnt(15)
	ds_write2_b32 v23, v56, v57 offset1:1
	ds_write2_b32 v23, v58, v59 offset0:2 offset1:3
	s_waitcnt vmcnt(14)
	ds_write2_b32 v24, v60, v61 offset1:1
	ds_write2_b32 v25, v62, v63 offset1:1
	s_waitcnt vmcnt(13)
	ds_write2_b32 v26, v64, v65 offset1:1
	ds_write2_b32 v27, v66, v67 offset1:1
	s_waitcnt vmcnt(12)
	ds_write2_b32 v28, v68, v69 offset1:1
	ds_write2_b32 v29, v70, v71 offset1:1
	s_waitcnt vmcnt(11)
	ds_write2_b32 v30, v72, v73 offset1:1
	ds_write2_b32 v31, v74, v75 offset1:1
	s_waitcnt vmcnt(10)
	ds_write2_b32 v32, v76, v77 offset1:1
	ds_write2_b32 v33, v78, v79 offset1:1
	s_waitcnt vmcnt(9)
	ds_write2_b32 v34, v80, v81 offset1:1
	ds_write2_b32 v35, v82, v83 offset1:1
	s_waitcnt vmcnt(8)
	ds_write2_b32 v36, v84, v85 offset1:1
	ds_write2_b32 v37, v86, v87 offset1:1
	s_waitcnt vmcnt(7)
	ds_write2_b32 v38, v88, v89 offset1:1
	ds_write2_b32 v39, v90, v91 offset1:1
	s_waitcnt vmcnt(6)
	ds_write2_b32 v40, v92, v93 offset1:1
	ds_write2_b32 v41, v94, v95 offset1:1
	s_waitcnt vmcnt(5)
	ds_write2_b32 v42, v96, v97 offset1:1
	ds_write2_b32 v43, v98, v99 offset1:1
	s_waitcnt vmcnt(4)
	ds_write2_b32 v44, v100, v101 offset1:1
	ds_write2_b32 v45, v102, v103 offset1:1
	s_waitcnt vmcnt(3)
; #define LAS __attribute__((address_space(3)))
; __device__ __forceinline__ unsigned pk2(float lo, float hi) { return f2bf(lo) | (f2bf(hi) << 16); }
; #define LDS_WAIT() asm volatile("s_waitcnt lgkmcnt(0)" ::: "memory")
; template <int MODE>
; __device__ __forceinline__ void transpose_item(const float* W, const float* W2, int K, int Nsrc, int Ndst, bf16_t* WT, LAS float* scr, int item, int lane) {
;     ...
;     for (int i = 0; i < 16; ++i) { LAS float* d = scr + (4 * i + r4) * 65 + lcol; d[0] = v[i].x; d[1] = v[i].y; d[2] = v[i].z; d[3] = v[i].w; }
;     LDS_WAIT(); asm volatile("" ::: "memory");
;     const int c = lane & 7;
; #pragma unroll
;     for (int j = 0; j < 8; ++j) { const int n = (lane >> 3) + 8 * j; const LAS float* sp = scr + (8 * c) * 65 + n;
;         u32x4 o; o.x = pk2(sp[0 * 65], sp[1 * 65]); o.y = pk2(sp[2 * 65], sp[3 * 65]); o.z = pk2(sp[4 * 65], sp[5 * 65]); o.w = pk2(sp[6 * 65], sp[7 * 65]);
	ds_write2_b32 v46, v104, v105 offset1:1
	ds_write2_b32 v47, v106, v107 offset1:1
	s_waitcnt vmcnt(2)
	ds_write2_b32 v48, v108, v109 offset1:1
	ds_write2_b32 v49, v110, v111 offset1:1
	s_waitcnt vmcnt(1)
	ds_write2_b32 v50, v112, v113 offset1:1
	ds_write2_b32 v51, v114, v115 offset1:1
	s_waitcnt vmcnt(0)
	ds_write2_b32 v52, v116, v117 offset1:1
	ds_write2_b32 v53, v118, v119 offset1:1
	s_waitcnt lgkmcnt(0)
	ds_read2_b32 v[56:57], v21 offset0:65 offset1:73
	ds_read2_b32 v[58:59], v21 offset1:8
	ds_read2_b32 v[60:61], v21 offset0:130 offset1:138
	ds_read2_b32 v[62:63], v21 offset0:195 offset1:203
	ds_read2_b32 v[64:65], v54 offset0:4 offset1:12
	ds_read2_b32 v[66:67], v54 offset0:69 offset1:77
	ds_read2_b32 v[68:69], v54 offset0:134 offset1:142
	ds_read2_b32 v[70:71], v54 offset0:199 offset1:207
	ds_read2_b32 v[72:73], v21 offset0:81 offset1:89
	ds_read2_b32 v[74:75], v21 offset0:16 offset1:24
	ds_read2_b32 v[76:77], v21 offset0:146 offset1:154
	ds_read2_b32 v[78:79], v21 offset0:211 offset1:219
	ds_read2_b32 v[80:81], v54 offset0:20 offset1:28
	ds_read2_b32 v[82:83], v54 offset0:85 offset1:93
	ds_read2_b32 v[84:85], v54 offset0:150 offset1:158
	ds_read2_b32 v[86:87], v54 offset0:215 offset1:223
	ds_read2_b32 v[88:89], v21 offset0:32 offset1:40
	ds_read2_b32 v[90:91], v21 offset0:97 offset1:105
	ds_read2_b32 v[92:93], v21 offset0:162 offset1:170
	ds_read2_b32 v[94:95], v21 offset0:227 offset1:235
	ds_read2_b32 v[96:97], v54 offset0:36 offset1:44
	ds_read2_b32 v[98:99], v54 offset0:101 offset1:109
	ds_read2_b32 v[100:101], v54 offset0:166 offset1:174
	ds_read2_b32 v[102:103], v54 offset0:231 offset1:239
	ds_read2_b32 v[104:105], v21 offset0:48 offset1:56
	ds_read2_b32 v[106:107], v21 offset0:113 offset1:121
	ds_read2_b32 v[108:109], v21 offset0:178 offset1:186
	ds_read2_b32 v[110:111], v21 offset0:243 offset1:251
	ds_read2_b32 v[112:113], v54 offset0:52 offset1:60
	ds_read2_b32 v[114:115], v54 offset0:117 offset1:125
	ds_read2_b32 v[116:117], v54 offset0:182 offset1:190
	ds_read2_b32 v[118:119], v54 offset0:247 offset1:255
	s_waitcnt lgkmcnt(14)
	v_bfe_u32 v55, v58, 16, 1
	v_bfe_u32 v121, v60, 16, 1
	v_bfe_u32 v122, v62, 16, 1
	v_bfe_u32 v123, v64, 16, 1
	v_bfe_u32 v124, v66, 16, 1
	v_bfe_u32 v125, v68, 16, 1
	v_bfe_u32 v120, v56, 16, 1
	v_bfe_u32 v126, v70, 16, 1
	v_bfe_u32 v127, v59, 16, 1
	v_bfe_u32 v128, v57, 16, 1
	v_bfe_u32 v129, v61, 16, 1
	v_bfe_u32 v130, v63, 16, 1
	v_bfe_u32 v131, v65, 16, 1
	v_bfe_u32 v132, v67, 16, 1
	v_bfe_u32 v133, v69, 16, 1
	v_bfe_u32 v134, v71, 16, 1
	v_bfe_u32 v135, v74, 16, 1
	v_bfe_u32 v137, v75, 16, 1
	v_bfe_u32 v138, v76, 16, 1
	v_bfe_u32 v140, v78, 16, 1
	v_bfe_u32 v141, v77, 16, 1
	v_bfe_u32 v142, v80, 16, 1
	v_bfe_u32 v143, v79, 16, 1
	v_bfe_u32 v144, v82, 16, 1
	v_bfe_u32 v145, v81, 16, 1
	v_bfe_u32 v146, v84, 16, 1
	v_bfe_u32 v147, v83, 16, 1
	v_bfe_u32 v148, v86, 16, 1
	v_bfe_u32 v149, v85, 16, 1
	v_bfe_u32 v150, v87, 16, 1
	v_bfe_u32 v151, v88, 16, 1
	v_bfe_u32 v152, v90, 16, 1
	v_bfe_u32 v153, v89, 16, 1
	s_waitcnt lgkmcnt(13)
	v_bfe_u32 v154, v92, 16, 1
	v_bfe_u32 v155, v91, 16, 1
	v_bfe_u32 v156, v93, 16, 1
	s_waitcnt lgkmcnt(12)
	v_bfe_u32 v157, v94, 16, 1
	v_bfe_u32 v158, v95, 16, 1
	s_waitcnt lgkmcnt(11)
	v_bfe_u32 v159, v96, 16, 1
	v_bfe_u32 v160, v97, 16, 1
	s_waitcnt lgkmcnt(10)
	v_bfe_u32 v161, v98, 16, 1
	v_bfe_u32 v162, v99, 16, 1
	s_waitcnt lgkmcnt(9)
	v_bfe_u32 v163, v100, 16, 1
	v_bfe_u32 v164, v101, 16, 1
	s_waitcnt lgkmcnt(8)
	v_bfe_u32 v165, v102, 16, 1
	v_bfe_u32 v166, v103, 16, 1
	s_waitcnt lgkmcnt(7)
	v_bfe_u32 v167, v104, 16, 1
	v_bfe_u32 v168, v105, 16, 1
	s_waitcnt lgkmcnt(6)
	v_bfe_u32 v169, v106, 16, 1
	v_bfe_u32 v170, v107, 16, 1
	s_waitcnt lgkmcnt(5)
	v_bfe_u32 v171, v108, 16, 1
	v_bfe_u32 v172, v109, 16, 1
	s_waitcnt lgkmcnt(4)
	v_bfe_u32 v173, v110, 16, 1
	v_bfe_u32 v174, v111, 16, 1
	s_waitcnt lgkmcnt(3)
	v_bfe_u32 v175, v112, 16, 1
	v_bfe_u32 v176, v113, 16, 1
	s_waitcnt lgkmcnt(2)
	v_bfe_u32 v177, v114, 16, 1
	v_bfe_u32 v178, v115, 16, 1
	s_waitcnt lgkmcnt(1)
	v_bfe_u32 v179, v116, 16, 1
	v_bfe_u32 v180, v117, 16, 1
	v_add3_u32 v55, v58, v55, s7
	v_add3_u32 v58, v60, v121, s7
	v_add3_u32 v60, v62, v122, s7
	v_add3_u32 v62, v64, v123, s7
	v_add3_u32 v64, v66, v124, s7
	v_add3_u32 v66, v68, v125, s7
	v_bfe_u32 v136, v72, 16, 1
	v_bfe_u32 v139, v73, 16, 1
	s_waitcnt lgkmcnt(0)
; #define LAS __attribute__((address_space(3)))
; __device__ __forceinline__ unsigned pk2(float lo, float hi) { return f2bf(lo) | (f2bf(hi) << 16); }
; #define LDS_WAIT() asm volatile("s_waitcnt lgkmcnt(0)" ::: "memory")
; template <int MODE>
; __device__ __forceinline__ void transpose_item(const float* W, const float* W2, int K, int Nsrc, int Ndst, bf16_t* WT, LAS float* scr, int item, int lane) {
;     ...
;     for (int j = 0; j < 8; ++j) { const int n = (lane >> 3) + 8 * j; const LAS float* sp = scr + (8 * c) * 65 + n;
;         u32x4 o; o.x = pk2(sp[0 * 65], sp[1 * 65]); o.y = pk2(sp[2 * 65], sp[3 * 65]); o.z = pk2(sp[4 * 65], sp[5 * 65]); o.w = pk2(sp[6 * 65], sp[7 * 65]);
;         *(u32x4*)(WT + (size_t)(n0 + n) * K + k0 + 8 * c) = o; }
;     LDS_WAIT(); asm volatile("" ::: "memory");
; template <bool OUT_BF16>
; __device__ __forceinline__ void rmsnorm_rows(Frame& F, const float* X, const float* gain, void* O) {
;     const int gw = F.bid * NWAVES + F.wave, NGW = F.G * NWAVES;
;     f32x4 gv[8];
; #pragma unroll
;     for (int j = 0; j < 8; ++j) gv[j] = ((const f32x4*)gain)[F.lane + 64 * j];
;     for (int m = gw; m < S; m += NGW) {
;         const f32x4* xr = (const f32x4*)(X + (size_t)m * DM) + F.lane;
;         f32x4 v[8]; float s = 0.f;
; #pragma unroll
;         for (int j = 0; j < 8; ++j) { v[j] = xr[64 * j]; s += (v[j].x * v[j].x + v[j].y * v[j].y) + (v[j].z * v[j].z + v[j].w * v[j].w); }
;         const float rs = 1.f / sqrtf(wave_sum(s) * (1.f / DM) + NORM_EPS);
	v_bfe_u32 v181, v118, 16, 1
	v_bfe_u32 v182, v119, 16, 1
	v_add3_u32 v56, v56, v120, s7
	v_add3_u32 v68, v70, v126, s7
	v_add3_u32 v59, v59, v127, s7
	v_add3_u32 v70, v57, v128, s7
	v_add3_u32 v57, v61, v129, s7
	v_add3_u32 v61, v63, v130, s7
	v_add3_u32 v63, v65, v131, s7
	v_add3_u32 v65, v67, v132, s7
	v_add3_u32 v67, v69, v133, s7
	v_add3_u32 v69, v71, v134, s7
	v_add3_u32 v71, v74, v135, s7
	v_add3_u32 v74, v75, v137, s7
	v_add3_u32 v75, v76, v138, s7
	v_add3_u32 v76, v77, v141, s7
	v_add3_u32 v77, v78, v140, s7
	v_add3_u32 v78, v79, v143, s7
	v_add3_u32 v79, v80, v142, s7
	v_add3_u32 v80, v81, v145, s7
	v_add3_u32 v81, v82, v144, s7
	v_add3_u32 v82, v83, v147, s7
	v_add3_u32 v83, v84, v146, s7
	v_add3_u32 v84, v85, v149, s7
	v_add3_u32 v85, v86, v148, s7
	v_add3_u32 v86, v87, v150, s7
	v_add3_u32 v87, v88, v151, s7
	v_add3_u32 v88, v89, v153, s7
	v_add3_u32 v89, v90, v152, s7
	v_add3_u32 v90, v91, v155, s7
	v_add3_u32 v91, v92, v154, s7
	v_add3_u32 v92, v93, v156, s7
	v_add3_u32 v93, v94, v157, s7
	v_add3_u32 v94, v95, v158, s7
	v_add3_u32 v95, v96, v159, s7
	v_add3_u32 v96, v97, v160, s7
	v_add3_u32 v97, v98, v161, s7
	v_add3_u32 v98, v99, v162, s7
	v_add3_u32 v99, v100, v163, s7
	v_add3_u32 v100, v101, v164, s7
	v_add3_u32 v101, v102, v165, s7
	v_add3_u32 v102, v103, v166, s7
	v_add3_u32 v103, v104, v167, s7
	v_add3_u32 v104, v105, v168, s7
	v_add3_u32 v105, v106, v169, s7
	v_add3_u32 v106, v107, v170, s7
	v_add3_u32 v107, v108, v171, s7
	v_add3_u32 v108, v109, v172, s7
	v_add3_u32 v109, v110, v173, s7
	v_add3_u32 v110, v111, v174, s7
	v_add3_u32 v111, v112, v175, s7
	v_add3_u32 v112, v113, v176, s7
	v_add3_u32 v113, v114, v177, s7
	v_add3_u32 v114, v115, v178, s7
	v_add3_u32 v115, v116, v179, s7
	v_add3_u32 v116, v117, v180, s7
	v_lshrrev_b32_e32 v55, 16, v55
	v_lshrrev_b32_e32 v58, 16, v58
	v_lshrrev_b32_e32 v62, 16, v62
	v_lshrrev_b32_e32 v66, 16, v66
	v_add3_u32 v72, v72, v136, s7
	v_add3_u32 v73, v73, v139, s7
	v_add3_u32 v117, v118, v181, s7
	v_add3_u32 v118, v119, v182, s7
	v_lshrrev_b32_e32 v119, 16, v59
	v_lshrrev_b32_e32 v120, 16, v57
	v_lshrrev_b32_e32 v63, 16, v63
	v_lshrrev_b32_e32 v67, 16, v67
	v_lshrrev_b32_e32 v71, 16, v71
	v_lshrrev_b32_e32 v75, 16, v75
	v_lshrrev_b32_e32 v79, 16, v79
	v_lshrrev_b32_e32 v83, 16, v83
	v_lshrrev_b32_e32 v74, 16, v74
	v_lshrrev_b32_e32 v76, 16, v76
	v_lshrrev_b32_e32 v80, 16, v80
	v_lshrrev_b32_e32 v84, 16, v84
	v_lshrrev_b32_e32 v87, 16, v87
	v_lshrrev_b32_e32 v91, 16, v91
	v_lshrrev_b32_e32 v95, 16, v95
	v_lshrrev_b32_e32 v99, 16, v99
	v_lshrrev_b32_e32 v88, 16, v88
	v_lshrrev_b32_e32 v92, 16, v92
	v_lshrrev_b32_e32 v96, 16, v96
	v_lshrrev_b32_e32 v100, 16, v100
	v_lshrrev_b32_e32 v103, 16, v103
	v_lshrrev_b32_e32 v107, 16, v107
	v_lshrrev_b32_e32 v111, 16, v111
	v_lshrrev_b32_e32 v115, 16, v115
	v_lshrrev_b32_e32 v104, 16, v104
	v_lshrrev_b32_e32 v108, 16, v108
	v_lshrrev_b32_e32 v112, 16, v112
	v_lshrrev_b32_e32 v116, 16, v116
	v_and_or_b32 v56, v56, s11, v55
	v_and_or_b32 v57, v60, s11, v58
	v_and_or_b32 v58, v64, s11, v62
	v_and_or_b32 v59, v68, s11, v66
	v_and_or_b32 v60, v70, s11, v119
	v_and_or_b32 v61, v61, s11, v120
	v_and_or_b32 v62, v65, s11, v63
	v_and_or_b32 v63, v69, s11, v67
	v_and_or_b32 v64, v72, s11, v71
	v_and_or_b32 v65, v77, s11, v75
	v_and_or_b32 v66, v81, s11, v79
	v_and_or_b32 v67, v85, s11, v83
	v_and_or_b32 v68, v73, s11, v74
	v_and_or_b32 v69, v78, s11, v76
	v_and_or_b32 v70, v82, s11, v80
	v_and_or_b32 v71, v86, s11, v84
	v_and_or_b32 v72, v89, s11, v87
	v_and_or_b32 v73, v93, s11, v91
	v_and_or_b32 v74, v97, s11, v95
	v_and_or_b32 v75, v101, s11, v99
	v_and_or_b32 v76, v90, s11, v88
	v_and_or_b32 v77, v94, s11, v92
	v_and_or_b32 v78, v98, s11, v96
	v_and_or_b32 v79, v102, s11, v100
	v_and_or_b32 v80, v105, s11, v103
	v_and_or_b32 v81, v109, s11, v107
	v_and_or_b32 v82, v113, s11, v111
	v_and_or_b32 v83, v117, s11, v115
	v_and_or_b32 v84, v106, s11, v104
	v_and_or_b32 v85, v110, s11, v108
	v_and_or_b32 v86, v114, s11, v112
	v_and_or_b32 v87, v118, s11, v116
	global_store_dwordx4 v[4:5], v[56:59], off
	global_store_dwordx4 v[6:7], v[60:63], off
	global_store_dwordx4 v[8:9], v[64:67], off
	global_store_dwordx4 v[10:11], v[68:71], off
	global_store_dwordx4 v[12:13], v[72:75], off
	global_store_dwordx4 v[14:15], v[76:79], off
	global_store_dwordx4 v[16:17], v[80:83], off
	global_store_dwordx4 v[18:19], v[84:87], off
	s_waitcnt lgkmcnt(0)
	s_add_i32 s13, s13, s12
	s_add_i32 s5, s5, s6
	s_cmpk_lt_i32 s13, 0xb00
	v_add_u32_e32 v22, s4, v22
	s_cbranch_scc1 .LBB0_28
.LBB0_29:
	s_cmpk_gt_i32 s10, 0x3fff
	s_cbranch_scc1 .LBB0_32
	s_load_dwordx4 s[4:7], s[0:1], 0x0
	v_lshlrev_b32_e32 v32, 4, v184
	v_mov_b32_e32 v33, 0
	s_ashr_i32 s11, s10, 31
	s_mov_b64 s[14:15], 0x1000
	s_waitcnt lgkmcnt(0)
	v_lshl_add_u64 v[16:17], s[6:7], 0, v[32:33]
	v_add_co_u32_e32 v34, vcc, 0x1000, v16
	global_load_dwordx4 v[0:3], v32, s[6:7]
	global_load_dwordx4 v[4:7], v32, s[6:7] offset:1024
	v_addc_co_u32_e32 v35, vcc, 0, v17, vcc
	global_load_dwordx4 v[8:11], v32, s[6:7] offset:3072
	global_load_dwordx4 v[12:15], v32, s[6:7] offset:2048
	global_load_dwordx4 v[16:19], v[34:35], off nt
	global_load_dwordx4 v[20:23], v[34:35], off offset:1024 nt
	global_load_dwordx4 v[24:27], v[34:35], off offset:2048 nt
	global_load_dwordx4 v[28:31], v[34:35], off offset:3072 nt
	s_lshl_b64 s[6:7], s[10:11], 13
	s_add_u32 s4, s4, s6
	s_addc_u32 s5, s5, s7
	s_ashr_i32 s13, s12, 31
	s_lshl_b64 s[24:25], s[10:11], 12
	s_lshl_b64 s[6:7], s[12:13], 13
	v_lshl_add_u64 v[34:35], s[4:5], 0, v[32:33]
	s_add_u32 s4, s34, s24
	v_lshlrev_b32_e32 v32, 3, v184
	s_addc_u32 s5, s35, s25
	s_mov_b64 s[18:19], 0xb000000
	v_lshl_add_u64 v[32:33], s[4:5], 0, v[32:33]
	v_mov_b32_e32 v68, 0x358637bd
	s_mov_b32 s16, 0xf800000
	v_mov_b32_e32 v69, 0x260
	s_movk_i32 s17, 0x7fff
	v_mov_b32_e32 v70, 0x3a000000
	v_lshl_add_u64 v[62:63], v[34:35], 0, s[14:15]
	s_lshl_b64 s[14:15], s[12:13], 12
	v_lshl_add_u64 v[64:65], v[32:33], 0, s[18:19]
	v_mov_b32_e32 v71, 1
	s_waitcnt vmcnt(7)
	v_mov_b32_e32 v66, v1
	v_mov_b32_e32 v67, v3
	v_mov_b32_e32 v1, v2
	s_waitcnt vmcnt(6)
	v_mov_b32_e32 v2, v5
	v_mov_b32_e32 v3, v7
	v_mov_b32_e32 v5, v6
	s_waitcnt vmcnt(4)
	v_mov_b32_e32 v6, v13
	v_mov_b32_e32 v7, v15
	v_mov_b32_e32 v13, v14
	v_mov_b32_e32 v14, v9
	v_mov_b32_e32 v15, v11
	v_mov_b32_e32 v9, v10
	s_waitcnt vmcnt(3)
	v_mov_b32_e32 v10, v17
	v_mov_b32_e32 v11, v19
	v_mov_b32_e32 v17, v18
	s_waitcnt vmcnt(2)
	v_mov_b32_e32 v18, v21
	v_mov_b32_e32 v19, v23
	v_mov_b32_e32 v21, v22
	s_waitcnt vmcnt(1)
	v_mov_b32_e32 v22, v25
	v_mov_b32_e32 v23, v27
	v_mov_b32_e32 v25, v26
	s_waitcnt vmcnt(0)
	v_mov_b32_e32 v26, v29
	v_mov_b32_e32 v27, v31
	v_mov_b32_e32 v29, v30
; __device__ __forceinline__ unsigned pk2(float lo, float hi) { return f2bf(lo) | (f2bf(hi) << 16); }
; template <bool OUT_BF16>
; __device__ __forceinline__ void rmsnorm_rows(Frame& F, const float* X, const float* gain, void* O) {
;     ...
;     for (int m = gw; m < S; m += NGW) {
;         const f32x4* xr = (const f32x4*)(X + (size_t)m * DM) + F.lane;
;         f32x4 v[8]; float s = 0.f;
; #pragma unroll
;         for (int j = 0; j < 8; ++j) { v[j] = xr[64 * j]; s += (v[j].x * v[j].x + v[j].y * v[j].y) + (v[j].z * v[j].z + v[j].w * v[j].w); }
;         const float rs = 1.f / sqrtf(wave_sum(s) * (1.f / DM) + NORM_EPS);
;         if (OUT_BF16) {
;             u32x2* o8 = (u32x2*)((bf16_t*)O + (size_t)m * DM) + F.lane;
; #pragma unroll
;             for (int j = 0; j < 8; ++j) { u32x2 w; w.x = pk2(v[j].x * rs * gv[j].x, v[j].y * rs * gv[j].y); w.y = pk2(v[j].z * rs * gv[j].z, v[j].w * rs * gv[j].w); o8[64 * j] = w; }
.LBB0_31:
	global_load_dwordx4 v[30:33], v[62:63], off offset:-4096 nt
	global_load_dwordx4 v[34:37], v[62:63], off offset:-3072 nt
	global_load_dwordx4 v[38:41], v[62:63], off offset:-2048 nt
	global_load_dwordx4 v[42:45], v[62:63], off offset:-1024 nt
	global_load_dwordx4 v[46:49], v[62:63], off nt
	global_load_dwordx4 v[50:53], v[62:63], off offset:1024 nt
	global_load_dwordx4 v[54:57], v[62:63], off offset:2048 nt
	global_load_dwordx4 v[58:61], v[62:63], off offset:3072 nt
	v_mov_b32_e32 v88, 0
	v_mov_b32_e32 v89, 0
	s_add_i32 s10, s10, s12
	v_lshl_add_u64 v[62:63], v[62:63], 0, s[6:7]
	s_cmpk_lt_i32 s10, 0x4000
	s_waitcnt vmcnt(7)
	v_mul_f32_e32 v90, v31, v31
	v_mul_f32_e32 v91, v33, v33
	s_waitcnt vmcnt(6)
	v_mul_f32_e32 v92, v35, v35
	v_mul_f32_e32 v93, v37, v37
	s_waitcnt vmcnt(5)
	v_mul_f32_e32 v94, v39, v39
	v_mul_f32_e32 v95, v41, v41
	v_fmac_f32_e32 v90, v30, v30
	v_fmac_f32_e32 v91, v32, v32
	v_fmac_f32_e32 v92, v34, v34
	v_fmac_f32_e32 v93, v36, v36
	s_waitcnt vmcnt(4)
	v_mul_f32_e32 v96, v43, v43
	v_mul_f32_e32 v97, v45, v45
	v_mov_b32_e32 v72, v30
	v_mov_b32_e32 v73, v32
	v_fmac_f32_e32 v94, v38, v38
	v_fmac_f32_e32 v95, v40, v40
	v_mov_b32_e32 v32, v31
	v_add_f32_e32 v30, v90, v91
	v_add_f32_e32 v31, v92, v93
	s_waitcnt vmcnt(3)
	v_mul_f32_e32 v98, v47, v47
	v_mul_f32_e32 v99, v49, v49
	v_mov_b32_e32 v74, v34
	v_fmac_f32_e32 v96, v42, v42
	v_fmac_f32_e32 v97, v44, v44
	v_add_f32_e32 v34, v94, v95
	v_add_f32_e32 v30, v30, v31
	s_waitcnt vmcnt(2)
	v_mul_f32_e32 v100, v51, v51
	v_mul_f32_e32 v101, v53, v53
	v_mov_b32_e32 v75, v36
	v_fmac_f32_e32 v98, v46, v46
	v_fmac_f32_e32 v99, v48, v48
	v_mov_b32_e32 v36, v35
	v_add_f32_e32 v35, v96, v97
	v_add_f32_e32 v30, v30, v34
	s_waitcnt vmcnt(1)
	v_mul_f32_e32 v102, v55, v55
	v_mul_f32_e32 v103, v57, v57
	v_mov_b32_e32 v76, v38
	v_fmac_f32_e32 v100, v50, v50
	v_fmac_f32_e32 v101, v52, v52
	v_add_f32_e32 v38, v98, v99
	v_add_f32_e32 v30, v30, v35
	s_waitcnt vmcnt(0)
	v_mul_f32_e32 v104, v59, v59
	v_mul_f32_e32 v105, v61, v61
	v_mov_b32_e32 v77, v40
	v_fmac_f32_e32 v102, v54, v54
	v_fmac_f32_e32 v103, v56, v56
	v_mov_b32_e32 v40, v39
	v_add_f32_e32 v39, v100, v101
	v_add_f32_e32 v30, v30, v38
	v_mov_b32_e32 v78, v42
	v_fmac_f32_e32 v104, v58, v58
	v_fmac_f32_e32 v105, v60, v60
	v_add_f32_e32 v42, v102, v103
	v_add_f32_e32 v30, v30, v39
	v_mov_b32_e32 v79, v44
	v_mov_b32_e32 v44, v43
	v_add_f32_e32 v43, v104, v105
	v_add_f32_e32 v30, v30, v42
	v_add_f32_e32 v30, v30, v43
	v_mov_b32_e32 v80, v46
	v_mov_b32_e32 v81, v48
	v_add_f32_dpp v30, v30, v30 quad_perm:[1,0,3,2] row_mask:0xf bank_mask:0xf bound_ctrl:1
	v_mov_b32_e32 v82, v50
	v_mov_b32_e32 v83, v52
	v_add_f32_dpp v30, v30, v30 quad_perm:[2,3,0,1] row_mask:0xf bank_mask:0xf bound_ctrl:1
	v_mov_b32_e32 v84, v54
	v_mov_b32_e32 v85, v56
	v_add_f32_dpp v30, v30, v30 row_half_mirror row_mask:0xf bank_mask:0xf bound_ctrl:1
	v_mov_b32_e32 v86, v58
	v_mov_b32_e32 v87, v60
	v_add_f32_dpp v30, v30, v30 row_mirror row_mask:0xf bank_mask:0xf bound_ctrl:1
	v_mov_b32_e32 v48, v47
	v_mov_b32_e32 v52, v51
	v_mov_b32_dpp v88, v30 row_bcast:15 row_mask:0xa bank_mask:0xf
	v_add_f32_e32 v30, v30, v88
	v_mov_b32_e32 v56, v55
	v_mov_b32_e32 v60, v59
	v_mov_b32_dpp v89, v30 row_bcast:31 row_mask:0xc bank_mask:0xf
	v_add_f32_e32 v30, v30, v89
	s_nop 0
	v_readlane_b32 s4, v30, 63
	s_nop 1
	v_fma_f32 v30, s4, v70, v68
	v_mul_f32_e32 v31, 0x4f800000, v30
	v_cmp_gt_f32_e32 vcc, s16, v30
	s_nop 1
	v_cndmask_b32_e32 v30, v30, v31, vcc
	v_sqrt_f32_e32 v31, v30
	s_nop 0
	v_add_u32_e32 v34, -1, v31
	v_add_u32_e32 v35, 1, v31
	v_fma_f32 v38, -v34, v31, v30
	v_fma_f32 v39, -v35, v31, v30
	v_cmp_ge_f32_e64 s[4:5], 0, v38
	s_nop 1
	v_cndmask_b32_e64 v31, v31, v34, s[4:5]
	v_cmp_lt_f32_e64 s[4:5], 0, v39
	s_nop 1
	v_cndmask_b32_e64 v31, v31, v35, s[4:5]
	v_mul_f32_e32 v34, 0x37800000, v31
	v_cndmask_b32_e32 v31, v31, v34, vcc
	v_cmp_class_f32_e32 vcc, v30, v69
	s_nop 1
	v_cndmask_b32_e32 v30, v31, v30, vcc
	v_div_scale_f32 v31, s[4:5], v30, v30, 1.0
	v_rcp_f32_e32 v35, v31
	v_div_scale_f32 v34, vcc, 1.0, v30, 1.0
	v_fma_f32 v38, -v31, v35, 1.0
	v_fmac_f32_e32 v35, v38, v35
	v_mul_f32_e32 v38, v34, v35
	v_fma_f32 v39, -v31, v38, v34
	v_fmac_f32_e32 v38, v39, v35
	v_fma_f32 v31, -v31, v38, v34
	v_div_fmas_f32 v31, v31, v35, v38
	v_div_fixup_f32 v30, v31, v30, 1.0
	v_pk_mul_f32 v[32:33], v[32:33], v[30:31] op_sel_hi:[1,0]
	v_pk_mul_f32 v[34:35], v[72:73], v[30:31] op_sel_hi:[1,0]
	v_pk_mul_f32 v[38:39], v[74:75], v[30:31] op_sel_hi:[1,0]
	v_pk_mul_f32 v[36:37], v[36:37], v[30:31] op_sel_hi:[1,0]
	v_pk_mul_f32 v[42:43], v[76:77], v[30:31] op_sel_hi:[1,0]
	v_pk_mul_f32 v[40:41], v[40:41], v[30:31] op_sel_hi:[1,0]
	v_pk_mul_f32 v[46:47], v[78:79], v[30:31] op_sel_hi:[1,0]
	v_pk_mul_f32 v[44:45], v[44:45], v[30:31] op_sel_hi:[1,0]
	v_pk_mul_f32 v[50:51], v[80:81], v[30:31] op_sel_hi:[1,0]
	v_pk_mul_f32 v[48:49], v[48:49], v[30:31] op_sel_hi:[1,0]
	v_pk_mul_f32 v[54:55], v[82:83], v[30:31] op_sel_hi:[1,0]
	v_pk_mul_f32 v[52:53], v[52:53], v[30:31] op_sel_hi:[1,0]
	v_pk_mul_f32 v[58:59], v[84:85], v[30:31] op_sel_hi:[1,0]
	v_pk_mul_f32 v[56:57], v[56:57], v[30:31] op_sel_hi:[1,0]
	v_pk_mul_f32 v[72:73], v[86:87], v[30:31] op_sel_hi:[1,0]
	v_pk_mul_f32 v[30:31], v[60:61], v[30:31] op_sel_hi:[1,0]
	v_pk_mul_f32 v[32:33], v[66:67], v[32:33]
	v_pk_mul_f32 v[34:35], v[0:1], v[34:35]
	v_pk_mul_f32 v[36:37], v[2:3], v[36:37]
	v_pk_mul_f32 v[40:41], v[6:7], v[40:41]
	v_pk_mul_f32 v[44:45], v[14:15], v[44:45]
	v_pk_mul_f32 v[48:49], v[10:11], v[48:49]
	v_pk_mul_f32 v[52:53], v[18:19], v[52:53]
	v_pk_mul_f32 v[56:57], v[22:23], v[56:57]
	v_pk_mul_f32 v[30:31], v[26:27], v[30:31]
; __device__ __forceinline__ unsigned pk2(float lo, float hi) { return f2bf(lo) | (f2bf(hi) << 16); }
; template <bool OUT_BF16>
; __device__ __forceinline__ void rmsnorm_rows(Frame& F, const float* X, const float* gain, void* O) {
;     ...
;             u32x2* o8 = (u32x2*)((bf16_t*)O + (size_t)m * DM) + F.lane;
; #pragma unroll
;             for (int j = 0; j < 8; ++j) { u32x2 w; w.x = pk2(v[j].x * rs * gv[j].x, v[j].y * rs * gv[j].y); w.y = pk2(v[j].z * rs * gv[j].z, v[j].w * rs * gv[j].w); o8[64 * j] = w; }
	v_and_b32_sdwa v74, v33, v71 dst_sel:DWORD dst_unused:UNUSED_PAD src0_sel:WORD_1 src1_sel:DWORD
	v_and_b32_sdwa v75, v32, v71 dst_sel:DWORD dst_unused:UNUSED_PAD src0_sel:WORD_1 src1_sel:DWORD
	v_pk_mul_f32 v[38:39], v[4:5], v[38:39]
	v_pk_mul_f32 v[42:43], v[12:13], v[42:43]
	v_pk_mul_f32 v[46:47], v[8:9], v[46:47]
	v_pk_mul_f32 v[50:51], v[16:17], v[50:51]
	v_pk_mul_f32 v[54:55], v[20:21], v[54:55]
	v_pk_mul_f32 v[58:59], v[24:25], v[58:59]
	v_pk_mul_f32 v[60:61], v[28:29], v[72:73]
	v_and_b32_sdwa v72, v35, v71 dst_sel:DWORD dst_unused:UNUSED_PAD src0_sel:WORD_1 src1_sel:DWORD
	v_and_b32_sdwa v73, v34, v71 dst_sel:DWORD dst_unused:UNUSED_PAD src0_sel:WORD_1 src1_sel:DWORD
	v_and_b32_sdwa v78, v37, v71 dst_sel:DWORD dst_unused:UNUSED_PAD src0_sel:WORD_1 src1_sel:DWORD
	v_and_b32_sdwa v79, v36, v71 dst_sel:DWORD dst_unused:UNUSED_PAD src0_sel:WORD_1 src1_sel:DWORD
	v_and_b32_sdwa v82, v41, v71 dst_sel:DWORD dst_unused:UNUSED_PAD src0_sel:WORD_1 src1_sel:DWORD
	v_and_b32_sdwa v83, v40, v71 dst_sel:DWORD dst_unused:UNUSED_PAD src0_sel:WORD_1 src1_sel:DWORD
	v_and_b32_sdwa v86, v45, v71 dst_sel:DWORD dst_unused:UNUSED_PAD src0_sel:WORD_1 src1_sel:DWORD
	v_and_b32_sdwa v87, v44, v71 dst_sel:DWORD dst_unused:UNUSED_PAD src0_sel:WORD_1 src1_sel:DWORD
	v_and_b32_sdwa v90, v49, v71 dst_sel:DWORD dst_unused:UNUSED_PAD src0_sel:WORD_1 src1_sel:DWORD
	v_and_b32_sdwa v91, v48, v71 dst_sel:DWORD dst_unused:UNUSED_PAD src0_sel:WORD_1 src1_sel:DWORD
	v_and_b32_sdwa v94, v53, v71 dst_sel:DWORD dst_unused:UNUSED_PAD src0_sel:WORD_1 src1_sel:DWORD
	v_and_b32_sdwa v95, v52, v71 dst_sel:DWORD dst_unused:UNUSED_PAD src0_sel:WORD_1 src1_sel:DWORD
	v_and_b32_sdwa v98, v57, v71 dst_sel:DWORD dst_unused:UNUSED_PAD src0_sel:WORD_1 src1_sel:DWORD
	v_and_b32_sdwa v99, v56, v71 dst_sel:DWORD dst_unused:UNUSED_PAD src0_sel:WORD_1 src1_sel:DWORD
	v_and_b32_sdwa v102, v31, v71 dst_sel:DWORD dst_unused:UNUSED_PAD src0_sel:WORD_1 src1_sel:DWORD
	v_and_b32_sdwa v103, v30, v71 dst_sel:DWORD dst_unused:UNUSED_PAD src0_sel:WORD_1 src1_sel:DWORD
	v_add3_u32 v33, v33, v74, s17
	v_add3_u32 v32, v32, v75, s17
	v_and_b32_sdwa v76, v39, v71 dst_sel:DWORD dst_unused:UNUSED_PAD src0_sel:WORD_1 src1_sel:DWORD
	v_and_b32_sdwa v77, v38, v71 dst_sel:DWORD dst_unused:UNUSED_PAD src0_sel:WORD_1 src1_sel:DWORD
	v_and_b32_sdwa v80, v43, v71 dst_sel:DWORD dst_unused:UNUSED_PAD src0_sel:WORD_1 src1_sel:DWORD
	v_and_b32_sdwa v81, v42, v71 dst_sel:DWORD dst_unused:UNUSED_PAD src0_sel:WORD_1 src1_sel:DWORD
	v_and_b32_sdwa v84, v47, v71 dst_sel:DWORD dst_unused:UNUSED_PAD src0_sel:WORD_1 src1_sel:DWORD
	v_and_b32_sdwa v85, v46, v71 dst_sel:DWORD dst_unused:UNUSED_PAD src0_sel:WORD_1 src1_sel:DWORD
	v_and_b32_sdwa v88, v51, v71 dst_sel:DWORD dst_unused:UNUSED_PAD src0_sel:WORD_1 src1_sel:DWORD
	v_and_b32_sdwa v89, v50, v71 dst_sel:DWORD dst_unused:UNUSED_PAD src0_sel:WORD_1 src1_sel:DWORD
	v_and_b32_sdwa v92, v55, v71 dst_sel:DWORD dst_unused:UNUSED_PAD src0_sel:WORD_1 src1_sel:DWORD
	v_and_b32_sdwa v93, v54, v71 dst_sel:DWORD dst_unused:UNUSED_PAD src0_sel:WORD_1 src1_sel:DWORD
	v_and_b32_sdwa v96, v59, v71 dst_sel:DWORD dst_unused:UNUSED_PAD src0_sel:WORD_1 src1_sel:DWORD
	v_and_b32_sdwa v97, v58, v71 dst_sel:DWORD dst_unused:UNUSED_PAD src0_sel:WORD_1 src1_sel:DWORD
	v_and_b32_sdwa v100, v61, v71 dst_sel:DWORD dst_unused:UNUSED_PAD src0_sel:WORD_1 src1_sel:DWORD
	v_and_b32_sdwa v101, v60, v71 dst_sel:DWORD dst_unused:UNUSED_PAD src0_sel:WORD_1 src1_sel:DWORD
	v_add3_u32 v34, v34, v73, s17
	v_add3_u32 v35, v35, v72, s17
	v_add3_u32 v37, v37, v78, s17
	v_add3_u32 v36, v36, v79, s17
	v_add3_u32 v41, v41, v82, s17
	v_add3_u32 v40, v40, v83, s17
	v_add3_u32 v45, v45, v86, s17
	v_add3_u32 v44, v44, v87, s17
	v_add3_u32 v49, v49, v90, s17
	v_add3_u32 v48, v48, v91, s17
	v_add3_u32 v53, v53, v94, s17
	v_add3_u32 v52, v52, v95, s17
	v_add3_u32 v57, v57, v98, s17
	v_add3_u32 v56, v56, v99, s17
	v_add3_u32 v31, v31, v102, s17
	v_add3_u32 v30, v30, v103, s17
	v_and_b32_e32 v33, 0xffff0000, v33
	v_and_b32_e32 v32, 0xffff0000, v32
	v_add3_u32 v38, v38, v77, s17
	v_add3_u32 v39, v39, v76, s17
	v_add3_u32 v42, v42, v81, s17
	v_add3_u32 v43, v43, v80, s17
	v_add3_u32 v46, v46, v85, s17
	v_add3_u32 v47, v47, v84, s17
	v_add3_u32 v50, v50, v89, s17
	v_add3_u32 v51, v51, v88, s17
	v_add3_u32 v54, v54, v93, s17
	v_add3_u32 v55, v55, v92, s17
	v_add3_u32 v58, v58, v97, s17
	v_add3_u32 v59, v59, v96, s17
	v_add3_u32 v60, v60, v101, s17
	v_add3_u32 v61, v61, v100, s17
	v_and_b32_e32 v37, 0xffff0000, v37
	v_and_b32_e32 v36, 0xffff0000, v36
	v_and_b32_e32 v41, 0xffff0000, v41
	v_and_b32_e32 v40, 0xffff0000, v40
	v_and_b32_e32 v45, 0xffff0000, v45
	v_and_b32_e32 v44, 0xffff0000, v44
	v_and_b32_e32 v49, 0xffff0000, v49
	v_and_b32_e32 v48, 0xffff0000, v48
	v_and_b32_e32 v53, 0xffff0000, v53
	v_and_b32_e32 v52, 0xffff0000, v52
	v_and_b32_e32 v57, 0xffff0000, v57
	v_and_b32_e32 v56, 0xffff0000, v56
	v_and_b32_e32 v72, 0xffff0000, v31
	v_and_b32_e32 v73, 0xffff0000, v30
	v_or_b32_sdwa v31, v33, v35 dst_sel:DWORD dst_unused:UNUSED_PAD src0_sel:DWORD src1_sel:WORD_1
	v_or_b32_sdwa v30, v32, v34 dst_sel:DWORD dst_unused:UNUSED_PAD src0_sel:DWORD src1_sel:WORD_1
	v_or_b32_sdwa v33, v37, v39 dst_sel:DWORD dst_unused:UNUSED_PAD src0_sel:DWORD src1_sel:WORD_1
	v_or_b32_sdwa v32, v36, v38 dst_sel:DWORD dst_unused:UNUSED_PAD src0_sel:DWORD src1_sel:WORD_1
	v_or_b32_sdwa v35, v41, v43 dst_sel:DWORD dst_unused:UNUSED_PAD src0_sel:DWORD src1_sel:WORD_1
	v_or_b32_sdwa v34, v40, v42 dst_sel:DWORD dst_unused:UNUSED_PAD src0_sel:DWORD src1_sel:WORD_1
	v_or_b32_sdwa v37, v45, v47 dst_sel:DWORD dst_unused:UNUSED_PAD src0_sel:DWORD src1_sel:WORD_1
	v_or_b32_sdwa v36, v44, v46 dst_sel:DWORD dst_unused:UNUSED_PAD src0_sel:DWORD src1_sel:WORD_1
	v_or_b32_sdwa v39, v49, v51 dst_sel:DWORD dst_unused:UNUSED_PAD src0_sel:DWORD src1_sel:WORD_1
	v_or_b32_sdwa v38, v48, v50 dst_sel:DWORD dst_unused:UNUSED_PAD src0_sel:DWORD src1_sel:WORD_1
	v_or_b32_sdwa v41, v53, v55 dst_sel:DWORD dst_unused:UNUSED_PAD src0_sel:DWORD src1_sel:WORD_1
	v_or_b32_sdwa v40, v52, v54 dst_sel:DWORD dst_unused:UNUSED_PAD src0_sel:DWORD src1_sel:WORD_1
	v_or_b32_sdwa v43, v57, v59 dst_sel:DWORD dst_unused:UNUSED_PAD src0_sel:DWORD src1_sel:WORD_1
	v_or_b32_sdwa v42, v56, v58 dst_sel:DWORD dst_unused:UNUSED_PAD src0_sel:DWORD src1_sel:WORD_1
	v_or_b32_sdwa v45, v72, v61 dst_sel:DWORD dst_unused:UNUSED_PAD src0_sel:DWORD src1_sel:WORD_1
	v_or_b32_sdwa v44, v73, v60 dst_sel:DWORD dst_unused:UNUSED_PAD src0_sel:DWORD src1_sel:WORD_1
	global_store_dwordx2 v[64:65], v[30:31], off
	global_store_dwordx2 v[64:65], v[32:33], off offset:512
	global_store_dwordx2 v[64:65], v[34:35], off offset:1024
	global_store_dwordx2 v[64:65], v[36:37], off offset:1536
	global_store_dwordx2 v[64:65], v[38:39], off offset:2048
	global_store_dwordx2 v[64:65], v[40:41], off offset:2560
	global_store_dwordx2 v[64:65], v[42:43], off offset:3072
	global_store_dwordx2 v[64:65], v[44:45], off offset:3584
	v_lshl_add_u64 v[64:65], v[64:65], 0, s[14:15]
	s_cbranch_scc1 .LBB0_31

; template <int MODE>
; __device__ __forceinline__ void transpose_item(const float* W, const float* W2, int K, int Nsrc, int Ndst, bf16_t* WT, LAS float* scr, int item, int lane) {
;     const int nblk = Ndst / 64, kb = item / nblk, nb = item % nblk, k0 = 64 * kb, n0 = 64 * nb;
;     const int c4 = lane & 15, r4 = lane >> 4;
;     const float* src; bool ok = true; int lcol;
;     if (MODE == 0) { src = W + n0 + 4 * c4; ok = (n0 + 4 * c4) < Nsrc; lcol = 4 * c4; }
;     else if (MODE == 2) {
;         const int n = n0 + 4 * c4; int sc = -1; if (n < 3264) sc = 2120 + n; else if (n >= 3328 && n < 3328 + 2120) sc = n - 3328;
;         ok = sc >= 0; src = W + (ok ? sc : 0); lcol = 4 * c4; }
;     else if (MODE == 3) { const int n = n0 + 4 * c4; ok = n < 2120; src = W + (ok ? n : 0); lcol = 4 * c4; }
;     else { const int t = c4 >> 3, g = c4 & 7; src = (t ? W2 : W) + n0 / 2 + 4 * g; lcol = 8 * g + 4 * t; }
;     f32x4 v[16];
; #pragma unroll
;     for (int i = 0; i < 16; ++i) v[i] = ok ? *(const f32x4*)(src + (size_t)(k0 + 4 * i + r4) * Nsrc) : (f32x4){0.f, 0.f, 0.f, 0.f};
.LBB0_244:
	s_mul_hi_i32 s12, s25, 0x4ec4ec4f
	s_lshr_b32 s13, s12, 31
	s_ashr_i32 s12, s12, 4
	s_add_i32 s13, s12, s13
	s_mul_i32 s26, s13, 0xfffff300
	s_add_i32 s26, s26, s11
	v_add_u32_e32 v0, s26, v71
	v_add_u32_e32 v1, 0x848, v0
	v_cmp_gt_i32_e32 vcc, s17, v0
	s_lshl_b32 s12, s13, 6
	v_mov_b32_e32 v2, 0
	v_cndmask_b32_e32 v0, -1, v1, vcc
	v_cmp_lt_i32_e32 vcc, -1, v0
	v_mov_b32_e32 v1, 0
	v_mov_b32_e32 v3, 0
	v_cndmask_b32_e32 v64, 0, v0, vcc
	s_waitcnt lgkmcnt(0)
	v_lshl_add_u64 v[68:69], v[64:65], 2, s[4:5]
	v_or_b32_e32 v64, s12, v70
	v_mov_b32_e32 v0, 0
	s_and_saveexec_b64 s[14:15], vcc
	s_cbranch_execz .LBB0_246
	v_mad_i64_i32 v[0:1], s[28:29], v64, s18, v[68:69]
	global_load_dwordx4 v[0:3], v[0:1], off nt
.LBB0_246:
	s_or_b64 exec, exec, s[14:15]
	v_mov_b32_e32 v4, 0
	v_mov_b32_e32 v8, 0
	v_mov_b32_e32 v9, 0
	v_mov_b32_e32 v10, 0
	v_mov_b32_e32 v11, 0
	s_and_saveexec_b64 s[14:15], vcc
	s_cbranch_execz .LBB0_248
	v_or_b32_e32 v5, 4, v64
	v_mad_i64_i32 v[6:7], s[28:29], v5, s18, v[68:69]
	global_load_dwordx4 v[8:11], v[6:7], off nt
.LBB0_248:
	s_or_b64 exec, exec, s[14:15]
	v_mov_b32_e32 v5, 0
	v_mov_b32_e32 v6, 0
	v_mov_b32_e32 v7, 0
	s_and_saveexec_b64 s[14:15], vcc
	s_cbranch_execz .LBB0_250
	v_or_b32_e32 v4, 8, v64
	v_mad_i64_i32 v[4:5], s[28:29], v4, s18, v[68:69]
	global_load_dwordx4 v[4:7], v[4:5], off nt
.LBB0_250:
	s_or_b64 exec, exec, s[14:15]
	v_mov_b32_e32 v12, 0
	v_mov_b32_e32 v16, 0
	v_mov_b32_e32 v17, 0
	v_mov_b32_e32 v18, 0
	v_mov_b32_e32 v19, 0
	s_and_saveexec_b64 s[14:15], vcc
	s_cbranch_execz .LBB0_252
	v_or_b32_e32 v13, 12, v64
	v_mad_i64_i32 v[14:15], s[28:29], v13, s18, v[68:69]
	global_load_dwordx4 v[16:19], v[14:15], off nt
.LBB0_252:
	s_or_b64 exec, exec, s[14:15]
	v_mov_b32_e32 v13, 0
	v_mov_b32_e32 v14, 0
	v_mov_b32_e32 v15, 0
	s_and_saveexec_b64 s[14:15], vcc
	s_cbranch_execz .LBB0_254
	v_or_b32_e32 v12, 16, v64
	v_mad_i64_i32 v[12:13], s[28:29], v12, s18, v[68:69]
	global_load_dwordx4 v[12:15], v[12:13], off nt
.LBB0_254:
	s_or_b64 exec, exec, s[14:15]
	v_mov_b32_e32 v20, 0
	v_mov_b32_e32 v24, 0
	v_mov_b32_e32 v25, 0
	v_mov_b32_e32 v26, 0
	v_mov_b32_e32 v27, 0
	s_and_saveexec_b64 s[14:15], vcc
	s_cbranch_execz .LBB0_256
	v_or_b32_e32 v21, 20, v64
	v_mad_i64_i32 v[22:23], s[28:29], v21, s18, v[68:69]
	global_load_dwordx4 v[24:27], v[22:23], off nt
.LBB0_256:
	s_or_b64 exec, exec, s[14:15]
	v_mov_b32_e32 v21, 0
	v_mov_b32_e32 v22, 0
	v_mov_b32_e32 v23, 0
	s_and_saveexec_b64 s[14:15], vcc
	s_cbranch_execz .LBB0_258
	v_or_b32_e32 v20, 24, v64
	v_mad_i64_i32 v[20:21], s[28:29], v20, s18, v[68:69]
	global_load_dwordx4 v[20:23], v[20:21], off nt
.LBB0_258:
	s_or_b64 exec, exec, s[14:15]
	v_mov_b32_e32 v28, 0
	v_mov_b32_e32 v32, 0
	v_mov_b32_e32 v33, 0
	v_mov_b32_e32 v34, 0
	v_mov_b32_e32 v35, 0
	s_and_saveexec_b64 s[14:15], vcc
	s_cbranch_execz .LBB0_260
	v_or_b32_e32 v29, 28, v64
	v_mad_i64_i32 v[30:31], s[28:29], v29, s18, v[68:69]
	global_load_dwordx4 v[32:35], v[30:31], off nt
.LBB0_260:
	s_or_b64 exec, exec, s[14:15]
	v_mov_b32_e32 v29, 0
	v_mov_b32_e32 v30, 0
	v_mov_b32_e32 v31, 0
	s_and_saveexec_b64 s[14:15], vcc
	s_cbranch_execz .LBB0_262
	v_or_b32_e32 v28, 32, v64
	v_mad_i64_i32 v[28:29], s[28:29], v28, s18, v[68:69]
	global_load_dwordx4 v[28:31], v[28:29], off nt
.LBB0_262:
	s_or_b64 exec, exec, s[14:15]
	v_mov_b32_e32 v36, 0
	v_mov_b32_e32 v40, 0
	v_mov_b32_e32 v41, 0
	v_mov_b32_e32 v42, 0
	v_mov_b32_e32 v43, 0
	s_and_saveexec_b64 s[14:15], vcc
	s_cbranch_execz .LBB0_264
	v_or_b32_e32 v37, 36, v64
	v_mad_i64_i32 v[38:39], s[28:29], v37, s18, v[68:69]
	global_load_dwordx4 v[40:43], v[38:39], off nt
.LBB0_264:
	s_or_b64 exec, exec, s[14:15]
	v_mov_b32_e32 v37, 0
	v_mov_b32_e32 v38, 0
	v_mov_b32_e32 v39, 0
	s_and_saveexec_b64 s[14:15], vcc
	s_cbranch_execz .LBB0_266
	v_or_b32_e32 v36, 40, v64
	v_mad_i64_i32 v[36:37], s[28:29], v36, s18, v[68:69]
	global_load_dwordx4 v[36:39], v[36:37], off nt
.LBB0_266:
	s_or_b64 exec, exec, s[14:15]
	v_mov_b32_e32 v44, 0
	v_mov_b32_e32 v48, 0
	v_mov_b32_e32 v49, 0
	v_mov_b32_e32 v50, 0
	v_mov_b32_e32 v51, 0
	s_and_saveexec_b64 s[14:15], vcc
	s_cbranch_execz .LBB0_268
	v_or_b32_e32 v45, 44, v64
	v_mad_i64_i32 v[46:47], s[28:29], v45, s18, v[68:69]
	global_load_dwordx4 v[48:51], v[46:47], off nt
.LBB0_268:
	s_or_b64 exec, exec, s[14:15]
	v_mov_b32_e32 v45, 0
	v_mov_b32_e32 v46, 0
	v_mov_b32_e32 v47, 0
	s_and_saveexec_b64 s[14:15], vcc
	s_cbranch_execz .LBB0_270
	v_or_b32_e32 v44, 48, v64
	v_mad_i64_i32 v[44:45], s[28:29], v44, s18, v[68:69]
	global_load_dwordx4 v[44:47], v[44:45], off nt
.LBB0_270:
	s_or_b64 exec, exec, s[14:15]
	v_mov_b32_e32 v52, 0
	v_mov_b32_e32 v56, 0
	v_mov_b32_e32 v57, 0
	v_mov_b32_e32 v58, 0
	v_mov_b32_e32 v59, 0
	s_and_saveexec_b64 s[14:15], vcc
	s_cbranch_execz .LBB0_272
	v_or_b32_e32 v53, 52, v64
	v_mad_i64_i32 v[54:55], s[28:29], v53, s18, v[68:69]
	global_load_dwordx4 v[56:59], v[54:55], off nt
.LBB0_272:
	s_or_b64 exec, exec, s[14:15]
	v_mov_b32_e32 v53, 0
	v_mov_b32_e32 v54, 0
	v_mov_b32_e32 v55, 0
	s_and_saveexec_b64 s[14:15], vcc
	s_cbranch_execz .LBB0_274
	v_or_b32_e32 v52, 56, v64
	v_mad_i64_i32 v[52:53], s[28:29], v52, s18, v[68:69]
	global_load_dwordx4 v[52:55], v[52:53], off nt
.LBB0_274:
	s_or_b64 exec, exec, s[14:15]
	v_mov_b32_e32 v60, 0
	v_mov_b32_e32 v61, 0
	v_mov_b32_e32 v62, 0
	v_mov_b32_e32 v63, 0
	s_and_saveexec_b64 s[14:15], vcc
	s_cbranch_execz .LBB0_243
	v_or_b32_e32 v60, 60, v64
	v_mad_i64_i32 v[60:61], s[28:29], v60, s18, v[68:69]
	global_load_dwordx4 v[60:63], v[60:61], off nt
	s_branch .LBB0_243

; template <int MODE>
; __device__ __forceinline__ void transpose_item(const float* W, const float* W2, int K, int Nsrc, int Ndst, bf16_t* WT, LAS float* scr, int item, int lane) {
;     const int nblk = Ndst / 64, kb = item / nblk, nb = item % nblk, k0 = 64 * kb, n0 = 64 * nb;
;     const int c4 = lane & 15, r4 = lane >> 4;
;     const float* src; bool ok = true; int lcol;
;     if (MODE == 0) { src = W + n0 + 4 * c4; ok = (n0 + 4 * c4) < Nsrc; lcol = 4 * c4; }
;     else if (MODE == 2) {
;         const int n = n0 + 4 * c4; int sc = -1; if (n < 3264) sc = 2120 + n; else if (n >= 3328 && n < 3328 + 2120) sc = n - 3328;
;         ok = sc >= 0; src = W + (ok ? sc : 0); lcol = 4 * c4; }
;     else if (MODE == 3) { const int n = n0 + 4 * c4; ok = n < 2120; src = W + (ok ? n : 0); lcol = 4 * c4; }
;     else { const int t = c4 >> 3, g = c4 & 7; src = (t ? W2 : W) + n0 / 2 + 4 * g; lcol = 8 * g + 4 * t; }
;     f32x4 v[16];
; #pragma unroll
;     for (int i = 0; i < 16; ++i) v[i] = ok ? *(const f32x4*)(src + (size_t)(k0 + 4 * i + r4) * Nsrc) : (f32x4){0.f, 0.f, 0.f, 0.f};
.LBB0_279:
	s_mul_hi_i32 s12, s25, 0x38e38e39
	s_lshr_b32 s13, s12, 31
	s_ashr_i32 s12, s12, 3
	s_add_i32 s13, s12, s13
	s_mul_i32 s26, s13, 0xfffff700
	s_add_i32 s26, s26, s11
	v_add_u32_e32 v0, s26, v69
	v_cmp_gt_i32_e32 vcc, s17, v0
	s_lshl_b32 s12, s13, 6
	v_or_b32_e32 v73, s12, v68
	v_cndmask_b32_e32 v0, 0, v0, vcc
	v_ashrrev_i32_e32 v1, 31, v0
	s_waitcnt lgkmcnt(0)
	v_lshl_add_u64 v[66:67], v[0:1], 2, s[4:5]
	v_mov_b32_e32 v0, 0
	v_mov_b32_e32 v1, 0
	v_mov_b32_e32 v2, 0
	v_mov_b32_e32 v3, 0
	s_and_saveexec_b64 s[14:15], vcc
	s_cbranch_execz .LBB0_281
	v_mad_i64_i32 v[0:1], s[28:29], v73, s18, v[66:67]
	global_load_dwordx4 v[0:3], v[0:1], off nt
.LBB0_281:
	s_or_b64 exec, exec, s[14:15]
	v_mov_b32_e32 v4, 0
	v_mov_b32_e32 v8, 0
	v_mov_b32_e32 v9, 0
	v_mov_b32_e32 v10, 0
	v_mov_b32_e32 v11, 0
	s_and_saveexec_b64 s[14:15], vcc
	s_cbranch_execz .LBB0_283
	v_or_b32_e32 v5, 4, v73
	v_mad_i64_i32 v[6:7], s[28:29], v5, s18, v[66:67]
	global_load_dwordx4 v[8:11], v[6:7], off nt
.LBB0_283:
	s_or_b64 exec, exec, s[14:15]
	v_mov_b32_e32 v5, 0
	v_mov_b32_e32 v6, 0
	v_mov_b32_e32 v7, 0
	s_and_saveexec_b64 s[14:15], vcc
	s_cbranch_execz .LBB0_285
	v_or_b32_e32 v4, 8, v73
	v_mad_i64_i32 v[4:5], s[28:29], v4, s18, v[66:67]
	global_load_dwordx4 v[4:7], v[4:5], off nt
.LBB0_285:
	s_or_b64 exec, exec, s[14:15]
	v_mov_b32_e32 v12, 0
	v_mov_b32_e32 v16, 0
	v_mov_b32_e32 v17, 0
	v_mov_b32_e32 v18, 0
	v_mov_b32_e32 v19, 0
	s_and_saveexec_b64 s[14:15], vcc
	s_cbranch_execz .LBB0_287
	v_or_b32_e32 v13, 12, v73
	v_mad_i64_i32 v[14:15], s[28:29], v13, s18, v[66:67]
	global_load_dwordx4 v[16:19], v[14:15], off nt
.LBB0_287:
	s_or_b64 exec, exec, s[14:15]
	v_mov_b32_e32 v13, 0
	v_mov_b32_e32 v14, 0
	v_mov_b32_e32 v15, 0
	s_and_saveexec_b64 s[14:15], vcc
	s_cbranch_execz .LBB0_289
	v_or_b32_e32 v12, 16, v73
	v_mad_i64_i32 v[12:13], s[28:29], v12, s18, v[66:67]
	global_load_dwordx4 v[12:15], v[12:13], off nt
.LBB0_289:
	s_or_b64 exec, exec, s[14:15]
	v_mov_b32_e32 v20, 0
	v_mov_b32_e32 v24, 0
	v_mov_b32_e32 v25, 0
	v_mov_b32_e32 v26, 0
	v_mov_b32_e32 v27, 0
	s_and_saveexec_b64 s[14:15], vcc
	s_cbranch_execz .LBB0_291
	v_or_b32_e32 v21, 20, v73
	v_mad_i64_i32 v[22:23], s[28:29], v21, s18, v[66:67]
	global_load_dwordx4 v[24:27], v[22:23], off nt
.LBB0_291:
	s_or_b64 exec, exec, s[14:15]
	v_mov_b32_e32 v21, 0
	v_mov_b32_e32 v22, 0
	v_mov_b32_e32 v23, 0
	s_and_saveexec_b64 s[14:15], vcc
	s_cbranch_execz .LBB0_293
	v_or_b32_e32 v20, 24, v73
	v_mad_i64_i32 v[20:21], s[28:29], v20, s18, v[66:67]
	global_load_dwordx4 v[20:23], v[20:21], off nt
.LBB0_293:
	s_or_b64 exec, exec, s[14:15]
	v_mov_b32_e32 v28, 0
	v_mov_b32_e32 v32, 0
	v_mov_b32_e32 v33, 0
	v_mov_b32_e32 v34, 0
	v_mov_b32_e32 v35, 0
	s_and_saveexec_b64 s[14:15], vcc
	s_cbranch_execz .LBB0_295
	v_or_b32_e32 v29, 28, v73
	v_mad_i64_i32 v[30:31], s[28:29], v29, s18, v[66:67]
	global_load_dwordx4 v[32:35], v[30:31], off nt
.LBB0_295:
	s_or_b64 exec, exec, s[14:15]
	v_mov_b32_e32 v29, 0
	v_mov_b32_e32 v30, 0
	v_mov_b32_e32 v31, 0
	s_and_saveexec_b64 s[14:15], vcc
	s_cbranch_execz .LBB0_297
	v_or_b32_e32 v28, 32, v73
	v_mad_i64_i32 v[28:29], s[28:29], v28, s18, v[66:67]
	global_load_dwordx4 v[28:31], v[28:29], off nt
.LBB0_297:
	s_or_b64 exec, exec, s[14:15]
	v_mov_b32_e32 v36, 0
	v_mov_b32_e32 v40, 0
	v_mov_b32_e32 v41, 0
	v_mov_b32_e32 v42, 0
	v_mov_b32_e32 v43, 0
	s_and_saveexec_b64 s[14:15], vcc
	s_cbranch_execz .LBB0_299
	v_or_b32_e32 v37, 36, v73
	v_mad_i64_i32 v[38:39], s[28:29], v37, s18, v[66:67]
	global_load_dwordx4 v[40:43], v[38:39], off nt
.LBB0_299:
	s_or_b64 exec, exec, s[14:15]
	v_mov_b32_e32 v37, 0
	v_mov_b32_e32 v38, 0
	v_mov_b32_e32 v39, 0
	s_and_saveexec_b64 s[14:15], vcc
	s_cbranch_execz .LBB0_301
	v_or_b32_e32 v36, 40, v73
	v_mad_i64_i32 v[36:37], s[28:29], v36, s18, v[66:67]
	global_load_dwordx4 v[36:39], v[36:37], off nt
.LBB0_301:
	s_or_b64 exec, exec, s[14:15]
	v_mov_b32_e32 v44, 0
	v_mov_b32_e32 v48, 0
	v_mov_b32_e32 v49, 0
	v_mov_b32_e32 v50, 0
	v_mov_b32_e32 v51, 0
	s_and_saveexec_b64 s[14:15], vcc
	s_cbranch_execz .LBB0_303
	v_or_b32_e32 v45, 44, v73
	v_mad_i64_i32 v[46:47], s[28:29], v45, s18, v[66:67]
	global_load_dwordx4 v[48:51], v[46:47], off nt
.LBB0_303:
	s_or_b64 exec, exec, s[14:15]
	v_mov_b32_e32 v45, 0
	v_mov_b32_e32 v46, 0
	v_mov_b32_e32 v47, 0
	s_and_saveexec_b64 s[14:15], vcc
	s_cbranch_execz .LBB0_305
	v_or_b32_e32 v44, 48, v73
	v_mad_i64_i32 v[44:45], s[28:29], v44, s18, v[66:67]
	global_load_dwordx4 v[44:47], v[44:45], off nt
.LBB0_305:
	s_or_b64 exec, exec, s[14:15]
	v_mov_b32_e32 v52, 0
	v_mov_b32_e32 v56, 0
	v_mov_b32_e32 v57, 0
	v_mov_b32_e32 v58, 0
	v_mov_b32_e32 v59, 0
	s_and_saveexec_b64 s[14:15], vcc
	s_cbranch_execz .LBB0_307
	v_or_b32_e32 v53, 52, v73
	v_mad_i64_i32 v[54:55], s[28:29], v53, s18, v[66:67]
	global_load_dwordx4 v[56:59], v[54:55], off nt
.LBB0_307:
	s_or_b64 exec, exec, s[14:15]
	v_mov_b32_e32 v53, 0
	v_mov_b32_e32 v54, 0
	v_mov_b32_e32 v55, 0
	s_and_saveexec_b64 s[14:15], vcc
	s_cbranch_execz .LBB0_309
	v_or_b32_e32 v52, 56, v73
	v_mad_i64_i32 v[52:53], s[28:29], v52, s18, v[66:67]
	global_load_dwordx4 v[52:55], v[52:53], off nt
.LBB0_309:
	s_or_b64 exec, exec, s[14:15]
	v_mov_b32_e32 v60, 0
	v_mov_b32_e32 v61, 0
	v_mov_b32_e32 v62, 0
	v_mov_b32_e32 v63, 0
	s_and_saveexec_b64 s[14:15], vcc
	s_cbranch_execz .LBB0_278
	v_or_b32_e32 v60, 60, v73
	v_mad_i64_i32 v[60:61], s[28:29], v60, s18, v[66:67]
	global_load_dwordx4 v[60:63], v[60:61], off nt
	s_branch .LBB0_278

; #define LAS __attribute__((address_space(3)))
; template <int MODE>
; __device__ __forceinline__ void transpose_item(const float* W, const float* W2, int K, int Nsrc, int Ndst, bf16_t* WT, LAS float* scr, int item, int lane) {
;     const int nblk = Ndst / 64, kb = item / nblk, nb = item % nblk, k0 = 64 * kb, n0 = 64 * nb;
;     const int c4 = lane & 15, r4 = lane >> 4;
;     const float* src; bool ok = true; int lcol;
;     if (MODE == 0) { src = W + n0 + 4 * c4; ok = (n0 + 4 * c4) < Nsrc; lcol = 4 * c4; }
;     else if (MODE == 2) {
;         const int n = n0 + 4 * c4; int sc = -1; if (n < 3264) sc = 2120 + n; else if (n >= 3328 && n < 3328 + 2120) sc = n - 3328;
;         ok = sc >= 0; src = W + (ok ? sc : 0); lcol = 4 * c4; }
;     else if (MODE == 3) { const int n = n0 + 4 * c4; ok = n < 2120; src = W + (ok ? n : 0); lcol = 4 * c4; }
;     else { const int t = c4 >> 3, g = c4 & 7; src = (t ? W2 : W) + n0 / 2 + 4 * g; lcol = 8 * g + 4 * t; }
;     f32x4 v[16];
; #pragma unroll
;     for (int i = 0; i < 16; ++i) v[i] = ok ? *(const f32x4*)(src + (size_t)(k0 + 4 * i + r4) * Nsrc) : (f32x4){0.f, 0.f, 0.f, 0.f};
; #pragma unroll
;     for (int i = 0; i < 16; ++i) { LAS float* d = scr + (4 * i + r4) * 65 + lcol; d[0] = v[i].x; d[1] = v[i].y; d[2] = v[i].z; d[3] = v[i].w; }
.LBB0_313:
	s_ashr_i32 s13, s12, 31
	s_lshr_b32 s13, s13, 27
	s_add_i32 s13, s12, s13
	s_ashr_i32 s13, s13, 5
	s_lshl_b32 s14, s13, 6
	s_lshl_b32 s13, s13, 11
	v_or_b32_e32 v4, s14, v20
	s_sub_i32 s16, s4, s13
	v_or_b32_e32 v6, 4, v4
	v_or_b32_e32 v56, 32, v4
	v_or_b32_e32 v58, 36, v4
	v_or_b32_e32 v60, 40, v4
	v_or_b32_e32 v62, 44, v4
	v_or_b32_e32 v64, 48, v4
	v_or_b32_e32 v66, 52, v4
	v_or_b32_e32 v68, 56, v4
	s_ashr_i32 s17, s16, 31
	v_ashrrev_i32_e32 v5, 31, v4
	v_or_b32_e32 v8, 8, v4
	v_or_b32_e32 v10, 12, v4
	v_or_b32_e32 v12, 16, v4
	v_or_b32_e32 v14, 20, v4
	v_or_b32_e32 v16, 24, v4
	v_or_b32_e32 v18, 28, v4
	v_or_b32_e32 v70, 60, v4
	v_add_u32_e32 v72, s16, v21
	v_ashrrev_i32_e32 v7, 31, v6
	v_ashrrev_i32_e32 v57, 31, v56
	v_ashrrev_i32_e32 v59, 31, v58
	v_ashrrev_i32_e32 v61, 31, v60
	v_ashrrev_i32_e32 v63, 31, v62
	v_ashrrev_i32_e32 v65, 31, v64
	v_ashrrev_i32_e32 v67, 31, v66
	v_ashrrev_i32_e32 v69, 31, v68
	s_ashr_i32 s15, s14, 31
	v_lshl_add_u64 v[74:75], s[16:17], 2, v[0:1]
	v_lshlrev_b64 v[4:5], 13, v[4:5]
	v_ashrrev_i32_e32 v9, 31, v8
	v_ashrrev_i32_e32 v11, 31, v10
	v_ashrrev_i32_e32 v13, 31, v12
	v_ashrrev_i32_e32 v15, 31, v14
	v_ashrrev_i32_e32 v17, 31, v16
	v_ashrrev_i32_e32 v19, 31, v18
	v_ashrrev_i32_e32 v71, 31, v70
	v_ashrrev_i32_e32 v73, 31, v72
	v_add_u32_e32 v76, 8, v72
	v_add_u32_e32 v78, 16, v72
	v_add_u32_e32 v80, 24, v72
	v_add_u32_e32 v82, 32, v72
	v_add_u32_e32 v84, 40, v72
	v_add_u32_e32 v86, 48, v72
	v_add_u32_e32 v88, 56, v72
	v_lshlrev_b64 v[6:7], 13, v[6:7]
	v_lshlrev_b64 v[90:91], 13, v[56:57]
	v_lshlrev_b64 v[92:93], 13, v[58:59]
	v_lshlrev_b64 v[60:61], 13, v[60:61]
	v_lshlrev_b64 v[62:63], 13, v[62:63]
	v_lshlrev_b64 v[64:65], 13, v[64:65]
	v_lshlrev_b64 v[66:67], 13, v[66:67]
	v_lshlrev_b64 v[68:69], 13, v[68:69]
	v_lshl_add_u64 v[120:121], s[14:15], 1, v[2:3]
	v_lshl_add_u64 v[4:5], v[74:75], 0, v[4:5]
	v_lshlrev_b64 v[8:9], 13, v[8:9]
	v_lshlrev_b64 v[10:11], 13, v[10:11]
	v_lshlrev_b64 v[12:13], 13, v[12:13]
	v_lshlrev_b64 v[14:15], 13, v[14:15]
	v_lshlrev_b64 v[16:17], 13, v[16:17]
	v_lshlrev_b64 v[18:19], 13, v[18:19]
	v_lshlrev_b64 v[70:71], 13, v[70:71]
	v_lshlrev_b64 v[72:73], 12, v[72:73]
	v_ashrrev_i32_e32 v77, 31, v76
	v_ashrrev_i32_e32 v79, 31, v78
	v_ashrrev_i32_e32 v81, 31, v80
	v_ashrrev_i32_e32 v83, 31, v82
	v_ashrrev_i32_e32 v85, 31, v84
	v_ashrrev_i32_e32 v87, 31, v86
	v_ashrrev_i32_e32 v89, 31, v88
	v_lshl_add_u64 v[6:7], v[74:75], 0, v[6:7]
	v_lshl_add_u64 v[94:95], v[74:75], 0, v[90:91]
	v_lshl_add_u64 v[108:109], v[74:75], 0, v[92:93]
	v_lshl_add_u64 v[110:111], v[74:75], 0, v[60:61]
	v_lshl_add_u64 v[112:113], v[74:75], 0, v[62:63]
	v_lshl_add_u64 v[114:115], v[74:75], 0, v[64:65]
	v_lshl_add_u64 v[116:117], v[74:75], 0, v[66:67]
	v_lshl_add_u64 v[118:119], v[74:75], 0, v[68:69]
	global_load_dwordx4 v[56:59], v[4:5], off nt
	v_lshl_add_u64 v[8:9], v[74:75], 0, v[8:9]
	v_lshl_add_u64 v[10:11], v[74:75], 0, v[10:11]
	v_lshl_add_u64 v[12:13], v[74:75], 0, v[12:13]
	v_lshl_add_u64 v[14:15], v[74:75], 0, v[14:15]
	v_lshl_add_u64 v[16:17], v[74:75], 0, v[16:17]
	v_lshl_add_u64 v[18:19], v[74:75], 0, v[18:19]
	v_lshl_add_u64 v[122:123], v[74:75], 0, v[70:71]
	v_lshl_add_u64 v[4:5], v[120:121], 0, v[72:73]
	v_lshlrev_b64 v[124:125], 12, v[76:77]
	v_lshlrev_b64 v[126:127], 12, v[78:79]
	v_lshlrev_b64 v[128:129], 12, v[80:81]
	v_lshlrev_b64 v[130:131], 12, v[82:83]
	v_lshlrev_b64 v[132:133], 12, v[84:85]
	v_lshlrev_b64 v[134:135], 12, v[86:87]
	v_lshlrev_b64 v[136:137], 12, v[88:89]
	global_load_dwordx4 v[60:63], v[6:7], off nt
	global_load_dwordx4 v[64:67], v[8:9], off nt
	global_load_dwordx4 v[68:71], v[10:11], off nt
	global_load_dwordx4 v[72:75], v[12:13], off nt
	global_load_dwordx4 v[76:79], v[14:15], off nt
	global_load_dwordx4 v[80:83], v[16:17], off nt
	global_load_dwordx4 v[84:87], v[18:19], off nt
	global_load_dwordx4 v[88:91], v[94:95], off nt
	s_nop 0
	global_load_dwordx4 v[92:95], v[108:109], off nt
	global_load_dwordx4 v[96:99], v[110:111], off nt
	global_load_dwordx4 v[100:103], v[112:113], off nt
	global_load_dwordx4 v[104:107], v[114:115], off nt
	s_nop 0
	global_load_dwordx4 v[108:111], v[116:117], off nt
	global_load_dwordx4 v[112:115], v[118:119], off nt
	s_nop 0
	global_load_dwordx4 v[116:119], v[122:123], off nt
	s_waitcnt vmcnt(0)
	ds_write2_b32 v23, v56, v57 offset1:1
	ds_write2_b32 v23, v58, v59 offset0:2 offset1:3
	ds_write2_b32 v24, v60, v61 offset1:1
	ds_write2_b32 v25, v62, v63 offset1:1
	ds_write2_b32 v26, v64, v65 offset1:1
	ds_write2_b32 v27, v66, v67 offset1:1
	ds_write2_b32 v28, v68, v69 offset1:1
	ds_write2_b32 v29, v70, v71 offset1:1
	ds_write2_b32 v30, v72, v73 offset1:1
	ds_write2_b32 v31, v74, v75 offset1:1
	ds_write2_b32 v32, v76, v77 offset1:1
	ds_write2_b32 v33, v78, v79 offset1:1
	ds_write2_b32 v34, v80, v81 offset1:1
	ds_write2_b32 v35, v82, v83 offset1:1
	ds_write2_b32 v36, v84, v85 offset1:1
	ds_write2_b32 v37, v86, v87 offset1:1
	ds_write2_b32 v38, v88, v89 offset1:1
	ds_write2_b32 v39, v90, v91 offset1:1
	ds_write2_b32 v40, v92, v93 offset1:1
	ds_write2_b32 v41, v94, v95 offset1:1
	ds_write2_b32 v42, v96, v97 offset1:1
	ds_write2_b32 v43, v98, v99 offset1:1
	ds_write2_b32 v44, v100, v101 offset1:1
	ds_write2_b32 v45, v102, v103 offset1:1
	ds_write2_b32 v46, v104, v105 offset1:1
	ds_write2_b32 v47, v106, v107 offset1:1
	ds_write2_b32 v48, v108, v109 offset1:1
	ds_write2_b32 v49, v110, v111 offset1:1
	ds_write2_b32 v50, v112, v113 offset1:1
	ds_write2_b32 v51, v114, v115 offset1:1
	ds_write2_b32 v52, v116, v117 offset1:1
	ds_write2_b32 v53, v118, v119 offset1:1
	s_waitcnt lgkmcnt(0)
; #define LAS __attribute__((address_space(3)))
; __device__ __forceinline__ unsigned pk2(float lo, float hi) { return f2bf(lo) | (f2bf(hi) << 16); }
; template <int MODE>
; __device__ __forceinline__ void transpose_item(const float* W, const float* W2, int K, int Nsrc, int Ndst, bf16_t* WT, LAS float* scr, int item, int lane) {
;     ...
;     const int c = lane & 7;
; #pragma unroll
;     for (int j = 0; j < 8; ++j) { const int n = (lane >> 3) + 8 * j; const LAS float* sp = scr + (8 * c) * 65 + n;
;         u32x4 o; o.x = pk2(sp[0 * 65], sp[1 * 65]); o.y = pk2(sp[2 * 65], sp[3 * 65]); o.z = pk2(sp[4 * 65], sp[5 * 65]); o.w = pk2(sp[6 * 65], sp[7 * 65]);
	ds_read2_b32 v[56:57], v22 offset0:65 offset1:73
	ds_read2_b32 v[58:59], v22 offset1:8
	ds_read2_b32 v[60:61], v22 offset0:130 offset1:138
	ds_read2_b32 v[62:63], v22 offset0:195 offset1:203
	ds_read2_b32 v[64:65], v54 offset0:4 offset1:12
	ds_read2_b32 v[66:67], v54 offset0:69 offset1:77
	ds_read2_b32 v[68:69], v54 offset0:134 offset1:142
	ds_read2_b32 v[70:71], v54 offset0:199 offset1:207
	ds_read2_b32 v[72:73], v22 offset0:81 offset1:89
	ds_read2_b32 v[74:75], v22 offset0:16 offset1:24
	ds_read2_b32 v[76:77], v22 offset0:146 offset1:154
	ds_read2_b32 v[78:79], v22 offset0:211 offset1:219
	ds_read2_b32 v[80:81], v54 offset0:20 offset1:28
	ds_read2_b32 v[82:83], v54 offset0:85 offset1:93
	ds_read2_b32 v[84:85], v54 offset0:150 offset1:158
	ds_read2_b32 v[86:87], v54 offset0:215 offset1:223
	ds_read2_b32 v[88:89], v22 offset0:32 offset1:40
	ds_read2_b32 v[90:91], v22 offset0:97 offset1:105
	ds_read2_b32 v[92:93], v22 offset0:162 offset1:170
	ds_read2_b32 v[94:95], v22 offset0:227 offset1:235
	ds_read2_b32 v[96:97], v54 offset0:36 offset1:44
	ds_read2_b32 v[98:99], v54 offset0:101 offset1:109
	ds_read2_b32 v[100:101], v54 offset0:166 offset1:174
	ds_read2_b32 v[102:103], v54 offset0:231 offset1:239
	ds_read2_b32 v[104:105], v22 offset0:48 offset1:56
	ds_read2_b32 v[106:107], v22 offset0:113 offset1:121
	ds_read2_b32 v[108:109], v22 offset0:178 offset1:186
	ds_read2_b32 v[110:111], v22 offset0:243 offset1:251
	ds_read2_b32 v[112:113], v54 offset0:52 offset1:60
	ds_read2_b32 v[114:115], v54 offset0:117 offset1:125
	ds_read2_b32 v[116:117], v54 offset0:182 offset1:190
	ds_read2_b32 v[118:119], v54 offset0:247 offset1:255
	v_lshl_add_u64 v[6:7], v[120:121], 0, v[124:125]
	v_lshl_add_u64 v[8:9], v[120:121], 0, v[126:127]
	v_lshl_add_u64 v[10:11], v[120:121], 0, v[128:129]
	v_lshl_add_u64 v[12:13], v[120:121], 0, v[130:131]
	v_lshl_add_u64 v[14:15], v[120:121], 0, v[132:133]
	v_lshl_add_u64 v[16:17], v[120:121], 0, v[134:135]
	v_lshl_add_u64 v[18:19], v[120:121], 0, v[136:137]
	s_waitcnt lgkmcnt(14)
	v_bfe_u32 v55, v58, 16, 1
	v_bfe_u32 v121, v60, 16, 1
	v_bfe_u32 v122, v62, 16, 1
	v_bfe_u32 v123, v64, 16, 1
	v_bfe_u32 v124, v66, 16, 1
	v_bfe_u32 v125, v68, 16, 1
	v_bfe_u32 v120, v56, 16, 1
	v_bfe_u32 v126, v70, 16, 1
	v_bfe_u32 v127, v59, 16, 1
	v_bfe_u32 v128, v57, 16, 1
	v_bfe_u32 v129, v61, 16, 1
	v_bfe_u32 v130, v63, 16, 1
	v_bfe_u32 v131, v65, 16, 1
	v_bfe_u32 v132, v67, 16, 1
	v_bfe_u32 v133, v69, 16, 1
	v_bfe_u32 v134, v71, 16, 1
	v_bfe_u32 v135, v74, 16, 1
	v_bfe_u32 v137, v76, 16, 1
	v_bfe_u32 v138, v78, 16, 1
	v_bfe_u32 v139, v80, 16, 1
	v_bfe_u32 v140, v82, 16, 1
	v_bfe_u32 v141, v84, 16, 1
	v_bfe_u32 v142, v86, 16, 1
	v_bfe_u32 v143, v75, 16, 1
	v_bfe_u32 v145, v77, 16, 1
	v_bfe_u32 v147, v81, 16, 1
	v_bfe_u32 v149, v85, 16, 1
	v_bfe_u32 v150, v87, 16, 1
	v_bfe_u32 v151, v88, 16, 1
	v_bfe_u32 v152, v90, 16, 1
	s_waitcnt lgkmcnt(13)
	v_bfe_u32 v153, v92, 16, 1
	s_waitcnt lgkmcnt(12)
	v_bfe_u32 v154, v94, 16, 1
	s_waitcnt lgkmcnt(11)
	v_bfe_u32 v155, v96, 16, 1
	s_waitcnt lgkmcnt(10)
	v_bfe_u32 v156, v98, 16, 1
	s_waitcnt lgkmcnt(9)
	v_bfe_u32 v157, v100, 16, 1
	s_waitcnt lgkmcnt(8)
	v_bfe_u32 v158, v102, 16, 1
	v_bfe_u32 v159, v89, 16, 1
	v_bfe_u32 v161, v93, 16, 1
	v_bfe_u32 v163, v97, 16, 1
	v_bfe_u32 v165, v101, 16, 1
	v_bfe_u32 v166, v103, 16, 1
	s_waitcnt lgkmcnt(7)
	v_bfe_u32 v167, v104, 16, 1
	s_waitcnt lgkmcnt(6)
	v_bfe_u32 v168, v106, 16, 1
	s_waitcnt lgkmcnt(5)
	v_bfe_u32 v169, v108, 16, 1
	s_waitcnt lgkmcnt(4)
	v_bfe_u32 v170, v110, 16, 1
	s_waitcnt lgkmcnt(3)
	v_bfe_u32 v171, v112, 16, 1
	s_waitcnt lgkmcnt(2)
	v_bfe_u32 v172, v114, 16, 1
	s_waitcnt lgkmcnt(1)
	v_bfe_u32 v173, v116, 16, 1
	v_bfe_u32 v175, v105, 16, 1
	v_bfe_u32 v177, v109, 16, 1
	v_bfe_u32 v179, v113, 16, 1
	v_bfe_u32 v181, v117, 16, 1
	v_add3_u32 v55, v58, v55, s9
	v_add3_u32 v58, v60, v121, s9
	v_add3_u32 v60, v62, v122, s9
	v_add3_u32 v62, v64, v123, s9
	v_add3_u32 v64, v66, v124, s9
	v_add3_u32 v66, v68, v125, s9
	v_bfe_u32 v136, v72, 16, 1
	v_bfe_u32 v144, v73, 16, 1
	v_bfe_u32 v146, v79, 16, 1
	v_bfe_u32 v148, v83, 16, 1
	v_bfe_u32 v160, v91, 16, 1
	v_bfe_u32 v162, v95, 16, 1
	v_bfe_u32 v164, v99, 16, 1
	s_waitcnt lgkmcnt(0)
	v_bfe_u32 v174, v118, 16, 1
	v_bfe_u32 v176, v107, 16, 1
	v_bfe_u32 v178, v111, 16, 1
	v_bfe_u32 v180, v115, 16, 1
	v_bfe_u32 v182, v119, 16, 1
	v_add3_u32 v56, v56, v120, s9
	v_add3_u32 v68, v70, v126, s9
	v_add3_u32 v59, v59, v127, s9
	v_add3_u32 v70, v57, v128, s9
	v_add3_u32 v57, v61, v129, s9
	v_add3_u32 v61, v63, v130, s9
	v_add3_u32 v63, v65, v131, s9
	v_add3_u32 v65, v67, v132, s9
	v_add3_u32 v67, v69, v133, s9
	v_add3_u32 v69, v71, v134, s9
	v_add3_u32 v71, v74, v135, s9
	v_add3_u32 v74, v76, v137, s9
	v_add3_u32 v76, v78, v138, s9
	v_add3_u32 v78, v80, v139, s9
	v_add3_u32 v80, v82, v140, s9
	v_add3_u32 v82, v84, v141, s9
	v_add3_u32 v84, v86, v142, s9
	v_add3_u32 v75, v75, v143, s9
	v_add3_u32 v77, v77, v145, s9
	v_add3_u32 v81, v81, v147, s9
	v_add3_u32 v85, v85, v149, s9
	v_add3_u32 v86, v87, v150, s9
	v_add3_u32 v87, v88, v151, s9
	v_add3_u32 v88, v90, v152, s9
	v_add3_u32 v90, v92, v153, s9
	v_add3_u32 v92, v94, v154, s9
	v_add3_u32 v94, v96, v155, s9
	v_add3_u32 v96, v98, v156, s9
	v_add3_u32 v98, v100, v157, s9
	v_add3_u32 v100, v102, v158, s9
	v_add3_u32 v89, v89, v159, s9
	v_add3_u32 v93, v93, v161, s9
	v_add3_u32 v97, v97, v163, s9
	v_add3_u32 v101, v101, v165, s9
	v_add3_u32 v102, v103, v166, s9
	v_add3_u32 v103, v104, v167, s9
	v_add3_u32 v104, v106, v168, s9
	v_add3_u32 v106, v108, v169, s9
	v_add3_u32 v108, v110, v170, s9
	v_add3_u32 v110, v112, v171, s9
	v_add3_u32 v112, v114, v172, s9
; #define LAS __attribute__((address_space(3)))
; __device__ __forceinline__ unsigned pk2(float lo, float hi) { return f2bf(lo) | (f2bf(hi) << 16); }
; #define LDS_WAIT() asm volatile("s_waitcnt lgkmcnt(0)" ::: "memory")
; template <int MODE>
; __device__ __forceinline__ void transpose_item(const float* W, const float* W2, int K, int Nsrc, int Ndst, bf16_t* WT, LAS float* scr, int item, int lane) {
;     ...
;     for (int j = 0; j < 8; ++j) { const int n = (lane >> 3) + 8 * j; const LAS float* sp = scr + (8 * c) * 65 + n;
;         u32x4 o; o.x = pk2(sp[0 * 65], sp[1 * 65]); o.y = pk2(sp[2 * 65], sp[3 * 65]); o.z = pk2(sp[4 * 65], sp[5 * 65]); o.w = pk2(sp[6 * 65], sp[7 * 65]);
;         *(u32x4*)(WT + (size_t)(n0 + n) * K + k0 + 8 * c) = o; }
;     LDS_WAIT(); asm volatile("" ::: "memory");
; template <bool OUT_BF16>
; __device__ __forceinline__ void rmsnorm_rows(Frame& F, const float* X, const float* gain, void* O) {
;     const int gw = F.bid * NWAVES + F.wave, NGW = F.G * NWAVES;
;     f32x4 gv[8];
; #pragma unroll
;     for (int j = 0; j < 8; ++j) gv[j] = ((const f32x4*)gain)[F.lane + 64 * j];
;     for (int m = gw; m < S; m += NGW) {
;         const f32x4* xr = (const f32x4*)(X + (size_t)m * DM) + F.lane;
;         f32x4 v[8]; float s = 0.f;
; #pragma unroll
;         for (int j = 0; j < 8; ++j) { v[j] = xr[64 * j]; s += (v[j].x * v[j].x + v[j].y * v[j].y) + (v[j].z * v[j].z + v[j].w * v[j].w); }
	v_add3_u32 v114, v116, v173, s9
	v_add3_u32 v105, v105, v175, s9
	v_add3_u32 v109, v109, v177, s9
	v_add3_u32 v113, v113, v179, s9
	v_add3_u32 v117, v117, v181, s9
	v_lshrrev_b32_e32 v55, 16, v55
	v_lshrrev_b32_e32 v58, 16, v58
	v_lshrrev_b32_e32 v62, 16, v62
	v_lshrrev_b32_e32 v66, 16, v66
	v_add3_u32 v72, v72, v136, s9
	v_add3_u32 v73, v73, v144, s9
	v_add3_u32 v79, v79, v146, s9
	v_add3_u32 v83, v83, v148, s9
	v_add3_u32 v91, v91, v160, s9
	v_add3_u32 v95, v95, v162, s9
	v_add3_u32 v99, v99, v164, s9
	v_add3_u32 v116, v118, v174, s9
	v_add3_u32 v107, v107, v176, s9
	v_add3_u32 v111, v111, v178, s9
	v_add3_u32 v115, v115, v180, s9
	v_add3_u32 v118, v119, v182, s9
	v_lshrrev_b32_e32 v119, 16, v59
	v_lshrrev_b32_e32 v120, 16, v57
	v_lshrrev_b32_e32 v63, 16, v63
	v_lshrrev_b32_e32 v67, 16, v67
	v_lshrrev_b32_e32 v71, 16, v71
	v_lshrrev_b32_e32 v74, 16, v74
	v_lshrrev_b32_e32 v78, 16, v78
	v_lshrrev_b32_e32 v82, 16, v82
	v_lshrrev_b32_e32 v75, 16, v75
	v_lshrrev_b32_e32 v77, 16, v77
	v_lshrrev_b32_e32 v81, 16, v81
	v_lshrrev_b32_e32 v85, 16, v85
	v_lshrrev_b32_e32 v87, 16, v87
	v_lshrrev_b32_e32 v90, 16, v90
	v_lshrrev_b32_e32 v94, 16, v94
	v_lshrrev_b32_e32 v98, 16, v98
	v_lshrrev_b32_e32 v89, 16, v89
	v_lshrrev_b32_e32 v93, 16, v93
	v_lshrrev_b32_e32 v97, 16, v97
	v_lshrrev_b32_e32 v101, 16, v101
	v_lshrrev_b32_e32 v103, 16, v103
	v_lshrrev_b32_e32 v106, 16, v106
	v_lshrrev_b32_e32 v110, 16, v110
	v_lshrrev_b32_e32 v114, 16, v114
	v_lshrrev_b32_e32 v105, 16, v105
	v_lshrrev_b32_e32 v109, 16, v109
	v_lshrrev_b32_e32 v113, 16, v113
	v_lshrrev_b32_e32 v117, 16, v117
	v_and_or_b32 v56, v56, s11, v55
	v_and_or_b32 v57, v60, s11, v58
	v_and_or_b32 v58, v64, s11, v62
	v_and_or_b32 v59, v68, s11, v66
	v_and_or_b32 v60, v70, s11, v119
	v_and_or_b32 v61, v61, s11, v120
	v_and_or_b32 v62, v65, s11, v63
	v_and_or_b32 v63, v69, s11, v67
	v_and_or_b32 v64, v72, s11, v71
	v_and_or_b32 v65, v76, s11, v74
	v_and_or_b32 v66, v80, s11, v78
	v_and_or_b32 v67, v84, s11, v82
	v_and_or_b32 v68, v73, s11, v75
	v_and_or_b32 v69, v79, s11, v77
	v_and_or_b32 v70, v83, s11, v81
	v_and_or_b32 v71, v86, s11, v85
	v_and_or_b32 v72, v88, s11, v87
	v_and_or_b32 v73, v92, s11, v90
	v_and_or_b32 v74, v96, s11, v94
	v_and_or_b32 v75, v100, s11, v98
	v_and_or_b32 v76, v91, s11, v89
	v_and_or_b32 v77, v95, s11, v93
	v_and_or_b32 v78, v99, s11, v97
	v_and_or_b32 v79, v102, s11, v101
	v_and_or_b32 v80, v104, s11, v103
	v_and_or_b32 v81, v108, s11, v106
	v_and_or_b32 v82, v112, s11, v110
	v_and_or_b32 v83, v116, s11, v114
	v_and_or_b32 v84, v107, s11, v105
	v_and_or_b32 v85, v111, s11, v109
	v_and_or_b32 v86, v115, s11, v113
	v_and_or_b32 v87, v118, s11, v117
	global_store_dwordx4 v[4:5], v[56:59], off
	global_store_dwordx4 v[6:7], v[60:63], off
	global_store_dwordx4 v[8:9], v[64:67], off
	global_store_dwordx4 v[10:11], v[68:71], off
	global_store_dwordx4 v[12:13], v[72:75], off
	global_store_dwordx4 v[14:15], v[76:79], off
	global_store_dwordx4 v[16:17], v[80:83], off
	global_store_dwordx4 v[18:19], v[84:87], off
	s_waitcnt lgkmcnt(0)
	s_add_i32 s12, s12, s10
	s_add_i32 s4, s4, s5
	s_cmpk_lt_i32 s12, 0x400
	s_cbranch_scc1 .LBB0_313
.LBB0_314:
	s_cmpk_gt_i32 s8, 0x3fff
	s_cbranch_scc1 .LBB0_317
	s_waitcnt lgkmcnt(0)
	s_load_dwordx2 s[4:5], s[0:1], 0x28
	v_lshlrev_b32_e32 v32, 4, v184
	v_mov_b32_e32 v33, 0
	s_ashr_i32 s9, s8, 31
	s_lshl_b64 s[12:13], s[8:9], 13
	s_waitcnt lgkmcnt(0)
	v_lshl_add_u64 v[16:17], s[4:5], 0, v[32:33]
	v_add_co_u32_e32 v34, vcc, 0x1000, v16
	global_load_dwordx4 v[0:3], v32, s[4:5]
	global_load_dwordx4 v[4:7], v32, s[4:5] offset:1024
	v_addc_co_u32_e32 v35, vcc, 0, v17, vcc
	global_load_dwordx4 v[8:11], v32, s[4:5] offset:3072
	global_load_dwordx4 v[12:15], v32, s[4:5] offset:2048
	global_load_dwordx4 v[16:19], v[34:35], off nt
	global_load_dwordx4 v[20:23], v[34:35], off offset:1024 nt
	global_load_dwordx4 v[24:27], v[34:35], off offset:2048 nt
	global_load_dwordx4 v[28:31], v[34:35], off offset:3072 nt
	s_load_dwordx2 s[4:5], s[0:1], 0xe8
	s_mov_b64 s[14:15], 0x1000
	s_mov_b64 s[18:19], 0xb000000
	v_mov_b32_e32 v68, 0x358637bd
	s_mov_b32 s16, 0xf800000
	s_waitcnt lgkmcnt(0)
	s_add_u32 s4, s4, s12
	s_addc_u32 s5, s5, s13
	s_ashr_i32 s11, s10, 31
	s_lshl_b64 s[24:25], s[8:9], 12
	s_lshl_b64 s[12:13], s[10:11], 13
	v_lshl_add_u64 v[34:35], s[4:5], 0, v[32:33]
	s_add_u32 s4, s34, s24
	v_lshlrev_b32_e32 v32, 3, v184
	s_addc_u32 s5, s35, s25
	v_lshl_add_u64 v[32:33], s[4:5], 0, v[32:33]
	v_mov_b32_e32 v69, 0x260
	s_movk_i32 s17, 0x7fff
	v_mov_b32_e32 v70, 0x3a000000
	v_lshl_add_u64 v[62:63], v[34:35], 0, s[14:15]
	s_lshl_b64 s[14:15], s[10:11], 12
	v_lshl_add_u64 v[64:65], v[32:33], 0, s[18:19]
	v_mov_b32_e32 v71, 1
	s_waitcnt vmcnt(0)
	v_mov_b32_e32 v66, v1
	v_mov_b32_e32 v67, v3
	v_mov_b32_e32 v1, v2
	v_mov_b32_e32 v2, v5
	v_mov_b32_e32 v3, v7
	v_mov_b32_e32 v5, v6
	v_mov_b32_e32 v6, v13
	v_mov_b32_e32 v7, v15
	v_mov_b32_e32 v13, v14
	v_mov_b32_e32 v14, v9
	v_mov_b32_e32 v15, v11
	v_mov_b32_e32 v9, v10
	v_mov_b32_e32 v10, v17
	v_mov_b32_e32 v11, v19
	v_mov_b32_e32 v17, v18
	v_mov_b32_e32 v18, v21
	v_mov_b32_e32 v19, v23
	v_mov_b32_e32 v21, v22
	v_mov_b32_e32 v22, v25
	v_mov_b32_e32 v23, v27
	v_mov_b32_e32 v25, v26
	v_mov_b32_e32 v26, v29
	v_mov_b32_e32 v27, v31
	v_mov_b32_e32 v29, v30
; __device__ __forceinline__ unsigned pk2(float lo, float hi) { return f2bf(lo) | (f2bf(hi) << 16); }
; template <bool OUT_BF16>
; __device__ __forceinline__ void rmsnorm_rows(Frame& F, const float* X, const float* gain, void* O) {
;     ...
;     for (int m = gw; m < S; m += NGW) {
;         const f32x4* xr = (const f32x4*)(X + (size_t)m * DM) + F.lane;
;         f32x4 v[8]; float s = 0.f;
; #pragma unroll
;         for (int j = 0; j < 8; ++j) { v[j] = xr[64 * j]; s += (v[j].x * v[j].x + v[j].y * v[j].y) + (v[j].z * v[j].z + v[j].w * v[j].w); }
;         const float rs = 1.f / sqrtf(wave_sum(s) * (1.f / DM) + NORM_EPS);
;         if (OUT_BF16) {
;             u32x2* o8 = (u32x2*)((bf16_t*)O + (size_t)m * DM) + F.lane;
; #pragma unroll
;             for (int j = 0; j < 8; ++j) { u32x2 w; w.x = pk2(v[j].x * rs * gv[j].x, v[j].y * rs * gv[j].y); w.y = pk2(v[j].z * rs * gv[j].z, v[j].w * rs * gv[j].w); o8[64 * j] = w; }
.LBB0_316:
	global_load_dwordx4 v[30:33], v[62:63], off offset:-4096 nt
	global_load_dwordx4 v[34:37], v[62:63], off offset:-3072 nt
	global_load_dwordx4 v[38:41], v[62:63], off offset:-2048 nt
	global_load_dwordx4 v[42:45], v[62:63], off offset:-1024 nt
	global_load_dwordx4 v[46:49], v[62:63], off nt
	global_load_dwordx4 v[50:53], v[62:63], off offset:1024 nt
	global_load_dwordx4 v[54:57], v[62:63], off offset:2048 nt
	global_load_dwordx4 v[58:61], v[62:63], off offset:3072 nt
	v_mov_b32_e32 v88, 0
	v_mov_b32_e32 v89, 0
	s_add_i32 s8, s8, s10
	v_lshl_add_u64 v[62:63], v[62:63], 0, s[12:13]
	s_cmpk_lt_i32 s8, 0x4000
	s_waitcnt vmcnt(7)
	v_mul_f32_e32 v90, v31, v31
	v_mul_f32_e32 v91, v33, v33
	s_waitcnt vmcnt(6)
	v_mul_f32_e32 v92, v35, v35
	v_mul_f32_e32 v93, v37, v37
	s_waitcnt vmcnt(5)
	v_mul_f32_e32 v94, v39, v39
	v_mul_f32_e32 v95, v41, v41
	v_fmac_f32_e32 v90, v30, v30
	v_fmac_f32_e32 v91, v32, v32
	v_fmac_f32_e32 v92, v34, v34
	v_fmac_f32_e32 v93, v36, v36
	s_waitcnt vmcnt(4)
	v_mul_f32_e32 v96, v43, v43
	v_mul_f32_e32 v97, v45, v45
	v_mov_b32_e32 v72, v30
	v_mov_b32_e32 v73, v32
	v_fmac_f32_e32 v94, v38, v38
	v_fmac_f32_e32 v95, v40, v40
	v_mov_b32_e32 v32, v31
	v_add_f32_e32 v30, v90, v91
	v_add_f32_e32 v31, v92, v93
	s_waitcnt vmcnt(3)
	v_mul_f32_e32 v98, v47, v47
	v_mul_f32_e32 v99, v49, v49
	v_mov_b32_e32 v74, v34
	v_fmac_f32_e32 v96, v42, v42
	v_fmac_f32_e32 v97, v44, v44
	v_add_f32_e32 v34, v94, v95
	v_add_f32_e32 v30, v30, v31
	s_waitcnt vmcnt(2)
	v_mul_f32_e32 v100, v51, v51
	v_mul_f32_e32 v101, v53, v53
	v_mov_b32_e32 v75, v36
	v_fmac_f32_e32 v98, v46, v46
	v_fmac_f32_e32 v99, v48, v48
	v_mov_b32_e32 v36, v35
	v_add_f32_e32 v35, v96, v97
	v_add_f32_e32 v30, v30, v34
	s_waitcnt vmcnt(1)
	v_mul_f32_e32 v102, v55, v55
	v_mul_f32_e32 v103, v57, v57
	v_mov_b32_e32 v76, v38
	v_fmac_f32_e32 v100, v50, v50
	v_fmac_f32_e32 v101, v52, v52
	v_add_f32_e32 v38, v98, v99
	v_add_f32_e32 v30, v30, v35
	s_waitcnt vmcnt(0)
	v_mul_f32_e32 v104, v59, v59
	v_mul_f32_e32 v105, v61, v61
	v_mov_b32_e32 v77, v40
	v_fmac_f32_e32 v102, v54, v54
	v_fmac_f32_e32 v103, v56, v56
	v_mov_b32_e32 v40, v39
	v_add_f32_e32 v39, v100, v101
	v_add_f32_e32 v30, v30, v38
	v_mov_b32_e32 v78, v42
	v_fmac_f32_e32 v104, v58, v58
	v_fmac_f32_e32 v105, v60, v60
	v_add_f32_e32 v42, v102, v103
	v_add_f32_e32 v30, v30, v39
	v_mov_b32_e32 v79, v44
	v_mov_b32_e32 v44, v43
	v_add_f32_e32 v43, v104, v105
	v_add_f32_e32 v30, v30, v42
	v_add_f32_e32 v30, v30, v43
	v_mov_b32_e32 v80, v46
	v_mov_b32_e32 v81, v48
	v_add_f32_dpp v30, v30, v30 quad_perm:[1,0,3,2] row_mask:0xf bank_mask:0xf bound_ctrl:1
	v_mov_b32_e32 v82, v50
	v_mov_b32_e32 v83, v52
	v_add_f32_dpp v30, v30, v30 quad_perm:[2,3,0,1] row_mask:0xf bank_mask:0xf bound_ctrl:1
	v_mov_b32_e32 v84, v54
	v_mov_b32_e32 v85, v56
	v_add_f32_dpp v30, v30, v30 row_half_mirror row_mask:0xf bank_mask:0xf bound_ctrl:1
	v_mov_b32_e32 v86, v58
	v_mov_b32_e32 v87, v60
	v_add_f32_dpp v30, v30, v30 row_mirror row_mask:0xf bank_mask:0xf bound_ctrl:1
	v_mov_b32_e32 v48, v47
	v_mov_b32_e32 v52, v51
	v_mov_b32_dpp v88, v30 row_bcast:15 row_mask:0xa bank_mask:0xf
	v_add_f32_e32 v30, v30, v88
	v_mov_b32_e32 v56, v55
	v_mov_b32_e32 v60, v59
	v_mov_b32_dpp v89, v30 row_bcast:31 row_mask:0xc bank_mask:0xf
	v_add_f32_e32 v30, v30, v89
	s_nop 0
	v_readlane_b32 s4, v30, 63
	s_nop 1
	v_fma_f32 v30, s4, v70, v68
	v_mul_f32_e32 v31, 0x4f800000, v30
	v_cmp_gt_f32_e32 vcc, s16, v30
	s_nop 1
	v_cndmask_b32_e32 v30, v30, v31, vcc
	v_sqrt_f32_e32 v31, v30
	s_nop 0
	v_add_u32_e32 v34, -1, v31
	v_add_u32_e32 v35, 1, v31
	v_fma_f32 v38, -v34, v31, v30
	v_fma_f32 v39, -v35, v31, v30
	v_cmp_ge_f32_e64 s[4:5], 0, v38
	s_nop 1
	v_cndmask_b32_e64 v31, v31, v34, s[4:5]
	v_cmp_lt_f32_e64 s[4:5], 0, v39
	s_nop 1
	v_cndmask_b32_e64 v31, v31, v35, s[4:5]
	v_mul_f32_e32 v34, 0x37800000, v31
	v_cndmask_b32_e32 v31, v31, v34, vcc
	v_cmp_class_f32_e32 vcc, v30, v69
	s_nop 1
	v_cndmask_b32_e32 v30, v31, v30, vcc
	v_div_scale_f32 v31, s[4:5], v30, v30, 1.0
	v_rcp_f32_e32 v35, v31
	v_div_scale_f32 v34, vcc, 1.0, v30, 1.0
	v_fma_f32 v38, -v31, v35, 1.0
	v_fmac_f32_e32 v35, v38, v35
	v_mul_f32_e32 v38, v34, v35
	v_fma_f32 v39, -v31, v38, v34
	v_fmac_f32_e32 v38, v39, v35
	v_fma_f32 v31, -v31, v38, v34
	v_div_fmas_f32 v31, v31, v35, v38
	v_div_fixup_f32 v30, v31, v30, 1.0
	v_pk_mul_f32 v[32:33], v[32:33], v[30:31] op_sel_hi:[1,0]
	v_pk_mul_f32 v[34:35], v[72:73], v[30:31] op_sel_hi:[1,0]
	v_pk_mul_f32 v[38:39], v[74:75], v[30:31] op_sel_hi:[1,0]
	v_pk_mul_f32 v[36:37], v[36:37], v[30:31] op_sel_hi:[1,0]
	v_pk_mul_f32 v[42:43], v[76:77], v[30:31] op_sel_hi:[1,0]
	v_pk_mul_f32 v[40:41], v[40:41], v[30:31] op_sel_hi:[1,0]
	v_pk_mul_f32 v[46:47], v[78:79], v[30:31] op_sel_hi:[1,0]
	v_pk_mul_f32 v[44:45], v[44:45], v[30:31] op_sel_hi:[1,0]
	v_pk_mul_f32 v[50:51], v[80:81], v[30:31] op_sel_hi:[1,0]
	v_pk_mul_f32 v[48:49], v[48:49], v[30:31] op_sel_hi:[1,0]
	v_pk_mul_f32 v[54:55], v[82:83], v[30:31] op_sel_hi:[1,0]
	v_pk_mul_f32 v[52:53], v[52:53], v[30:31] op_sel_hi:[1,0]
	v_pk_mul_f32 v[58:59], v[84:85], v[30:31] op_sel_hi:[1,0]
	v_pk_mul_f32 v[56:57], v[56:57], v[30:31] op_sel_hi:[1,0]
	v_pk_mul_f32 v[72:73], v[86:87], v[30:31] op_sel_hi:[1,0]
	v_pk_mul_f32 v[30:31], v[60:61], v[30:31] op_sel_hi:[1,0]
	v_pk_mul_f32 v[32:33], v[66:67], v[32:33]
	v_pk_mul_f32 v[34:35], v[0:1], v[34:35]
	v_pk_mul_f32 v[36:37], v[2:3], v[36:37]
	v_pk_mul_f32 v[40:41], v[6:7], v[40:41]
	v_pk_mul_f32 v[44:45], v[14:15], v[44:45]
	v_pk_mul_f32 v[48:49], v[10:11], v[48:49]
	v_pk_mul_f32 v[52:53], v[18:19], v[52:53]
	v_pk_mul_f32 v[56:57], v[22:23], v[56:57]
	v_pk_mul_f32 v[30:31], v[26:27], v[30:31]
; __device__ __forceinline__ unsigned pk2(float lo, float hi) { return f2bf(lo) | (f2bf(hi) << 16); }
; template <bool OUT_BF16>
; __device__ __forceinline__ void rmsnorm_rows(Frame& F, const float* X, const float* gain, void* O) {
;     ...
;             u32x2* o8 = (u32x2*)((bf16_t*)O + (size_t)m * DM) + F.lane;
; #pragma unroll
;             for (int j = 0; j < 8; ++j) { u32x2 w; w.x = pk2(v[j].x * rs * gv[j].x, v[j].y * rs * gv[j].y); w.y = pk2(v[j].z * rs * gv[j].z, v[j].w * rs * gv[j].w); o8[64 * j] = w; }
	v_and_b32_sdwa v74, v33, v71 dst_sel:DWORD dst_unused:UNUSED_PAD src0_sel:WORD_1 src1_sel:DWORD
	v_and_b32_sdwa v75, v32, v71 dst_sel:DWORD dst_unused:UNUSED_PAD src0_sel:WORD_1 src1_sel:DWORD
	v_pk_mul_f32 v[38:39], v[4:5], v[38:39]
	v_pk_mul_f32 v[42:43], v[12:13], v[42:43]
	v_pk_mul_f32 v[46:47], v[8:9], v[46:47]
	v_pk_mul_f32 v[50:51], v[16:17], v[50:51]
	v_pk_mul_f32 v[54:55], v[20:21], v[54:55]
	v_pk_mul_f32 v[58:59], v[24:25], v[58:59]
	v_pk_mul_f32 v[60:61], v[28:29], v[72:73]
	v_and_b32_sdwa v72, v35, v71 dst_sel:DWORD dst_unused:UNUSED_PAD src0_sel:WORD_1 src1_sel:DWORD
	v_and_b32_sdwa v73, v34, v71 dst_sel:DWORD dst_unused:UNUSED_PAD src0_sel:WORD_1 src1_sel:DWORD
	v_and_b32_sdwa v78, v37, v71 dst_sel:DWORD dst_unused:UNUSED_PAD src0_sel:WORD_1 src1_sel:DWORD
	v_and_b32_sdwa v79, v36, v71 dst_sel:DWORD dst_unused:UNUSED_PAD src0_sel:WORD_1 src1_sel:DWORD
	v_and_b32_sdwa v82, v41, v71 dst_sel:DWORD dst_unused:UNUSED_PAD src0_sel:WORD_1 src1_sel:DWORD
	v_and_b32_sdwa v83, v40, v71 dst_sel:DWORD dst_unused:UNUSED_PAD src0_sel:WORD_1 src1_sel:DWORD
	v_and_b32_sdwa v86, v45, v71 dst_sel:DWORD dst_unused:UNUSED_PAD src0_sel:WORD_1 src1_sel:DWORD
	v_and_b32_sdwa v87, v44, v71 dst_sel:DWORD dst_unused:UNUSED_PAD src0_sel:WORD_1 src1_sel:DWORD
	v_and_b32_sdwa v90, v49, v71 dst_sel:DWORD dst_unused:UNUSED_PAD src0_sel:WORD_1 src1_sel:DWORD
	v_and_b32_sdwa v91, v48, v71 dst_sel:DWORD dst_unused:UNUSED_PAD src0_sel:WORD_1 src1_sel:DWORD
	v_and_b32_sdwa v94, v53, v71 dst_sel:DWORD dst_unused:UNUSED_PAD src0_sel:WORD_1 src1_sel:DWORD
	v_and_b32_sdwa v95, v52, v71 dst_sel:DWORD dst_unused:UNUSED_PAD src0_sel:WORD_1 src1_sel:DWORD
	v_and_b32_sdwa v98, v57, v71 dst_sel:DWORD dst_unused:UNUSED_PAD src0_sel:WORD_1 src1_sel:DWORD
	v_and_b32_sdwa v99, v56, v71 dst_sel:DWORD dst_unused:UNUSED_PAD src0_sel:WORD_1 src1_sel:DWORD
	v_and_b32_sdwa v102, v31, v71 dst_sel:DWORD dst_unused:UNUSED_PAD src0_sel:WORD_1 src1_sel:DWORD
	v_and_b32_sdwa v103, v30, v71 dst_sel:DWORD dst_unused:UNUSED_PAD src0_sel:WORD_1 src1_sel:DWORD
	v_add3_u32 v33, v33, v74, s17
	v_add3_u32 v32, v32, v75, s17
	v_and_b32_sdwa v76, v39, v71 dst_sel:DWORD dst_unused:UNUSED_PAD src0_sel:WORD_1 src1_sel:DWORD
	v_and_b32_sdwa v77, v38, v71 dst_sel:DWORD dst_unused:UNUSED_PAD src0_sel:WORD_1 src1_sel:DWORD
	v_and_b32_sdwa v80, v43, v71 dst_sel:DWORD dst_unused:UNUSED_PAD src0_sel:WORD_1 src1_sel:DWORD
	v_and_b32_sdwa v81, v42, v71 dst_sel:DWORD dst_unused:UNUSED_PAD src0_sel:WORD_1 src1_sel:DWORD
	v_and_b32_sdwa v84, v47, v71 dst_sel:DWORD dst_unused:UNUSED_PAD src0_sel:WORD_1 src1_sel:DWORD
	v_and_b32_sdwa v85, v46, v71 dst_sel:DWORD dst_unused:UNUSED_PAD src0_sel:WORD_1 src1_sel:DWORD
	v_and_b32_sdwa v88, v51, v71 dst_sel:DWORD dst_unused:UNUSED_PAD src0_sel:WORD_1 src1_sel:DWORD
	v_and_b32_sdwa v89, v50, v71 dst_sel:DWORD dst_unused:UNUSED_PAD src0_sel:WORD_1 src1_sel:DWORD
	v_and_b32_sdwa v92, v55, v71 dst_sel:DWORD dst_unused:UNUSED_PAD src0_sel:WORD_1 src1_sel:DWORD
	v_and_b32_sdwa v93, v54, v71 dst_sel:DWORD dst_unused:UNUSED_PAD src0_sel:WORD_1 src1_sel:DWORD
	v_and_b32_sdwa v96, v59, v71 dst_sel:DWORD dst_unused:UNUSED_PAD src0_sel:WORD_1 src1_sel:DWORD
	v_and_b32_sdwa v97, v58, v71 dst_sel:DWORD dst_unused:UNUSED_PAD src0_sel:WORD_1 src1_sel:DWORD
	v_and_b32_sdwa v100, v61, v71 dst_sel:DWORD dst_unused:UNUSED_PAD src0_sel:WORD_1 src1_sel:DWORD
	v_and_b32_sdwa v101, v60, v71 dst_sel:DWORD dst_unused:UNUSED_PAD src0_sel:WORD_1 src1_sel:DWORD
	v_add3_u32 v34, v34, v73, s17
	v_add3_u32 v35, v35, v72, s17
	v_add3_u32 v37, v37, v78, s17
	v_add3_u32 v36, v36, v79, s17
	v_add3_u32 v41, v41, v82, s17
	v_add3_u32 v40, v40, v83, s17
	v_add3_u32 v45, v45, v86, s17
	v_add3_u32 v44, v44, v87, s17
	v_add3_u32 v49, v49, v90, s17
	v_add3_u32 v48, v48, v91, s17
	v_add3_u32 v53, v53, v94, s17
	v_add3_u32 v52, v52, v95, s17
	v_add3_u32 v57, v57, v98, s17
	v_add3_u32 v56, v56, v99, s17
	v_add3_u32 v31, v31, v102, s17
	v_add3_u32 v30, v30, v103, s17
	v_and_b32_e32 v33, 0xffff0000, v33
	v_and_b32_e32 v32, 0xffff0000, v32
	v_add3_u32 v38, v38, v77, s17
	v_add3_u32 v39, v39, v76, s17
	v_add3_u32 v42, v42, v81, s17
	v_add3_u32 v43, v43, v80, s17
	v_add3_u32 v46, v46, v85, s17
	v_add3_u32 v47, v47, v84, s17
	v_add3_u32 v50, v50, v89, s17
	v_add3_u32 v51, v51, v88, s17
	v_add3_u32 v54, v54, v93, s17
	v_add3_u32 v55, v55, v92, s17
	v_add3_u32 v58, v58, v97, s17
	v_add3_u32 v59, v59, v96, s17
	v_add3_u32 v60, v60, v101, s17
	v_add3_u32 v61, v61, v100, s17
	v_and_b32_e32 v37, 0xffff0000, v37
	v_and_b32_e32 v36, 0xffff0000, v36
	v_and_b32_e32 v41, 0xffff0000, v41
	v_and_b32_e32 v40, 0xffff0000, v40
	v_and_b32_e32 v45, 0xffff0000, v45
	v_and_b32_e32 v44, 0xffff0000, v44
	v_and_b32_e32 v49, 0xffff0000, v49
	v_and_b32_e32 v48, 0xffff0000, v48
	v_and_b32_e32 v53, 0xffff0000, v53
	v_and_b32_e32 v52, 0xffff0000, v52
	v_and_b32_e32 v57, 0xffff0000, v57
	v_and_b32_e32 v56, 0xffff0000, v56
	v_and_b32_e32 v72, 0xffff0000, v31
	v_and_b32_e32 v73, 0xffff0000, v30
	v_or_b32_sdwa v31, v33, v35 dst_sel:DWORD dst_unused:UNUSED_PAD src0_sel:DWORD src1_sel:WORD_1
	v_or_b32_sdwa v30, v32, v34 dst_sel:DWORD dst_unused:UNUSED_PAD src0_sel:DWORD src1_sel:WORD_1
	v_or_b32_sdwa v33, v37, v39 dst_sel:DWORD dst_unused:UNUSED_PAD src0_sel:DWORD src1_sel:WORD_1
	v_or_b32_sdwa v32, v36, v38 dst_sel:DWORD dst_unused:UNUSED_PAD src0_sel:DWORD src1_sel:WORD_1
	v_or_b32_sdwa v35, v41, v43 dst_sel:DWORD dst_unused:UNUSED_PAD src0_sel:DWORD src1_sel:WORD_1
	v_or_b32_sdwa v34, v40, v42 dst_sel:DWORD dst_unused:UNUSED_PAD src0_sel:DWORD src1_sel:WORD_1
	v_or_b32_sdwa v37, v45, v47 dst_sel:DWORD dst_unused:UNUSED_PAD src0_sel:DWORD src1_sel:WORD_1
	v_or_b32_sdwa v36, v44, v46 dst_sel:DWORD dst_unused:UNUSED_PAD src0_sel:DWORD src1_sel:WORD_1
	v_or_b32_sdwa v39, v49, v51 dst_sel:DWORD dst_unused:UNUSED_PAD src0_sel:DWORD src1_sel:WORD_1
	v_or_b32_sdwa v38, v48, v50 dst_sel:DWORD dst_unused:UNUSED_PAD src0_sel:DWORD src1_sel:WORD_1
	v_or_b32_sdwa v41, v53, v55 dst_sel:DWORD dst_unused:UNUSED_PAD src0_sel:DWORD src1_sel:WORD_1
	v_or_b32_sdwa v40, v52, v54 dst_sel:DWORD dst_unused:UNUSED_PAD src0_sel:DWORD src1_sel:WORD_1
	v_or_b32_sdwa v43, v57, v59 dst_sel:DWORD dst_unused:UNUSED_PAD src0_sel:DWORD src1_sel:WORD_1
	v_or_b32_sdwa v42, v56, v58 dst_sel:DWORD dst_unused:UNUSED_PAD src0_sel:DWORD src1_sel:WORD_1
	v_or_b32_sdwa v45, v72, v61 dst_sel:DWORD dst_unused:UNUSED_PAD src0_sel:DWORD src1_sel:WORD_1
	v_or_b32_sdwa v44, v73, v60 dst_sel:DWORD dst_unused:UNUSED_PAD src0_sel:DWORD src1_sel:WORD_1
	global_store_dwordx2 v[64:65], v[30:31], off
	global_store_dwordx2 v[64:65], v[32:33], off offset:512
	global_store_dwordx2 v[64:65], v[34:35], off offset:1024
	global_store_dwordx2 v[64:65], v[36:37], off offset:1536
	global_store_dwordx2 v[64:65], v[38:39], off offset:2048
	global_store_dwordx2 v[64:65], v[40:41], off offset:2560
	global_store_dwordx2 v[64:65], v[42:43], off offset:3072
	global_store_dwordx2 v[64:65], v[44:45], off offset:3584
	v_lshl_add_u64 v[64:65], v[64:65], 0, s[14:15]
	s_cbranch_scc1 .LBB0_316

; #define LAS __attribute__((address_space(3)))
; #define LDS_WAIT() asm volatile("s_waitcnt lgkmcnt(0)" ::: "memory")
; template <int MODE>
; __device__ __forceinline__ void transpose_item(const float* W, const float* W2, int K, int Nsrc, int Ndst, bf16_t* WT, LAS float* scr, int item, int lane) {
;     const int nblk = Ndst / 64, kb = item / nblk, nb = item % nblk, k0 = 64 * kb, n0 = 64 * nb;
;     const int c4 = lane & 15, r4 = lane >> 4;
;     const float* src; bool ok = true; int lcol;
;     if (MODE == 0) { src = W + n0 + 4 * c4; ok = (n0 + 4 * c4) < Nsrc; lcol = 4 * c4; }
;     else if (MODE == 2) {
;         const int n = n0 + 4 * c4; int sc = -1; if (n < 3264) sc = 2120 + n; else if (n >= 3328 && n < 3328 + 2120) sc = n - 3328;
;         ok = sc >= 0; src = W + (ok ? sc : 0); lcol = 4 * c4; }
;     else if (MODE == 3) { const int n = n0 + 4 * c4; ok = n < 2120; src = W + (ok ? n : 0); lcol = 4 * c4; }
;     else { const int t = c4 >> 3, g = c4 & 7; src = (t ? W2 : W) + n0 / 2 + 4 * g; lcol = 8 * g + 4 * t; }
;     f32x4 v[16];
; #pragma unroll
;     for (int i = 0; i < 16; ++i) v[i] = ok ? *(const f32x4*)(src + (size_t)(k0 + 4 * i + r4) * Nsrc) : (f32x4){0.f, 0.f, 0.f, 0.f};
; #pragma unroll
;     for (int i = 0; i < 16; ++i) { LAS float* d = scr + (4 * i + r4) * 65 + lcol; d[0] = v[i].x; d[1] = v[i].y; d[2] = v[i].z; d[3] = v[i].w; }
;     LDS_WAIT(); asm volatile("" ::: "memory");
; template <int MODE>
; __device__ __forceinline__ void convert_weight(Frame& F, const float* W, const float* W2, int K, int Nsrc, int Ndst, bf16_t* WT) {
;     ...
;     for (int it = gw; it < nitems; it += NGW) transpose_item<MODE>(W, W2, K, Nsrc, Ndst, WT, scr, it, F.lane);
.LBB0_1385:
	s_mul_hi_i32 s16, s15, 0x2e8ba2e9
	s_lshr_b32 s17, s16, 31
	s_ashr_i32 s16, s16, 5
	s_add_i32 s17, s16, s17
	s_mul_i32 s18, s17, 0xffffea00
	s_lshl_b32 s16, s17, 6
	s_mul_i32 s19, s17, 0xffffd400
	s_add_i32 s18, s5, s18
	v_or_b32_e32 v57, s16, v20
	v_add_u32_e32 v4, s19, v24
	s_ashr_i32 s19, s18, 31
	s_ashr_i32 s17, s16, 31
	v_or_b32_e32 v62, 4, v57
	v_or_b32_e32 v63, 8, v57
	v_or_b32_e32 v64, 12, v57
	v_or_b32_e32 v65, 16, v57
	v_or_b32_e32 v66, 20, v57
	v_or_b32_e32 v67, 24, v57
	v_or_b32_e32 v68, 28, v57
	v_or_b32_e32 v69, 32, v57
	v_or_b32_e32 v70, 36, v57
	v_or_b32_e32 v71, 40, v57
	v_or_b32_e32 v72, 44, v57
	v_or_b32_e32 v73, 48, v57
	v_or_b32_e32 v74, 52, v57
	v_or_b32_e32 v75, 56, v57
	v_or_b32_e32 v76, 60, v57
	v_add_u32_e32 v58, -8, v4
	v_lshl_add_u64 v[60:61], s[18:19], 2, v[0:1]
	v_lshl_add_u64 v[18:19], s[16:17], 1, v[2:3]
	v_ashrrev_i32_e32 v59, 31, v58
	v_mad_i64_i32 v[90:91], s[16:17], v57, s12, v[60:61]
	v_mad_i64_i32 v[92:93], s[16:17], v62, s12, v[60:61]
	v_mad_i64_i32 v[94:95], s[16:17], v63, s12, v[60:61]
	v_mad_i64_i32 v[96:97], s[16:17], v64, s12, v[60:61]
	v_mad_i64_i32 v[98:99], s[16:17], v65, s12, v[60:61]
	v_mad_i64_i32 v[100:101], s[16:17], v66, s12, v[60:61]
	v_mad_i64_i32 v[102:103], s[16:17], v67, s12, v[60:61]
	v_mad_i64_i32 v[104:105], s[16:17], v68, s12, v[60:61]
	v_mad_i64_i32 v[106:107], s[16:17], v69, s12, v[60:61]
	v_mad_i64_i32 v[108:109], s[16:17], v70, s12, v[60:61]
	v_mad_i64_i32 v[110:111], s[16:17], v71, s12, v[60:61]
	v_mad_i64_i32 v[112:113], s[16:17], v72, s12, v[60:61]
	v_mad_i64_i32 v[114:115], s[16:17], v73, s12, v[60:61]
	v_mad_i64_i32 v[116:117], s[16:17], v74, s12, v[60:61]
	v_mad_i64_i32 v[118:119], s[16:17], v75, s12, v[60:61]
	v_mad_i64_i32 v[120:121], s[16:17], v76, s12, v[60:61]
	v_lshlrev_b64 v[122:123], 12, v[58:59]
	global_load_dwordx4 v[58:61], v[90:91], off nt
	global_load_dwordx4 v[62:65], v[92:93], off nt
	global_load_dwordx4 v[66:69], v[94:95], off nt
	global_load_dwordx4 v[70:73], v[96:97], off nt
	global_load_dwordx4 v[74:77], v[98:99], off nt
	global_load_dwordx4 v[78:81], v[100:101], off nt
	global_load_dwordx4 v[82:85], v[102:103], off nt
	global_load_dwordx4 v[86:89], v[104:105], off nt
	global_load_dwordx4 v[90:93], v[106:107], off nt
	global_load_dwordx4 v[94:97], v[108:109], off nt
	s_nop 0
	global_load_dwordx4 v[98:101], v[110:111], off nt
	global_load_dwordx4 v[102:105], v[112:113], off nt
	global_load_dwordx4 v[106:109], v[114:115], off nt
	s_nop 0
	global_load_dwordx4 v[110:113], v[116:117], off nt
	s_nop 0
	global_load_dwordx4 v[114:117], v[118:119], off nt
	s_nop 0
	global_load_dwordx4 v[118:121], v[120:121], off nt
	v_subrev_u32_e32 v6, 56, v4
	v_subrev_u32_e32 v8, 48, v4
	v_subrev_u32_e32 v10, 40, v4
	v_subrev_u32_e32 v12, 32, v4
	v_subrev_u32_e32 v14, 24, v4
	v_add_u32_e32 v16, -16, v4
	v_ashrrev_i32_e32 v5, 31, v4
	v_ashrrev_i32_e32 v7, 31, v6
	v_ashrrev_i32_e32 v9, 31, v8
	v_ashrrev_i32_e32 v11, 31, v10
	v_ashrrev_i32_e32 v13, 31, v12
	v_ashrrev_i32_e32 v15, 31, v14
	v_ashrrev_i32_e32 v17, 31, v16
	v_lshlrev_b64 v[4:5], 12, v[4:5]
	v_lshlrev_b64 v[6:7], 12, v[6:7]
	v_lshlrev_b64 v[8:9], 12, v[8:9]
	v_lshlrev_b64 v[10:11], 12, v[10:11]
	v_lshlrev_b64 v[12:13], 12, v[12:13]
	v_lshlrev_b64 v[14:15], 12, v[14:15]
	v_lshlrev_b64 v[16:17], 12, v[16:17]
	v_lshl_add_u64 v[4:5], v[18:19], 0, v[4:5]
	v_lshl_add_u64 v[6:7], v[18:19], 0, v[6:7]
	v_lshl_add_u64 v[8:9], v[18:19], 0, v[8:9]
	s_waitcnt vmcnt(15)
	ds_write2_b32 v25, v58, v59 offset1:1
	ds_write2_b32 v25, v60, v61 offset0:2 offset1:3
	s_waitcnt vmcnt(14)
	ds_write2_b32 v26, v62, v63 offset1:1
	ds_write2_b32 v27, v64, v65 offset1:1
	s_waitcnt vmcnt(13)
	ds_write2_b32 v28, v66, v67 offset1:1
	ds_write2_b32 v29, v68, v69 offset1:1
	s_waitcnt vmcnt(12)
	ds_write2_b32 v30, v70, v71 offset1:1
	ds_write2_b32 v31, v72, v73 offset1:1
	s_waitcnt vmcnt(11)
	ds_write2_b32 v32, v74, v75 offset1:1
	ds_write2_b32 v33, v76, v77 offset1:1
	s_waitcnt vmcnt(10)
	ds_write2_b32 v34, v78, v79 offset1:1
	ds_write2_b32 v35, v80, v81 offset1:1
	s_waitcnt vmcnt(9)
	ds_write2_b32 v36, v82, v83 offset1:1
	ds_write2_b32 v37, v84, v85 offset1:1
	s_waitcnt vmcnt(8)
	ds_write2_b32 v38, v86, v87 offset1:1
	ds_write2_b32 v39, v88, v89 offset1:1
	s_waitcnt vmcnt(7)
	ds_write2_b32 v40, v90, v91 offset1:1
	ds_write2_b32 v41, v92, v93 offset1:1
	s_waitcnt vmcnt(6)
	ds_write2_b32 v42, v94, v95 offset1:1
	ds_write2_b32 v43, v96, v97 offset1:1
	s_waitcnt vmcnt(5)
	ds_write2_b32 v44, v98, v99 offset1:1
	ds_write2_b32 v45, v100, v101 offset1:1
	s_waitcnt vmcnt(4)
	ds_write2_b32 v46, v102, v103 offset1:1
	ds_write2_b32 v47, v104, v105 offset1:1
	s_waitcnt vmcnt(3)
	ds_write2_b32 v48, v106, v107 offset1:1
	ds_write2_b32 v49, v108, v109 offset1:1
	s_waitcnt vmcnt(2)
	ds_write2_b32 v50, v110, v111 offset1:1
	ds_write2_b32 v51, v112, v113 offset1:1
	s_waitcnt vmcnt(1)
	ds_write2_b32 v52, v114, v115 offset1:1
	ds_write2_b32 v53, v116, v117 offset1:1
	s_waitcnt vmcnt(0)
	ds_write2_b32 v54, v118, v119 offset1:1
	ds_write2_b32 v55, v120, v121 offset1:1
	s_waitcnt lgkmcnt(0)
; #define LAS __attribute__((address_space(3)))
; __device__ __forceinline__ unsigned pk2(float lo, float hi) { return f2bf(lo) | (f2bf(hi) << 16); }
; template <int MODE>
; __device__ __forceinline__ void transpose_item(const float* W, const float* W2, int K, int Nsrc, int Ndst, bf16_t* WT, LAS float* scr, int item, int lane) {
;     ...
;     const int c = lane & 7;
; #pragma unroll
;     for (int j = 0; j < 8; ++j) { const int n = (lane >> 3) + 8 * j; const LAS float* sp = scr + (8 * c) * 65 + n;
;         u32x4 o; o.x = pk2(sp[0 * 65], sp[1 * 65]); o.y = pk2(sp[2 * 65], sp[3 * 65]); o.z = pk2(sp[4 * 65], sp[5 * 65]); o.w = pk2(sp[6 * 65], sp[7 * 65]);
;         *(u32x4*)(WT + (size_t)(n0 + n) * K + k0 + 8 * c) = o; }
	ds_read2_b32 v[58:59], v23 offset0:65 offset1:73
	ds_read2_b32 v[60:61], v23 offset1:8
	ds_read2_b32 v[62:63], v23 offset0:130 offset1:138
	ds_read2_b32 v[64:65], v23 offset0:195 offset1:203
	ds_read2_b32 v[66:67], v56 offset0:4 offset1:12
	ds_read2_b32 v[68:69], v56 offset0:69 offset1:77
	ds_read2_b32 v[70:71], v56 offset0:134 offset1:142
	ds_read2_b32 v[72:73], v56 offset0:199 offset1:207
	ds_read2_b32 v[74:75], v23 offset0:81 offset1:89
	ds_read2_b32 v[76:77], v23 offset0:16 offset1:24
	ds_read2_b32 v[78:79], v23 offset0:146 offset1:154
	ds_read2_b32 v[80:81], v23 offset0:211 offset1:219
	ds_read2_b32 v[82:83], v56 offset0:20 offset1:28
	ds_read2_b32 v[84:85], v56 offset0:85 offset1:93
	ds_read2_b32 v[86:87], v56 offset0:150 offset1:158
	ds_read2_b32 v[88:89], v56 offset0:215 offset1:223
	ds_read2_b32 v[90:91], v23 offset0:32 offset1:40
	ds_read2_b32 v[92:93], v23 offset0:97 offset1:105
	ds_read2_b32 v[94:95], v23 offset0:162 offset1:170
	ds_read2_b32 v[96:97], v23 offset0:227 offset1:235
	ds_read2_b32 v[98:99], v56 offset0:36 offset1:44
	ds_read2_b32 v[100:101], v56 offset0:101 offset1:109
	ds_read2_b32 v[102:103], v56 offset0:166 offset1:174
	ds_read2_b32 v[104:105], v56 offset0:231 offset1:239
	ds_read2_b32 v[106:107], v23 offset0:48 offset1:56
	ds_read2_b32 v[108:109], v23 offset0:113 offset1:121
	ds_read2_b32 v[110:111], v23 offset0:178 offset1:186
	ds_read2_b32 v[112:113], v23 offset0:243 offset1:251
	ds_read2_b32 v[114:115], v56 offset0:52 offset1:60
	ds_read2_b32 v[116:117], v56 offset0:117 offset1:125
	ds_read2_b32 v[118:119], v56 offset0:182 offset1:190
	ds_read2_b32 v[120:121], v56 offset0:247 offset1:255
	v_lshl_add_u64 v[10:11], v[18:19], 0, v[10:11]
	v_lshl_add_u64 v[12:13], v[18:19], 0, v[12:13]
	v_lshl_add_u64 v[14:15], v[18:19], 0, v[14:15]
	v_lshl_add_u64 v[16:17], v[18:19], 0, v[16:17]
	v_lshl_add_u64 v[18:19], v[18:19], 0, v[122:123]
	s_waitcnt lgkmcnt(14)
	v_bfe_u32 v57, v60, 16, 1
	v_bfe_u32 v123, v62, 16, 1
	v_bfe_u32 v124, v64, 16, 1
	v_bfe_u32 v125, v66, 16, 1
	v_bfe_u32 v126, v68, 16, 1
	v_bfe_u32 v127, v70, 16, 1
	v_bfe_u32 v122, v58, 16, 1
	v_bfe_u32 v128, v72, 16, 1
	v_bfe_u32 v129, v61, 16, 1
	v_bfe_u32 v130, v59, 16, 1
	v_bfe_u32 v131, v63, 16, 1
	v_bfe_u32 v132, v65, 16, 1
	v_bfe_u32 v133, v67, 16, 1
	v_bfe_u32 v134, v69, 16, 1
	v_bfe_u32 v135, v71, 16, 1
	v_bfe_u32 v136, v73, 16, 1
	v_bfe_u32 v137, v76, 16, 1
	v_bfe_u32 v139, v78, 16, 1
	v_bfe_u32 v140, v80, 16, 1
	v_bfe_u32 v141, v82, 16, 1
	v_bfe_u32 v142, v84, 16, 1
	v_bfe_u32 v143, v86, 16, 1
	v_bfe_u32 v144, v88, 16, 1
	v_bfe_u32 v145, v77, 16, 1
	v_bfe_u32 v147, v79, 16, 1
	v_bfe_u32 v149, v83, 16, 1
	v_bfe_u32 v151, v87, 16, 1
	v_bfe_u32 v152, v89, 16, 1
	v_bfe_u32 v153, v90, 16, 1
	v_bfe_u32 v154, v92, 16, 1
	s_waitcnt lgkmcnt(13)
	v_bfe_u32 v155, v94, 16, 1
	s_waitcnt lgkmcnt(12)
	v_bfe_u32 v156, v96, 16, 1
	s_waitcnt lgkmcnt(11)
	v_bfe_u32 v157, v98, 16, 1
	s_waitcnt lgkmcnt(10)
	v_bfe_u32 v158, v100, 16, 1
	s_waitcnt lgkmcnt(9)
	v_bfe_u32 v159, v102, 16, 1
	s_waitcnt lgkmcnt(8)
	v_bfe_u32 v160, v104, 16, 1
	v_bfe_u32 v161, v91, 16, 1
	v_bfe_u32 v163, v95, 16, 1
	v_bfe_u32 v165, v99, 16, 1
	v_bfe_u32 v167, v103, 16, 1
	v_bfe_u32 v168, v105, 16, 1
	s_waitcnt lgkmcnt(7)
	v_bfe_u32 v169, v106, 16, 1
	s_waitcnt lgkmcnt(6)
	v_bfe_u32 v170, v108, 16, 1
	s_waitcnt lgkmcnt(5)
	v_bfe_u32 v171, v110, 16, 1
	s_waitcnt lgkmcnt(4)
	v_bfe_u32 v172, v112, 16, 1
	s_waitcnt lgkmcnt(3)
	v_bfe_u32 v173, v114, 16, 1
	s_waitcnt lgkmcnt(2)
	v_bfe_u32 v174, v116, 16, 1
	s_waitcnt lgkmcnt(1)
	v_bfe_u32 v175, v118, 16, 1
	v_bfe_u32 v177, v107, 16, 1
	v_bfe_u32 v179, v111, 16, 1
	v_bfe_u32 v181, v115, 16, 1
	v_bfe_u32 v183, v119, 16, 1
	v_add3_u32 v57, v60, v57, s13
	v_add3_u32 v60, v62, v123, s13
	v_add3_u32 v62, v64, v124, s13
	v_add3_u32 v64, v66, v125, s13
	v_add3_u32 v66, v68, v126, s13
	v_add3_u32 v68, v70, v127, s13
	v_bfe_u32 v138, v74, 16, 1
	v_bfe_u32 v146, v75, 16, 1
	v_bfe_u32 v148, v81, 16, 1
	v_bfe_u32 v150, v85, 16, 1
	v_bfe_u32 v162, v93, 16, 1
	v_bfe_u32 v164, v97, 16, 1
	v_bfe_u32 v166, v101, 16, 1
	s_waitcnt lgkmcnt(0)
; #define LAS __attribute__((address_space(3)))
; __device__ __forceinline__ unsigned pk2(float lo, float hi) { return f2bf(lo) | (f2bf(hi) << 16); }
; #define LDS_WAIT() asm volatile("s_waitcnt lgkmcnt(0)" ::: "memory")
; template <int MODE>
; __device__ __forceinline__ void transpose_item(const float* W, const float* W2, int K, int Nsrc, int Ndst, bf16_t* WT, LAS float* scr, int item, int lane) {
;     ...
;     for (int j = 0; j < 8; ++j) { const int n = (lane >> 3) + 8 * j; const LAS float* sp = scr + (8 * c) * 65 + n;
;         u32x4 o; o.x = pk2(sp[0 * 65], sp[1 * 65]); o.y = pk2(sp[2 * 65], sp[3 * 65]); o.z = pk2(sp[4 * 65], sp[5 * 65]); o.w = pk2(sp[6 * 65], sp[7 * 65]);
;         *(u32x4*)(WT + (size_t)(n0 + n) * K + k0 + 8 * c) = o; }
;     LDS_WAIT(); asm volatile("" ::: "memory");
; }
; template <int MODE>
; __device__ __forceinline__ void convert_weight(Frame& F, const float* W, const float* W2, int K, int Nsrc, int Ndst, bf16_t* WT) {
;     LAS float* scr = (LAS float*)(F.lds + F.wave * 17408);
;     const int gw = F.bid * NWAVES + F.wave, NGW = F.G * NWAVES, nitems = (K / 64) * (Ndst / 64);
;     for (int it = gw; it < nitems; it += NGW) transpose_item<MODE>(W, W2, K, Nsrc, Ndst, WT, scr, it, F.lane);
	v_bfe_u32 v176, v120, 16, 1
	v_bfe_u32 v178, v109, 16, 1
	v_bfe_u32 v180, v113, 16, 1
	v_bfe_u32 v182, v117, 16, 1
	v_bfe_u32 v186, v121, 16, 1
	v_add3_u32 v58, v58, v122, s13
	v_add3_u32 v70, v72, v128, s13
	v_add3_u32 v61, v61, v129, s13
	v_add3_u32 v72, v59, v130, s13
	v_add3_u32 v59, v63, v131, s13
	v_add3_u32 v63, v65, v132, s13
	v_add3_u32 v65, v67, v133, s13
	v_add3_u32 v67, v69, v134, s13
	v_add3_u32 v69, v71, v135, s13
	v_add3_u32 v71, v73, v136, s13
	v_add3_u32 v73, v76, v137, s13
	v_add3_u32 v76, v78, v139, s13
	v_add3_u32 v78, v80, v140, s13
	v_add3_u32 v80, v82, v141, s13
	v_add3_u32 v82, v84, v142, s13
	v_add3_u32 v84, v86, v143, s13
	v_add3_u32 v86, v88, v144, s13
	v_add3_u32 v77, v77, v145, s13
	v_add3_u32 v79, v79, v147, s13
	v_add3_u32 v83, v83, v149, s13
	v_add3_u32 v87, v87, v151, s13
	v_add3_u32 v88, v89, v152, s13
	v_add3_u32 v89, v90, v153, s13
	v_add3_u32 v90, v92, v154, s13
	v_add3_u32 v92, v94, v155, s13
	v_add3_u32 v94, v96, v156, s13
	v_add3_u32 v96, v98, v157, s13
	v_add3_u32 v98, v100, v158, s13
	v_add3_u32 v100, v102, v159, s13
	v_add3_u32 v102, v104, v160, s13
	v_add3_u32 v91, v91, v161, s13
	v_add3_u32 v95, v95, v163, s13
	v_add3_u32 v99, v99, v165, s13
	v_add3_u32 v103, v103, v167, s13
	v_add3_u32 v104, v105, v168, s13
	v_add3_u32 v105, v106, v169, s13
	v_add3_u32 v106, v108, v170, s13
	v_add3_u32 v108, v110, v171, s13
	v_add3_u32 v110, v112, v172, s13
	v_add3_u32 v112, v114, v173, s13
	v_add3_u32 v114, v116, v174, s13
	v_add3_u32 v116, v118, v175, s13
	v_add3_u32 v107, v107, v177, s13
	v_add3_u32 v111, v111, v179, s13
	v_add3_u32 v115, v115, v181, s13
	v_add3_u32 v119, v119, v183, s13
	v_lshrrev_b32_e32 v57, 16, v57
	v_lshrrev_b32_e32 v60, 16, v60
	v_lshrrev_b32_e32 v64, 16, v64
	v_lshrrev_b32_e32 v68, 16, v68
	v_add3_u32 v74, v74, v138, s13
	v_add3_u32 v75, v75, v146, s13
	v_add3_u32 v81, v81, v148, s13
	v_add3_u32 v85, v85, v150, s13
	v_add3_u32 v93, v93, v162, s13
	v_add3_u32 v97, v97, v164, s13
	v_add3_u32 v101, v101, v166, s13
	v_add3_u32 v118, v120, v176, s13
	v_add3_u32 v109, v109, v178, s13
	v_add3_u32 v113, v113, v180, s13
	v_add3_u32 v117, v117, v182, s13
	v_add3_u32 v120, v121, v186, s13
	v_lshrrev_b32_e32 v121, 16, v61
	v_lshrrev_b32_e32 v122, 16, v59
	v_lshrrev_b32_e32 v65, 16, v65
	v_lshrrev_b32_e32 v69, 16, v69
	v_lshrrev_b32_e32 v73, 16, v73
	v_lshrrev_b32_e32 v76, 16, v76
	v_lshrrev_b32_e32 v80, 16, v80
	v_lshrrev_b32_e32 v84, 16, v84
	v_lshrrev_b32_e32 v77, 16, v77
	v_lshrrev_b32_e32 v79, 16, v79
	v_lshrrev_b32_e32 v83, 16, v83
	v_lshrrev_b32_e32 v87, 16, v87
	v_lshrrev_b32_e32 v89, 16, v89
	v_lshrrev_b32_e32 v92, 16, v92
	v_lshrrev_b32_e32 v96, 16, v96
	v_lshrrev_b32_e32 v100, 16, v100
	v_lshrrev_b32_e32 v91, 16, v91
	v_lshrrev_b32_e32 v95, 16, v95
	v_lshrrev_b32_e32 v99, 16, v99
	v_lshrrev_b32_e32 v103, 16, v103
	v_lshrrev_b32_e32 v105, 16, v105
	v_lshrrev_b32_e32 v108, 16, v108
	v_lshrrev_b32_e32 v112, 16, v112
	v_lshrrev_b32_e32 v116, 16, v116
	v_lshrrev_b32_e32 v107, 16, v107
	v_lshrrev_b32_e32 v111, 16, v111
	v_lshrrev_b32_e32 v115, 16, v115
	v_lshrrev_b32_e32 v119, 16, v119
	v_and_or_b32 v58, v58, s14, v57
	v_and_or_b32 v59, v62, s14, v60
	v_and_or_b32 v60, v66, s14, v64
	v_and_or_b32 v61, v70, s14, v68
	v_and_or_b32 v62, v72, s14, v121
	v_and_or_b32 v63, v63, s14, v122
	v_and_or_b32 v64, v67, s14, v65
	v_and_or_b32 v65, v71, s14, v69
	v_and_or_b32 v66, v74, s14, v73
	v_and_or_b32 v67, v78, s14, v76
	v_and_or_b32 v68, v82, s14, v80
	v_and_or_b32 v69, v86, s14, v84
	v_and_or_b32 v70, v75, s14, v77
	v_and_or_b32 v71, v81, s14, v79
	v_and_or_b32 v72, v85, s14, v83
	v_and_or_b32 v73, v88, s14, v87
	v_and_or_b32 v74, v90, s14, v89
	v_and_or_b32 v75, v94, s14, v92
	v_and_or_b32 v76, v98, s14, v96
	v_and_or_b32 v77, v102, s14, v100
	v_and_or_b32 v78, v93, s14, v91
	v_and_or_b32 v79, v97, s14, v95
	v_and_or_b32 v80, v101, s14, v99
	v_and_or_b32 v81, v104, s14, v103
	v_and_or_b32 v82, v106, s14, v105
	v_and_or_b32 v83, v110, s14, v108
	v_and_or_b32 v84, v114, s14, v112
	v_and_or_b32 v85, v118, s14, v116
	v_and_or_b32 v86, v109, s14, v107
	v_and_or_b32 v87, v113, s14, v111
	v_and_or_b32 v88, v117, s14, v115
	v_and_or_b32 v89, v120, s14, v119
	global_store_dwordx4 v[6:7], v[58:61], off
	global_store_dwordx4 v[8:9], v[62:65], off
	global_store_dwordx4 v[10:11], v[66:69], off
	global_store_dwordx4 v[12:13], v[70:73], off
	global_store_dwordx4 v[14:15], v[74:77], off
	global_store_dwordx4 v[16:17], v[78:81], off
	global_store_dwordx4 v[18:19], v[82:85], off
	global_store_dwordx4 v[4:5], v[86:89], off
	s_waitcnt lgkmcnt(0)
	s_add_i32 s15, s15, s10
	s_add_i32 s5, s5, s9
	s_cmpk_lt_i32 s15, 0x1600
	v_add_u32_e32 v24, s11, v24
	s_cbranch_scc1 .LBB0_1385

; #define LAS __attribute__((address_space(3)))
; #define LDS_WAIT() asm volatile("s_waitcnt lgkmcnt(0)" ::: "memory")
; template <int MODE>
; __device__ __forceinline__ void transpose_item(const float* W, const float* W2, int K, int Nsrc, int Ndst, bf16_t* WT, LAS float* scr, int item, int lane) {
;     const int nblk = Ndst / 64, kb = item / nblk, nb = item % nblk, k0 = 64 * kb, n0 = 64 * nb;
;     const int c4 = lane & 15, r4 = lane >> 4;
;     const float* src; bool ok = true; int lcol;
;     if (MODE == 0) { src = W + n0 + 4 * c4; ok = (n0 + 4 * c4) < Nsrc; lcol = 4 * c4; }
;     else if (MODE == 2) {
;         const int n = n0 + 4 * c4; int sc = -1; if (n < 3264) sc = 2120 + n; else if (n >= 3328 && n < 3328 + 2120) sc = n - 3328;
;         ok = sc >= 0; src = W + (ok ? sc : 0); lcol = 4 * c4; }
;     else if (MODE == 3) { const int n = n0 + 4 * c4; ok = n < 2120; src = W + (ok ? n : 0); lcol = 4 * c4; }
;     else { const int t = c4 >> 3, g = c4 & 7; src = (t ? W2 : W) + n0 / 2 + 4 * g; lcol = 8 * g + 4 * t; }
;     f32x4 v[16];
; #pragma unroll
;     for (int i = 0; i < 16; ++i) v[i] = ok ? *(const f32x4*)(src + (size_t)(k0 + 4 * i + r4) * Nsrc) : (f32x4){0.f, 0.f, 0.f, 0.f};
; #pragma unroll
;     for (int i = 0; i < 16; ++i) { LAS float* d = scr + (4 * i + r4) * 65 + lcol; d[0] = v[i].x; d[1] = v[i].y; d[2] = v[i].z; d[3] = v[i].w; }
;     LDS_WAIT(); asm volatile("" ::: "memory");
.LBB0_1388:
	s_ashr_i32 s14, s13, 31
	s_lshr_b32 s14, s14, 27
	s_add_i32 s14, s13, s14
	s_ashr_i32 s15, s14, 5
	s_lshl_b32 s14, s15, 6
	s_lshl_b32 s16, s15, 11
	v_or_b32_e32 v4, s14, v20
	s_mul_i32 s17, s15, 0xff500000
	s_sub_i32 s16, s5, s16
	v_or_b32_e32 v8, 4, v4
	v_or_b32_e32 v10, 8, v4
	v_or_b32_e32 v12, 12, v4
	v_or_b32_e32 v14, 16, v4
	v_or_b32_e32 v16, 20, v4
	v_or_b32_e32 v18, 24, v4
	v_or_b32_e32 v56, 28, v4
	v_or_b32_e32 v58, 32, v4
	v_or_b32_e32 v60, 36, v4
	v_or_b32_e32 v62, 40, v4
	v_or_b32_e32 v64, 44, v4
	v_or_b32_e32 v66, 48, v4
	v_add_u32_e32 v6, s17, v22
	s_ashr_i32 s17, s16, 31
	v_ashrrev_i32_e32 v5, 31, v4
	v_or_b32_e32 v68, 52, v4
	v_or_b32_e32 v70, 56, v4
	v_or_b32_e32 v72, 60, v4
	v_ashrrev_i32_e32 v9, 31, v8
	v_ashrrev_i32_e32 v11, 31, v10
	v_ashrrev_i32_e32 v13, 31, v12
	v_ashrrev_i32_e32 v15, 31, v14
	v_ashrrev_i32_e32 v17, 31, v16
	v_ashrrev_i32_e32 v19, 31, v18
	v_ashrrev_i32_e32 v57, 31, v56
	v_ashrrev_i32_e32 v59, 31, v58
	v_ashrrev_i32_e32 v61, 31, v60
	v_ashrrev_i32_e32 v63, 31, v62
	v_ashrrev_i32_e32 v65, 31, v64
	v_ashrrev_i32_e32 v67, 31, v66
	s_ashr_i32 s15, s14, 31
	v_add_u32_e32 v76, 0xb000, v6
	v_add_u32_e32 v78, 0x16000, v6
	v_add_u32_e32 v80, 0x21000, v6
	v_add_u32_e32 v82, 0x2c000, v6
	v_add_u32_e32 v84, 0x37000, v6
	v_add_u32_e32 v86, 0x42000, v6
	v_add_u32_e32 v88, 0x4d000, v6
	v_lshl_add_u64 v[90:91], s[16:17], 2, v[0:1]
	v_lshlrev_b64 v[92:93], 13, v[4:5]
	v_ashrrev_i32_e32 v69, 31, v68
	v_ashrrev_i32_e32 v71, 31, v70
	v_ashrrev_i32_e32 v73, 31, v72
	v_lshlrev_b64 v[94:95], 13, v[8:9]
	v_lshlrev_b64 v[96:97], 13, v[10:11]
	v_lshlrev_b64 v[98:99], 13, v[12:13]
	v_lshlrev_b64 v[100:101], 13, v[14:15]
	v_lshlrev_b64 v[102:103], 13, v[16:17]
	v_lshlrev_b64 v[104:105], 13, v[18:19]
	v_lshlrev_b64 v[106:107], 13, v[56:57]
	v_lshlrev_b64 v[108:109], 13, v[58:59]
	v_lshlrev_b64 v[60:61], 13, v[60:61]
	v_lshlrev_b64 v[62:63], 13, v[62:63]
	v_lshlrev_b64 v[64:65], 13, v[64:65]
	v_lshlrev_b64 v[66:67], 13, v[66:67]
	v_lshl_add_u64 v[74:75], s[14:15], 1, v[2:3]
	v_ashrrev_i32_e32 v7, 31, v6
	v_ashrrev_i32_e32 v77, 31, v76
	v_ashrrev_i32_e32 v79, 31, v78
	v_ashrrev_i32_e32 v81, 31, v80
	v_ashrrev_i32_e32 v83, 31, v82
	v_ashrrev_i32_e32 v85, 31, v84
	v_ashrrev_i32_e32 v87, 31, v86
	v_ashrrev_i32_e32 v89, 31, v88
	v_lshl_add_u64 v[92:93], v[90:91], 0, v[92:93]
	v_lshlrev_b64 v[68:69], 13, v[68:69]
	v_lshlrev_b64 v[70:71], 13, v[70:71]
	v_lshlrev_b64 v[72:73], 13, v[72:73]
	v_lshl_add_u64 v[110:111], v[90:91], 0, v[94:95]
	v_lshl_add_u64 v[96:97], v[90:91], 0, v[96:97]
	v_lshl_add_u64 v[98:99], v[90:91], 0, v[98:99]
	v_lshl_add_u64 v[100:101], v[90:91], 0, v[100:101]
	v_lshl_add_u64 v[102:103], v[90:91], 0, v[102:103]
	v_lshl_add_u64 v[104:105], v[90:91], 0, v[104:105]
	v_lshl_add_u64 v[106:107], v[90:91], 0, v[106:107]
	v_lshl_add_u64 v[108:109], v[90:91], 0, v[108:109]
	v_lshl_add_u64 v[112:113], v[90:91], 0, v[60:61]
	v_lshl_add_u64 v[114:115], v[90:91], 0, v[62:63]
	v_lshl_add_u64 v[116:117], v[90:91], 0, v[64:65]
	v_lshl_add_u64 v[118:119], v[90:91], 0, v[66:67]
	v_lshl_add_u64 v[4:5], v[6:7], 1, v[74:75]
	v_lshl_add_u64 v[6:7], v[76:77], 1, v[74:75]
	v_lshl_add_u64 v[8:9], v[78:79], 1, v[74:75]
	v_lshl_add_u64 v[10:11], v[80:81], 1, v[74:75]
	v_lshl_add_u64 v[12:13], v[82:83], 1, v[74:75]
	v_lshl_add_u64 v[14:15], v[84:85], 1, v[74:75]
	v_lshl_add_u64 v[16:17], v[86:87], 1, v[74:75]
	v_lshl_add_u64 v[18:19], v[88:89], 1, v[74:75]
	global_load_dwordx4 v[56:59], v[92:93], off nt
	v_lshl_add_u64 v[120:121], v[90:91], 0, v[68:69]
	v_lshl_add_u64 v[122:123], v[90:91], 0, v[70:71]
	v_lshl_add_u64 v[124:125], v[90:91], 0, v[72:73]
	global_load_dwordx4 v[60:63], v[110:111], off nt
	global_load_dwordx4 v[64:67], v[96:97], off nt
	global_load_dwordx4 v[68:71], v[98:99], off nt
	global_load_dwordx4 v[72:75], v[100:101], off nt
	global_load_dwordx4 v[76:79], v[102:103], off nt
	global_load_dwordx4 v[80:83], v[104:105], off nt
	global_load_dwordx4 v[84:87], v[106:107], off nt
	global_load_dwordx4 v[88:91], v[108:109], off nt
	global_load_dwordx4 v[92:95], v[112:113], off nt
	global_load_dwordx4 v[96:99], v[114:115], off nt
	global_load_dwordx4 v[100:103], v[116:117], off nt
	s_nop 0
	global_load_dwordx4 v[104:107], v[118:119], off nt
	global_load_dwordx4 v[108:111], v[120:121], off nt
	global_load_dwordx4 v[112:115], v[122:123], off nt
	s_nop 0
	global_load_dwordx4 v[116:119], v[124:125], off nt
	s_waitcnt vmcnt(15)
	ds_write2_b32 v23, v56, v57 offset1:1
	ds_write2_b32 v23, v58, v59 offset0:2 offset1:3
	s_waitcnt vmcnt(14)
	ds_write2_b32 v24, v60, v61 offset1:1
	ds_write2_b32 v25, v62, v63 offset1:1
	s_waitcnt vmcnt(13)
	ds_write2_b32 v26, v64, v65 offset1:1
	ds_write2_b32 v27, v66, v67 offset1:1
	s_waitcnt vmcnt(12)
	ds_write2_b32 v28, v68, v69 offset1:1
	ds_write2_b32 v29, v70, v71 offset1:1
	s_waitcnt vmcnt(11)
	ds_write2_b32 v30, v72, v73 offset1:1
	ds_write2_b32 v31, v74, v75 offset1:1
	s_waitcnt vmcnt(10)
	ds_write2_b32 v32, v76, v77 offset1:1
	ds_write2_b32 v33, v78, v79 offset1:1
	s_waitcnt vmcnt(9)
	ds_write2_b32 v34, v80, v81 offset1:1
	ds_write2_b32 v35, v82, v83 offset1:1
	s_waitcnt vmcnt(8)
	ds_write2_b32 v36, v84, v85 offset1:1
	ds_write2_b32 v37, v86, v87 offset1:1
	s_waitcnt vmcnt(7)
	ds_write2_b32 v38, v88, v89 offset1:1
	ds_write2_b32 v39, v90, v91 offset1:1
	s_waitcnt vmcnt(6)
	ds_write2_b32 v40, v92, v93 offset1:1
	ds_write2_b32 v41, v94, v95 offset1:1
	s_waitcnt vmcnt(5)
	ds_write2_b32 v42, v96, v97 offset1:1
	ds_write2_b32 v43, v98, v99 offset1:1
	s_waitcnt vmcnt(4)
	ds_write2_b32 v44, v100, v101 offset1:1
	ds_write2_b32 v45, v102, v103 offset1:1
	s_waitcnt vmcnt(3)
; #define LAS __attribute__((address_space(3)))
; __device__ __forceinline__ unsigned pk2(float lo, float hi) { return f2bf(lo) | (f2bf(hi) << 16); }
; #define LDS_WAIT() asm volatile("s_waitcnt lgkmcnt(0)" ::: "memory")
; template <int MODE>
; __device__ __forceinline__ void transpose_item(const float* W, const float* W2, int K, int Nsrc, int Ndst, bf16_t* WT, LAS float* scr, int item, int lane) {
;     ...
;     for (int i = 0; i < 16; ++i) { LAS float* d = scr + (4 * i + r4) * 65 + lcol; d[0] = v[i].x; d[1] = v[i].y; d[2] = v[i].z; d[3] = v[i].w; }
;     LDS_WAIT(); asm volatile("" ::: "memory");
;     const int c = lane & 7;
; #pragma unroll
;     for (int j = 0; j < 8; ++j) { const int n = (lane >> 3) + 8 * j; const LAS float* sp = scr + (8 * c) * 65 + n;
;         u32x4 o; o.x = pk2(sp[0 * 65], sp[1 * 65]); o.y = pk2(sp[2 * 65], sp[3 * 65]); o.z = pk2(sp[4 * 65], sp[5 * 65]); o.w = pk2(sp[6 * 65], sp[7 * 65]);
	ds_write2_b32 v46, v104, v105 offset1:1
	ds_write2_b32 v47, v106, v107 offset1:1
	s_waitcnt vmcnt(2)
	ds_write2_b32 v48, v108, v109 offset1:1
	ds_write2_b32 v49, v110, v111 offset1:1
	s_waitcnt vmcnt(1)
	ds_write2_b32 v50, v112, v113 offset1:1
	ds_write2_b32 v51, v114, v115 offset1:1
	s_waitcnt vmcnt(0)
	ds_write2_b32 v52, v116, v117 offset1:1
	ds_write2_b32 v53, v118, v119 offset1:1
	s_waitcnt lgkmcnt(0)
	ds_read2_b32 v[56:57], v21 offset0:65 offset1:73
	ds_read2_b32 v[58:59], v21 offset1:8
	ds_read2_b32 v[60:61], v21 offset0:130 offset1:138
	ds_read2_b32 v[62:63], v21 offset0:195 offset1:203
	ds_read2_b32 v[64:65], v54 offset0:4 offset1:12
	ds_read2_b32 v[66:67], v54 offset0:69 offset1:77
	ds_read2_b32 v[68:69], v54 offset0:134 offset1:142
	ds_read2_b32 v[70:71], v54 offset0:199 offset1:207
	ds_read2_b32 v[72:73], v21 offset0:81 offset1:89
	ds_read2_b32 v[74:75], v21 offset0:16 offset1:24
	ds_read2_b32 v[76:77], v21 offset0:146 offset1:154
	ds_read2_b32 v[78:79], v21 offset0:211 offset1:219
	ds_read2_b32 v[80:81], v54 offset0:20 offset1:28
	ds_read2_b32 v[82:83], v54 offset0:85 offset1:93
	ds_read2_b32 v[84:85], v54 offset0:150 offset1:158
	ds_read2_b32 v[86:87], v54 offset0:215 offset1:223
	ds_read2_b32 v[88:89], v21 offset0:32 offset1:40
	ds_read2_b32 v[90:91], v21 offset0:97 offset1:105
	ds_read2_b32 v[92:93], v21 offset0:162 offset1:170
	ds_read2_b32 v[94:95], v21 offset0:227 offset1:235
	ds_read2_b32 v[96:97], v54 offset0:36 offset1:44
	ds_read2_b32 v[98:99], v54 offset0:101 offset1:109
	ds_read2_b32 v[100:101], v54 offset0:166 offset1:174
	ds_read2_b32 v[102:103], v54 offset0:231 offset1:239
	ds_read2_b32 v[104:105], v21 offset0:48 offset1:56
	ds_read2_b32 v[106:107], v21 offset0:113 offset1:121
	ds_read2_b32 v[108:109], v21 offset0:178 offset1:186
	ds_read2_b32 v[110:111], v21 offset0:243 offset1:251
	ds_read2_b32 v[112:113], v54 offset0:52 offset1:60
	ds_read2_b32 v[114:115], v54 offset0:117 offset1:125
	ds_read2_b32 v[116:117], v54 offset0:182 offset1:190
	ds_read2_b32 v[118:119], v54 offset0:247 offset1:255
	s_waitcnt lgkmcnt(14)
	v_bfe_u32 v55, v58, 16, 1
	v_bfe_u32 v121, v60, 16, 1
	v_bfe_u32 v122, v62, 16, 1
	v_bfe_u32 v123, v64, 16, 1
	v_bfe_u32 v124, v66, 16, 1
	v_bfe_u32 v125, v68, 16, 1
	v_bfe_u32 v120, v56, 16, 1
	v_bfe_u32 v126, v70, 16, 1
	v_bfe_u32 v127, v59, 16, 1
	v_bfe_u32 v128, v57, 16, 1
	v_bfe_u32 v129, v61, 16, 1
	v_bfe_u32 v130, v63, 16, 1
	v_bfe_u32 v131, v65, 16, 1
	v_bfe_u32 v132, v67, 16, 1
	v_bfe_u32 v133, v69, 16, 1
	v_bfe_u32 v134, v71, 16, 1
	v_bfe_u32 v135, v74, 16, 1
	v_bfe_u32 v137, v76, 16, 1
	v_bfe_u32 v138, v78, 16, 1
	v_bfe_u32 v139, v80, 16, 1
	v_bfe_u32 v140, v82, 16, 1
	v_bfe_u32 v141, v84, 16, 1
	v_bfe_u32 v142, v86, 16, 1
	v_bfe_u32 v143, v75, 16, 1
	v_bfe_u32 v145, v77, 16, 1
	v_bfe_u32 v147, v81, 16, 1
	v_bfe_u32 v149, v85, 16, 1
	v_bfe_u32 v150, v87, 16, 1
	v_bfe_u32 v151, v88, 16, 1
	v_bfe_u32 v152, v90, 16, 1
	s_waitcnt lgkmcnt(13)
	v_bfe_u32 v153, v92, 16, 1
	s_waitcnt lgkmcnt(12)
	v_bfe_u32 v154, v94, 16, 1
	s_waitcnt lgkmcnt(11)
	v_bfe_u32 v155, v96, 16, 1
	s_waitcnt lgkmcnt(10)
	v_bfe_u32 v156, v98, 16, 1
	s_waitcnt lgkmcnt(9)
	v_bfe_u32 v157, v100, 16, 1
	s_waitcnt lgkmcnt(8)
	v_bfe_u32 v158, v102, 16, 1
	v_bfe_u32 v159, v89, 16, 1
	v_bfe_u32 v161, v93, 16, 1
	v_bfe_u32 v163, v97, 16, 1
	v_bfe_u32 v165, v101, 16, 1
	v_bfe_u32 v166, v103, 16, 1
	s_waitcnt lgkmcnt(7)
	v_bfe_u32 v167, v104, 16, 1
	s_waitcnt lgkmcnt(6)
	v_bfe_u32 v168, v106, 16, 1
	s_waitcnt lgkmcnt(5)
	v_bfe_u32 v169, v108, 16, 1
	s_waitcnt lgkmcnt(4)
	v_bfe_u32 v170, v110, 16, 1
	s_waitcnt lgkmcnt(3)
	v_bfe_u32 v171, v112, 16, 1
	s_waitcnt lgkmcnt(2)
	v_bfe_u32 v172, v114, 16, 1
	s_waitcnt lgkmcnt(1)
	v_bfe_u32 v173, v116, 16, 1
	v_bfe_u32 v175, v105, 16, 1
	v_bfe_u32 v177, v109, 16, 1
	v_bfe_u32 v179, v113, 16, 1
	v_bfe_u32 v181, v117, 16, 1
	v_add3_u32 v55, v58, v55, s11
	v_add3_u32 v58, v60, v121, s11
	v_add3_u32 v60, v62, v122, s11
	v_add3_u32 v62, v64, v123, s11
	v_add3_u32 v64, v66, v124, s11
	v_add3_u32 v66, v68, v125, s11
	v_bfe_u32 v136, v72, 16, 1
	v_bfe_u32 v144, v73, 16, 1
	v_bfe_u32 v146, v79, 16, 1
	v_bfe_u32 v148, v83, 16, 1
	v_bfe_u32 v160, v91, 16, 1
	v_bfe_u32 v162, v95, 16, 1
	v_bfe_u32 v164, v99, 16, 1
	s_waitcnt lgkmcnt(0)
; #define LAS __attribute__((address_space(3)))
; __device__ __forceinline__ unsigned pk2(float lo, float hi) { return f2bf(lo) | (f2bf(hi) << 16); }
; #define LDS_WAIT() asm volatile("s_waitcnt lgkmcnt(0)" ::: "memory")
; template <int MODE>
; __device__ __forceinline__ void transpose_item(const float* W, const float* W2, int K, int Nsrc, int Ndst, bf16_t* WT, LAS float* scr, int item, int lane) {
;     ...
;     for (int j = 0; j < 8; ++j) { const int n = (lane >> 3) + 8 * j; const LAS float* sp = scr + (8 * c) * 65 + n;
;         u32x4 o; o.x = pk2(sp[0 * 65], sp[1 * 65]); o.y = pk2(sp[2 * 65], sp[3 * 65]); o.z = pk2(sp[4 * 65], sp[5 * 65]); o.w = pk2(sp[6 * 65], sp[7 * 65]);
;         *(u32x4*)(WT + (size_t)(n0 + n) * K + k0 + 8 * c) = o; }
;     LDS_WAIT(); asm volatile("" ::: "memory");
; }
; template <int MODE>
; __device__ __forceinline__ void convert_weight(Frame& F, const float* W, const float* W2, int K, int Nsrc, int Ndst, bf16_t* WT) {
;     LAS float* scr = (LAS float*)(F.lds + F.wave * 17408);
;     const int gw = F.bid * NWAVES + F.wave, NGW = F.G * NWAVES, nitems = (K / 64) * (Ndst / 64);
;     for (int it = gw; it < nitems; it += NGW) transpose_item<MODE>(W, W2, K, Nsrc, Ndst, WT, scr, it, F.lane);
	v_bfe_u32 v174, v118, 16, 1
	v_bfe_u32 v176, v107, 16, 1
	v_bfe_u32 v178, v111, 16, 1
	v_bfe_u32 v180, v115, 16, 1
	v_bfe_u32 v182, v119, 16, 1
	v_add3_u32 v56, v56, v120, s11
	v_add3_u32 v68, v70, v126, s11
	v_add3_u32 v59, v59, v127, s11
	v_add3_u32 v70, v57, v128, s11
	v_add3_u32 v57, v61, v129, s11
	v_add3_u32 v61, v63, v130, s11
	v_add3_u32 v63, v65, v131, s11
	v_add3_u32 v65, v67, v132, s11
	v_add3_u32 v67, v69, v133, s11
	v_add3_u32 v69, v71, v134, s11
	v_add3_u32 v71, v74, v135, s11
	v_add3_u32 v74, v76, v137, s11
	v_add3_u32 v76, v78, v138, s11
	v_add3_u32 v78, v80, v139, s11
	v_add3_u32 v80, v82, v140, s11
	v_add3_u32 v82, v84, v141, s11
	v_add3_u32 v84, v86, v142, s11
	v_add3_u32 v75, v75, v143, s11
	v_add3_u32 v77, v77, v145, s11
	v_add3_u32 v81, v81, v147, s11
	v_add3_u32 v85, v85, v149, s11
	v_add3_u32 v86, v87, v150, s11
	v_add3_u32 v87, v88, v151, s11
	v_add3_u32 v88, v90, v152, s11
	v_add3_u32 v90, v92, v153, s11
	v_add3_u32 v92, v94, v154, s11
	v_add3_u32 v94, v96, v155, s11
	v_add3_u32 v96, v98, v156, s11
	v_add3_u32 v98, v100, v157, s11
	v_add3_u32 v100, v102, v158, s11
	v_add3_u32 v89, v89, v159, s11
	v_add3_u32 v93, v93, v161, s11
	v_add3_u32 v97, v97, v163, s11
	v_add3_u32 v101, v101, v165, s11
	v_add3_u32 v102, v103, v166, s11
	v_add3_u32 v103, v104, v167, s11
	v_add3_u32 v104, v106, v168, s11
	v_add3_u32 v106, v108, v169, s11
	v_add3_u32 v108, v110, v170, s11
	v_add3_u32 v110, v112, v171, s11
	v_add3_u32 v112, v114, v172, s11
	v_add3_u32 v114, v116, v173, s11
	v_add3_u32 v105, v105, v175, s11
	v_add3_u32 v109, v109, v177, s11
	v_add3_u32 v113, v113, v179, s11
	v_add3_u32 v117, v117, v181, s11
	v_lshrrev_b32_e32 v55, 16, v55
	v_lshrrev_b32_e32 v58, 16, v58
	v_lshrrev_b32_e32 v62, 16, v62
	v_lshrrev_b32_e32 v66, 16, v66
	v_add3_u32 v72, v72, v136, s11
	v_add3_u32 v73, v73, v144, s11
	v_add3_u32 v79, v79, v146, s11
	v_add3_u32 v83, v83, v148, s11
	v_add3_u32 v91, v91, v160, s11
	v_add3_u32 v95, v95, v162, s11
	v_add3_u32 v99, v99, v164, s11
	v_add3_u32 v116, v118, v174, s11
	v_add3_u32 v107, v107, v176, s11
	v_add3_u32 v111, v111, v178, s11
	v_add3_u32 v115, v115, v180, s11
	v_add3_u32 v118, v119, v182, s11
	v_lshrrev_b32_e32 v119, 16, v59
	v_lshrrev_b32_e32 v120, 16, v57
	v_lshrrev_b32_e32 v63, 16, v63
	v_lshrrev_b32_e32 v67, 16, v67
	v_lshrrev_b32_e32 v71, 16, v71
	v_lshrrev_b32_e32 v74, 16, v74
	v_lshrrev_b32_e32 v78, 16, v78
	v_lshrrev_b32_e32 v82, 16, v82
	v_lshrrev_b32_e32 v75, 16, v75
	v_lshrrev_b32_e32 v77, 16, v77
	v_lshrrev_b32_e32 v81, 16, v81
	v_lshrrev_b32_e32 v85, 16, v85
	v_lshrrev_b32_e32 v87, 16, v87
	v_lshrrev_b32_e32 v90, 16, v90
	v_lshrrev_b32_e32 v94, 16, v94
	v_lshrrev_b32_e32 v98, 16, v98
	v_lshrrev_b32_e32 v89, 16, v89
	v_lshrrev_b32_e32 v93, 16, v93
	v_lshrrev_b32_e32 v97, 16, v97
	v_lshrrev_b32_e32 v101, 16, v101
	v_lshrrev_b32_e32 v103, 16, v103
	v_lshrrev_b32_e32 v106, 16, v106
	v_lshrrev_b32_e32 v110, 16, v110
	v_lshrrev_b32_e32 v114, 16, v114
	v_lshrrev_b32_e32 v105, 16, v105
	v_lshrrev_b32_e32 v109, 16, v109
	v_lshrrev_b32_e32 v113, 16, v113
	v_lshrrev_b32_e32 v117, 16, v117
	v_and_or_b32 v56, v56, s12, v55
	v_and_or_b32 v57, v60, s12, v58
	v_and_or_b32 v58, v64, s12, v62
	v_and_or_b32 v59, v68, s12, v66
	v_and_or_b32 v60, v70, s12, v119
	v_and_or_b32 v61, v61, s12, v120
	v_and_or_b32 v62, v65, s12, v63
	v_and_or_b32 v63, v69, s12, v67
	v_and_or_b32 v64, v72, s12, v71
	v_and_or_b32 v65, v76, s12, v74
	v_and_or_b32 v66, v80, s12, v78
	v_and_or_b32 v67, v84, s12, v82
	v_and_or_b32 v68, v73, s12, v75
	v_and_or_b32 v69, v79, s12, v77
	v_and_or_b32 v70, v83, s12, v81
	v_and_or_b32 v71, v86, s12, v85
	v_and_or_b32 v72, v88, s12, v87
	v_and_or_b32 v73, v92, s12, v90
	v_and_or_b32 v74, v96, s12, v94
	v_and_or_b32 v75, v100, s12, v98
	v_and_or_b32 v76, v91, s12, v89
	v_and_or_b32 v77, v95, s12, v93
	v_and_or_b32 v78, v99, s12, v97
	v_and_or_b32 v79, v102, s12, v101
	v_and_or_b32 v80, v104, s12, v103
	v_and_or_b32 v81, v108, s12, v106
	v_and_or_b32 v82, v112, s12, v110
	v_and_or_b32 v83, v116, s12, v114
	v_and_or_b32 v84, v107, s12, v105
	v_and_or_b32 v85, v111, s12, v109
	v_and_or_b32 v86, v115, s12, v113
	v_and_or_b32 v87, v118, s12, v117
	global_store_dwordx4 v[4:5], v[56:59], off
	global_store_dwordx4 v[6:7], v[60:63], off
	global_store_dwordx4 v[8:9], v[64:67], off
	global_store_dwordx4 v[10:11], v[68:71], off
	global_store_dwordx4 v[12:13], v[72:75], off
	global_store_dwordx4 v[14:15], v[76:79], off
	global_store_dwordx4 v[16:17], v[80:83], off
	global_store_dwordx4 v[18:19], v[84:87], off
	s_waitcnt lgkmcnt(0)
	s_add_i32 s13, s13, s10
	s_add_i32 s5, s5, s9
	s_cmpk_lt_i32 s13, 0xb00
	v_add_u32_e32 v22, s4, v22
	s_cbranch_scc1 .LBB0_1388

; template <bool OUT_BF16>
; __device__ __forceinline__ void rmsnorm_rows(Frame& F, const float* X, const float* gain, void* O) {
;     const int gw = F.bid * NWAVES + F.wave, NGW = F.G * NWAVES;
;     f32x4 gv[8];
; #pragma unroll
;     for (int j = 0; j < 8; ++j) gv[j] = ((const f32x4*)gain)[F.lane + 64 * j];
;     for (int m = gw; m < S; m += NGW) {
;         const f32x4* xr = (const f32x4*)(X + (size_t)m * DM) + F.lane;
;         f32x4 v[8]; float s = 0.f;
; #pragma unroll
;         for (int j = 0; j < 8; ++j) { v[j] = xr[64 * j]; s += (v[j].x * v[j].x + v[j].y * v[j].y) + (v[j].z * v[j].z + v[j].w * v[j].w); }
.LBB0_1600:
	s_cmp_lt_i32 s30, 13
	s_cselect_b64 s[6:7], -1, 0
	s_and_b64 s[4:5], s[6:7], s[4:5]
	s_andn2_b64 vcc, exec, s[4:5]
	s_cbranch_vccnz .LBB0_1604
	s_lshl_b32 s2, s2, 3
	s_add_i32 s2, s33, s2
	s_cmpk_gt_i32 s2, 0x3fff
	s_cbranch_scc1 .LBB0_1604
	s_load_dwordx4 s[4:7], s[0:1], 0xe0
	v_lshlrev_b32_e32 v32, 4, v184
	v_mov_b32_e32 v33, 0
	v_mov_b32_e32 v36, 0x260
	s_waitcnt lgkmcnt(0)
	global_load_dwordx4 v[0:3], v32, s[4:5]
	global_load_dwordx4 v[4:7], v32, s[4:5] offset:1024
	global_load_dwordx4 v[8:11], v32, s[4:5] offset:2048
	global_load_dwordx4 v[12:15], v32, s[4:5] offset:3072
	s_waitcnt vmcnt(0)
	v_lshl_add_u64 v[16:17], s[4:5], 0, v[32:33]
	v_add_co_u32_e32 v34, vcc, 0x1000, v16
	s_lshl_b32 s4, s3, 3
	s_nop 0
	v_addc_co_u32_e32 v35, vcc, 0, v17, vcc
	global_load_dwordx4 v[16:19], v[34:35], off nt
	global_load_dwordx4 v[20:23], v[34:35], off offset:1024 nt
	global_load_dwordx4 v[24:27], v[34:35], off offset:2048 nt
	global_load_dwordx4 v[28:31], v[34:35], off offset:3072 nt
	s_ashr_i32 s3, s2, 31
	s_lshl_b64 s[0:1], s[2:3], 13
	s_add_u32 s0, s6, s0
	s_addc_u32 s1, s7, s1
	v_lshl_add_u64 v[32:33], s[0:1], 0, v[32:33]
	s_mov_b64 s[0:1], 0x1000
	s_ashr_i32 s5, s4, 31
	v_lshl_add_u64 v[32:33], v[32:33], 0, s[0:1]
	s_lshl_b64 s[6:7], s[4:5], 13
	v_mov_b32_e32 v34, 0x358637bd
	v_mov_b32_e32 v35, 0x3a000000
	s_mov_b32 s3, 0xf800000
; __device__ __forceinline__ unsigned pk2(float lo, float hi) { return f2bf(lo) | (f2bf(hi) << 16); }
; template <bool OUT_BF16>
; __device__ __forceinline__ void rmsnorm_rows(Frame& F, const float* X, const float* gain, void* O) {
;     ...
;     for (int m = gw; m < S; m += NGW) {
;         const f32x4* xr = (const f32x4*)(X + (size_t)m * DM) + F.lane;
;         f32x4 v[8]; float s = 0.f;
; #pragma unroll
;         for (int j = 0; j < 8; ++j) { v[j] = xr[64 * j]; s += (v[j].x * v[j].x + v[j].y * v[j].y) + (v[j].z * v[j].z + v[j].w * v[j].w); }
;         const float rs = 1.f / sqrtf(wave_sum(s) * (1.f / DM) + NORM_EPS);
;         if (OUT_BF16) {
;             u32x2* o8 = (u32x2*)((bf16_t*)O + (size_t)m * DM) + F.lane;
; #pragma unroll
;             for (int j = 0; j < 8; ++j) { u32x2 w; w.x = pk2(v[j].x * rs * gv[j].x, v[j].y * rs * gv[j].y); w.y = pk2(v[j].z * rs * gv[j].z, v[j].w * rs * gv[j].w); o8[64 * j] = w; }
;         } else {
;             f32x4* o = (f32x4*)((float*)O + (size_t)m * DM) + F.lane;
; #pragma unroll
;             for (int j = 0; j < 8; ++j) o[64 * j] = v[j] * rs * gv[j];
;         }
.LBB0_1603:
	global_load_dwordx4 v[38:41], v[32:33], off offset:-4096 nt
	global_load_dwordx4 v[42:45], v[32:33], off offset:-3072 nt
	global_load_dwordx4 v[46:49], v[32:33], off offset:-2048 nt
	global_load_dwordx4 v[50:53], v[32:33], off offset:-1024 nt
	global_load_dwordx4 v[54:57], v[32:33], off nt
	global_load_dwordx4 v[58:61], v[32:33], off offset:1024 nt
	global_load_dwordx4 v[62:65], v[32:33], off offset:2048 nt
	global_load_dwordx4 v[66:69], v[32:33], off offset:3072 nt
	v_mov_b32_e32 v37, 0
	v_mov_b32_e32 v70, 0
	s_add_i32 s2, s2, s4
	s_cmpk_lt_i32 s2, 0x4000
	s_waitcnt vmcnt(7)
	v_mul_f32_e32 v71, v39, v39
	v_mul_f32_e32 v72, v41, v41
	s_waitcnt vmcnt(6)
	v_mul_f32_e32 v73, v43, v43
	v_mul_f32_e32 v74, v45, v45
	s_waitcnt vmcnt(5)
	v_mul_f32_e32 v75, v47, v47
	v_mul_f32_e32 v76, v49, v49
	v_fmac_f32_e32 v71, v38, v38
	v_fmac_f32_e32 v72, v40, v40
	v_fmac_f32_e32 v73, v42, v42
	v_fmac_f32_e32 v74, v44, v44
	s_waitcnt vmcnt(4)
	v_mul_f32_e32 v77, v51, v51
	v_mul_f32_e32 v78, v53, v53
	v_fmac_f32_e32 v75, v46, v46
	v_fmac_f32_e32 v76, v48, v48
	v_add_f32_e32 v71, v71, v72
	v_add_f32_e32 v72, v73, v74
	s_waitcnt vmcnt(3)
	v_mul_f32_e32 v79, v55, v55
	v_mul_f32_e32 v80, v57, v57
	v_fmac_f32_e32 v77, v50, v50
	v_fmac_f32_e32 v78, v52, v52
	v_add_f32_e32 v73, v75, v76
	v_add_f32_e32 v71, v71, v72
	s_waitcnt vmcnt(2)
	v_mul_f32_e32 v81, v59, v59
	v_mul_f32_e32 v82, v61, v61
	v_fmac_f32_e32 v79, v54, v54
	v_fmac_f32_e32 v80, v56, v56
	v_add_f32_e32 v74, v77, v78
	v_add_f32_e32 v71, v71, v73
	s_waitcnt vmcnt(1)
	v_mul_f32_e32 v83, v63, v63
	v_mul_f32_e32 v84, v65, v65
	v_fmac_f32_e32 v81, v58, v58
	v_fmac_f32_e32 v82, v60, v60
	v_add_f32_e32 v75, v79, v80
	v_add_f32_e32 v71, v71, v74
	s_waitcnt vmcnt(0)
	v_mul_f32_e32 v85, v67, v67
	v_mul_f32_e32 v86, v69, v69
	v_fmac_f32_e32 v83, v62, v62
	v_fmac_f32_e32 v84, v64, v64
	v_add_f32_e32 v76, v81, v82
	v_add_f32_e32 v71, v71, v75
	v_fmac_f32_e32 v85, v66, v66
	v_fmac_f32_e32 v86, v68, v68
	v_add_f32_e32 v77, v83, v84
	v_add_f32_e32 v71, v71, v76
	v_add_f32_e32 v78, v85, v86
	v_add_f32_e32 v71, v71, v77
	v_add_f32_e32 v71, v71, v78
	s_nop 1
	v_add_f32_dpp v71, v71, v71 quad_perm:[1,0,3,2] row_mask:0xf bank_mask:0xf bound_ctrl:1
	s_nop 1
	v_add_f32_dpp v71, v71, v71 quad_perm:[2,3,0,1] row_mask:0xf bank_mask:0xf bound_ctrl:1
	s_nop 1
	v_add_f32_dpp v71, v71, v71 row_half_mirror row_mask:0xf bank_mask:0xf bound_ctrl:1
	s_nop 1
	v_add_f32_dpp v71, v71, v71 row_mirror row_mask:0xf bank_mask:0xf bound_ctrl:1
	s_nop 1
	v_mov_b32_dpp v37, v71 row_bcast:15 row_mask:0xa bank_mask:0xf
	v_add_f32_e32 v37, v71, v37
	s_nop 1
	v_mov_b32_dpp v70, v37 row_bcast:31 row_mask:0xc bank_mask:0xf
	v_add_f32_e32 v37, v37, v70
	s_nop 0
	v_readlane_b32 s0, v37, 63
	s_nop 1
	v_fma_f32 v37, s0, v35, v34
	v_mul_f32_e32 v70, 0x4f800000, v37
	v_cmp_gt_f32_e32 vcc, s3, v37
	s_nop 1
	v_cndmask_b32_e32 v37, v37, v70, vcc
	v_sqrt_f32_e32 v70, v37
	s_nop 0
	v_add_u32_e32 v71, -1, v70
	v_add_u32_e32 v72, 1, v70
	v_fma_f32 v73, -v71, v70, v37
	v_fma_f32 v74, -v72, v70, v37
	v_cmp_ge_f32_e64 s[0:1], 0, v73
	s_nop 1
	v_cndmask_b32_e64 v70, v70, v71, s[0:1]
	v_cmp_lt_f32_e64 s[0:1], 0, v74
	s_nop 1
	v_cndmask_b32_e64 v70, v70, v72, s[0:1]
	v_mul_f32_e32 v71, 0x37800000, v70
	v_cndmask_b32_e32 v70, v70, v71, vcc
	v_cmp_class_f32_e32 vcc, v37, v36
	s_nop 1
	v_cndmask_b32_e32 v37, v70, v37, vcc
	v_div_scale_f32 v70, s[0:1], v37, v37, 1.0
	v_rcp_f32_e32 v71, v70
	v_div_scale_f32 v72, vcc, 1.0, v37, 1.0
	v_fma_f32 v73, -v70, v71, 1.0
	v_fmac_f32_e32 v71, v73, v71
	v_mul_f32_e32 v73, v72, v71
	v_fma_f32 v74, -v70, v73, v72
	v_fmac_f32_e32 v73, v74, v71
	v_fma_f32 v70, -v70, v73, v72
	v_div_fmas_f32 v70, v70, v71, v73
	v_div_fixup_f32 v70, v70, v37, 1.0
	v_pk_mul_f32 v[38:39], v[38:39], v[70:71] op_sel_hi:[1,0]
	v_pk_mul_f32 v[40:41], v[40:41], v[70:71] op_sel_hi:[1,0]
	v_pk_mul_f32 v[42:43], v[42:43], v[70:71] op_sel_hi:[1,0]
	v_pk_mul_f32 v[44:45], v[44:45], v[70:71] op_sel_hi:[1,0]
	v_pk_mul_f32 v[46:47], v[46:47], v[70:71] op_sel_hi:[1,0]
	v_pk_mul_f32 v[48:49], v[48:49], v[70:71] op_sel_hi:[1,0]
	v_pk_mul_f32 v[50:51], v[50:51], v[70:71] op_sel_hi:[1,0]
	v_pk_mul_f32 v[52:53], v[52:53], v[70:71] op_sel_hi:[1,0]
	v_pk_mul_f32 v[54:55], v[54:55], v[70:71] op_sel_hi:[1,0]
	v_pk_mul_f32 v[56:57], v[56:57], v[70:71] op_sel_hi:[1,0]
	v_pk_mul_f32 v[58:59], v[58:59], v[70:71] op_sel_hi:[1,0]
	v_pk_mul_f32 v[60:61], v[60:61], v[70:71] op_sel_hi:[1,0]
	v_pk_mul_f32 v[62:63], v[62:63], v[70:71] op_sel_hi:[1,0]
	v_pk_mul_f32 v[64:65], v[64:65], v[70:71] op_sel_hi:[1,0]
	v_pk_mul_f32 v[40:41], v[2:3], v[40:41]
	v_pk_mul_f32 v[38:39], v[0:1], v[38:39]
	v_pk_mul_f32 v[44:45], v[6:7], v[44:45]
	v_pk_mul_f32 v[42:43], v[4:5], v[42:43]
	v_pk_mul_f32 v[48:49], v[10:11], v[48:49]
	v_pk_mul_f32 v[46:47], v[8:9], v[46:47]
	v_pk_mul_f32 v[52:53], v[14:15], v[52:53]
	v_pk_mul_f32 v[50:51], v[12:13], v[50:51]
	v_pk_mul_f32 v[56:57], v[18:19], v[56:57]
	v_pk_mul_f32 v[54:55], v[16:17], v[54:55]
	v_pk_mul_f32 v[60:61], v[22:23], v[60:61]
	v_pk_mul_f32 v[58:59], v[20:21], v[58:59]
	global_store_dwordx4 v[32:33], v[38:41], off offset:-4096
	global_store_dwordx4 v[32:33], v[42:45], off offset:-3072
	global_store_dwordx4 v[32:33], v[46:49], off offset:-2048
	global_store_dwordx4 v[32:33], v[50:53], off offset:-1024
	global_store_dwordx4 v[32:33], v[54:57], off
	global_store_dwordx4 v[32:33], v[58:61], off offset:1024
	v_pk_mul_f32 v[40:41], v[26:27], v[64:65]
	v_pk_mul_f32 v[38:39], v[24:25], v[62:63]
	global_store_dwordx4 v[32:33], v[38:41], off offset:2048
	s_nop 1
	v_pk_mul_f32 v[38:39], v[66:67], v[70:71] op_sel_hi:[1,0]
	v_pk_mul_f32 v[40:41], v[68:69], v[70:71] op_sel_hi:[1,0]
	v_pk_mul_f32 v[38:39], v[28:29], v[38:39]
	v_pk_mul_f32 v[40:41], v[30:31], v[40:41]
	global_store_dwordx4 v[32:33], v[38:41], off offset:3072
	v_lshl_add_u64 v[32:33], v[32:33], 0, s[6:7]
	s_cbranch_scc1 .LBB0_1603
